# K-steps without stage-toggle VALU in the unrolled hand-written GEMM phases; M0 set ahead of the interleaved MFMA (no filler nops)
# baseline (speedup 1.0000x reference)
.Lgk0_loop:
	ds_read_b128 v[128:131], v233
	ds_read_b128 v[136:139], v237
	ds_read_b128 v[132:135], v233 offset:4096
	ds_read_b128 v[140:143], v237 offset:4096
	ds_read_b128 v[144:147], v237 offset:8192
	ds_read_b128 v[148:151], v237 offset:12288
	s_waitcnt lgkmcnt(6)
	v_mfma_f32_32x32x16_bf16 v[112:127], v[206:209], v[216:219], v[112:127]
	v_mfma_f32_32x32x16_bf16 v[48:63], v[212:215], v[216:219], v[48:63]
	v_mfma_f32_32x32x16_bf16 v[96:111], v[206:209], v[220:223], v[96:111]
	v_mfma_f32_32x32x16_bf16 v[32:47], v[212:215], v[220:223], v[32:47]
	v_mfma_f32_32x32x16_bf16 v[80:95], v[206:209], v[224:227], v[80:95]
	v_mfma_f32_32x32x16_bf16 v[16:31], v[212:215], v[224:227], v[16:31]
	v_mfma_f32_32x32x16_bf16 v[64:79], v[206:209], v[228:231], v[64:79]
	v_mfma_f32_32x32x16_bf16 v[0:15], v[212:215], v[228:231], v[0:15]
	ds_read_b128 v[206:209], v234
	ds_read_b128 v[216:219], v238
	ds_read_b128 v[212:215], v234 offset:4096
	ds_read_b128 v[220:223], v238 offset:4096
	ds_read_b128 v[224:227], v238 offset:8192
	ds_read_b128 v[228:231], v238 offset:12288
	s_waitcnt lgkmcnt(6)
	v_mfma_f32_32x32x16_bf16 v[112:127], v[128:131], v[136:139], v[112:127]
	v_mfma_f32_32x32x16_bf16 v[48:63], v[132:135], v[136:139], v[48:63]
	v_mfma_f32_32x32x16_bf16 v[96:111], v[128:131], v[140:143], v[96:111]
	v_mfma_f32_32x32x16_bf16 v[32:47], v[132:135], v[140:143], v[32:47]
	v_mfma_f32_32x32x16_bf16 v[80:95], v[128:131], v[144:147], v[80:95]
	v_mfma_f32_32x32x16_bf16 v[16:31], v[132:135], v[144:147], v[16:31]
	v_mfma_f32_32x32x16_bf16 v[64:79], v[128:131], v[148:151], v[64:79]
	v_mfma_f32_32x32x16_bf16 v[0:15], v[132:135], v[148:151], v[0:15]
	ds_read_b128 v[128:131], v235
	ds_read_b128 v[136:139], v239
	ds_read_b128 v[132:135], v235 offset:4096
	ds_read_b128 v[140:143], v239 offset:4096
	ds_read_b128 v[144:147], v239 offset:8192
	ds_read_b128 v[148:151], v239 offset:12288
	s_waitcnt lgkmcnt(6)
	v_mfma_f32_32x32x16_bf16 v[112:127], v[206:209], v[216:219], v[112:127]
	v_mfma_f32_32x32x16_bf16 v[48:63], v[212:215], v[216:219], v[48:63]
	v_mfma_f32_32x32x16_bf16 v[96:111], v[206:209], v[220:223], v[96:111]
	v_mfma_f32_32x32x16_bf16 v[32:47], v[212:215], v[220:223], v[32:47]
	v_mfma_f32_32x32x16_bf16 v[80:95], v[206:209], v[224:227], v[80:95]
	v_mfma_f32_32x32x16_bf16 v[16:31], v[212:215], v[224:227], v[16:31]
	v_mfma_f32_32x32x16_bf16 v[64:79], v[206:209], v[228:231], v[64:79]
	v_mfma_f32_32x32x16_bf16 v[0:15], v[212:215], v[228:231], v[0:15]
	s_waitcnt vmcnt(0) lgkmcnt(0)
	s_barrier
	v_xor_b32_e32 v232, 0x10000, v232
	v_xor_b32_e32 v236, 0x10000, v236
	ds_read_b128 v[206:209], v232
	ds_read_b128 v[216:219], v236
	ds_read_b128 v[212:215], v232 offset:4096
	ds_read_b128 v[220:223], v236 offset:4096
	ds_read_b128 v[224:227], v236 offset:8192
	ds_read_b128 v[228:231], v236 offset:12288
	s_cmpk_eq_i32 s2, 0x700
	s_cbranch_scc1 .Lgk0_nodma
	s_add_u32 s94, s2, s92
	s_add_u32 s94, s94, 0x100
	s_and_b32 s94, s94, 0x780
	s_sub_u32 s94, s94, 0x80
	s_subb_u32 s95, 0, 0
	s_add_u32 s100, s96, s94
	s_addc_u32 s101, s97, s95
	s_add_u32 s94, s98, s94
	s_addc_u32 s95, s99, s95
	s_add_u32 s90, s88, s89
	s_add_u32 m0, s90, 0
	v_mfma_f32_32x32x16_bf16 v[112:127], v[128:131], v[136:139], v[112:127]
	v_xor_b32_e32 v233, 0x10000, v233
	v_xor_b32_e32 v237, 0x10000, v237
	global_load_lds_dwordx4 v152, s[100:101]
	s_add_u32 m0, s90, 32768
	v_mfma_f32_32x32x16_bf16 v[48:63], v[132:135], v[136:139], v[48:63]
	v_xor_b32_e32 v234, 0x10000, v234
	v_xor_b32_e32 v238, 0x10000, v238
	global_load_lds_dwordx4 v153, s[94:95]
	s_add_u32 m0, s90, 8192
	v_mfma_f32_32x32x16_bf16 v[96:111], v[128:131], v[140:143], v[96:111]
	v_xor_b32_e32 v235, 0x10000, v235
	v_xor_b32_e32 v239, 0x10000, v239
	global_load_lds_dwordx4 v154, s[100:101]
	s_add_u32 m0, s90, 40960
	v_mfma_f32_32x32x16_bf16 v[32:47], v[132:135], v[140:143], v[32:47]
	global_load_lds_dwordx4 v155, s[94:95]
	s_add_u32 m0, s90, 16384
	v_mfma_f32_32x32x16_bf16 v[80:95], v[128:131], v[144:147], v[80:95]
	global_load_lds_dwordx4 v156, s[100:101]
	s_add_u32 m0, s90, 49152
	v_mfma_f32_32x32x16_bf16 v[16:31], v[132:135], v[144:147], v[16:31]
	global_load_lds_dwordx4 v157, s[94:95]
	s_add_u32 m0, s90, 24576
	v_mfma_f32_32x32x16_bf16 v[64:79], v[128:131], v[148:151], v[64:79]
	global_load_lds_dwordx4 v158, s[100:101]
	s_add_u32 m0, s90, 57344
	v_mfma_f32_32x32x16_bf16 v[0:15], v[132:135], v[148:151], v[0:15]
	global_load_lds_dwordx4 v160, s[94:95]
	s_branch .Lgk0_join

.Lmq3_vb:
	v_mbcnt_hi_u32_b32 v206, -1, v210
	s_lshr_b32 s29, s70, 6
	s_lshl_b32 s88, s70, 4
	s_and_b32 s90, s70, 0x40
	v_and_b32_e32 v245, 48, v206
	v_or_b32_e32 v245, s90, v245
	v_and_b32_e32 v207, 31, v206
	v_lshrrev_b32_e32 v208, 5, v206
	v_bfe_u32 v209, v206, 1, 3
	v_lshlrev_b32_e32 v211, 7, v207
	s_lshr_b32 s91, s70, 7
	s_lshl_b32 s31, s91, 6
	s_lshl_b32 s91, s91, 13
	s_lshl_b32 s34, s90, 1
	s_lshl_b32 s90, s90, 8
	s_add_u32 s90, s90, 0x8000
	v_xor_b32_e32 v212, v208, v209
	v_lshl_add_u32 v212, v212, 4, v211
	v_add_u32_e32 v184, s91, v212
	v_add_u32_e32 v188, s90, v212
	v_add_u32_e32 v246, 0x10000, v184
	v_add_u32_e32 v250, 0x10000, v188
	v_or_b32_e32 v212, 2, v208
	v_xor_b32_e32 v212, v212, v209
	v_lshl_add_u32 v212, v212, 4, v211
	v_add_u32_e32 v185, s91, v212
	v_add_u32_e32 v189, s90, v212
	v_add_u32_e32 v247, 0x10000, v185
	v_add_u32_e32 v251, 0x10000, v189
	v_or_b32_e32 v212, 4, v208
	v_xor_b32_e32 v212, v212, v209
	v_lshl_add_u32 v212, v212, 4, v211
	v_add_u32_e32 v186, s91, v212
	v_add_u32_e32 v190, s90, v212
	v_add_u32_e32 v248, 0x10000, v186
	v_add_u32_e32 v252, 0x10000, v190
	v_or_b32_e32 v212, 6, v208
	v_xor_b32_e32 v212, v212, v209
	v_lshl_add_u32 v212, v212, 4, v211
	v_add_u32_e32 v187, s91, v212
	v_add_u32_e32 v191, s90, v212
	v_add_u32_e32 v249, 0x10000, v187
	v_add_u32_e32 v253, 0x10000, v191
	v_lshlrev_b32_e32 v200, 3, v207
	v_lshlrev_b32_e32 v203, 2, v208
	s_mul_i32 s91, s29, 0x1200
	s_add_u32 s91, s91, 0x12000
	v_mul_u32_u24_e32 v212, 0x240, v208
	v_lshl_add_u32 v212, v207, 1, v212
	v_add_u32_e32 v201, s91, v212
	v_lshrrev_b32_e32 v204, 3, v206
	v_and_b32_e32 v212, 7, v206
	v_lshlrev_b32_e32 v205, 4, v212
	v_mul_u32_u24_e32 v212, 0x90, v204
	v_add3_u32 v202, v212, v205, s91
	s_load_dwordx2 s[4:5], s[0:1], 0x168
	s_load_dwordx2 s[6:7], s[0:1], 0xd0
	s_load_dwordx2 s[8:9], s[0:1], 0x210
	s_load_dwordx2 s[10:11], s[0:1], 0x148
	s_load_dwordx2 s[12:13], s[0:1], 0x178
	s_lshl_b32 s96, s29, 3
	v_add_u32_e32 v206, s96, v204
	v_xor_b32_e32 v207, v245, v205
	v_lshl_add_u32 v192, v206, 9, v207
	v_mov_b32_e32 v193, 0
	v_add_u32_e32 v208, 64, v206
	v_lshl_add_u32 v194, v208, 9, v207
	v_mov_b32_e32 v195, 0
	v_add_u32_e32 v208, 128, v206
	v_lshl_add_u32 v196, v208, 9, v207
	v_mov_b32_e32 v197, 0
	v_add_u32_e32 v208, 192, v206
	v_lshl_add_u32 v198, v208, 9, v207
	v_mov_b32_e32 v199, 0
	s_mov_b32 s30, s28
	s_cmp_ge_u32 s30, 768
	s_cbranch_scc1 .Lmq3q_done
	s_waitcnt lgkmcnt(0)
	s_mul_hi_u32 s35, s30, 0xaaaaaaab
	s_lshr_b32 s35, s35, 2
	s_mul_i32 s36, s35, 6
	s_sub_u32 s36, s30, s36
	s_lshl_b32 s98, s35, 17
	s_add_u32 s16, s4, s98
	s_addc_u32 s17, s5, 0
	s_lshl_b32 s98, s36, 17
	s_add_u32 s18, s6, s98
	s_addc_u32 s19, s7, 0
	s_add_u32 m0, s88, 0
	s_nop 0
	global_load_lds_dwordx4 v192, s[16:17]
	s_add_u32 m0, s88, 32768
	s_nop 0
	global_load_lds_dwordx4 v192, s[18:19]
	s_add_u32 m0, s88, 8192
	s_nop 0
	global_load_lds_dwordx4 v194, s[16:17]
	s_add_u32 m0, s88, 40960
	s_nop 0
	global_load_lds_dwordx4 v194, s[18:19]
	s_add_u32 m0, s88, 16384
	s_nop 0
	global_load_lds_dwordx4 v196, s[16:17]
	s_add_u32 m0, s88, 49152
	s_nop 0
	global_load_lds_dwordx4 v196, s[18:19]
	s_add_u32 m0, s88, 24576
	s_nop 0
	global_load_lds_dwordx4 v198, s[16:17]
	s_add_u32 m0, s88, 57344
	s_nop 0
	global_load_lds_dwordx4 v198, s[18:19]
.Lmq3q_tile:
	s_mul_hi_u32 s35, s30, 0xaaaaaaab
	s_lshr_b32 s35, s35, 2
	s_mul_i32 s36, s35, 6
	s_sub_u32 s36, s30, s36
	s_lshl_b32 s92, s35, 8
	s_add_u32 s92, s92, s31
	s_lshl_b32 s93, s36, 8
	s_add_u32 s93, s93, s34
	s_lshl_b32 s96, s92, 2
	v_lshl_add_u32 v212, v203, 2, s96
	s_waitcnt vmcnt(0)
	s_barrier
	s_add_u32 s20, s16, 128
	s_addc_u32 s21, s17, 0
	s_add_u32 s24, s18, 128
	s_addc_u32 s25, s19, 0
	s_add_u32 m0, s88, 65536
	s_nop 0
	global_load_lds_dwordx4 v192, s[20:21]
	s_add_u32 m0, s88, 98304
	s_nop 0
	global_load_lds_dwordx4 v192, s[24:25]
	s_add_u32 m0, s88, 73728
	s_nop 0
	global_load_lds_dwordx4 v194, s[20:21]
	s_add_u32 m0, s88, 106496
	s_nop 0
	global_load_lds_dwordx4 v194, s[24:25]
	s_add_u32 m0, s88, 81920
	s_nop 0
	global_load_lds_dwordx4 v196, s[20:21]
	s_add_u32 m0, s88, 114688
	s_nop 0
	global_load_lds_dwordx4 v196, s[24:25]
	s_add_u32 m0, s88, 90112
	s_nop 0
	global_load_lds_dwordx4 v198, s[20:21]
	s_add_u32 m0, s88, 122880
	s_nop 0
	global_load_lds_dwordx4 v198, s[24:25]
	global_load_dword v213, v212, s[8:9] offset:0
	global_load_dword v214, v212, s[8:9] offset:4
	global_load_dword v215, v212, s[8:9] offset:8
	global_load_dword v216, v212, s[8:9] offset:12
	global_load_dword v217, v212, s[8:9] offset:32
	global_load_dword v218, v212, s[8:9] offset:36
	global_load_dword v219, v212, s[8:9] offset:40
	global_load_dword v220, v212, s[8:9] offset:44
	global_load_dword v221, v212, s[8:9] offset:64
	global_load_dword v222, v212, s[8:9] offset:68
	global_load_dword v223, v212, s[8:9] offset:72
	global_load_dword v224, v212, s[8:9] offset:76
	global_load_dword v225, v212, s[8:9] offset:96
	global_load_dword v226, v212, s[8:9] offset:100
	global_load_dword v227, v212, s[8:9] offset:104
	global_load_dword v228, v212, s[8:9] offset:108
	global_load_dword v229, v212, s[8:9] offset:128
	global_load_dword v230, v212, s[8:9] offset:132
	global_load_dword v231, v212, s[8:9] offset:136
	global_load_dword v232, v212, s[8:9] offset:140
	global_load_dword v233, v212, s[8:9] offset:160
	global_load_dword v234, v212, s[8:9] offset:164
	global_load_dword v235, v212, s[8:9] offset:168
	global_load_dword v236, v212, s[8:9] offset:172
	global_load_dword v237, v212, s[8:9] offset:192
	global_load_dword v238, v212, s[8:9] offset:196
	global_load_dword v239, v212, s[8:9] offset:200
	global_load_dword v240, v212, s[8:9] offset:204
	global_load_dword v241, v212, s[8:9] offset:224
	global_load_dword v242, v212, s[8:9] offset:228
	global_load_dword v243, v212, s[8:9] offset:232
	global_load_dword v244, v212, s[8:9] offset:236
	ds_read_b128 v[160:163], v184
	ds_read_b128 v[168:171], v188
	ds_read_b128 v[164:167], v184 offset:4096
	ds_read_b128 v[172:175], v188 offset:4096
	ds_read_b128 v[176:179], v188 offset:8192
	ds_read_b128 v[180:183], v188 offset:12288
	ds_read_b128 v[128:131], v185
	ds_read_b128 v[136:139], v189
	ds_read_b128 v[132:135], v185 offset:4096
	ds_read_b128 v[140:143], v189 offset:4096
	ds_read_b128 v[144:147], v189 offset:8192
	ds_read_b128 v[148:151], v189 offset:12288
	s_waitcnt lgkmcnt(6)
	v_mfma_f32_32x32x16_bf16 v[112:127], v[160:163], v[168:171], 0
	v_mfma_f32_32x32x16_bf16 v[48:63], v[164:167], v[168:171], 0
	v_mfma_f32_32x32x16_bf16 v[96:111], v[160:163], v[172:175], 0
	v_mfma_f32_32x32x16_bf16 v[32:47], v[164:167], v[172:175], 0
	v_mfma_f32_32x32x16_bf16 v[80:95], v[160:163], v[176:179], 0
	v_mfma_f32_32x32x16_bf16 v[16:31], v[164:167], v[176:179], 0
	v_mfma_f32_32x32x16_bf16 v[64:79], v[160:163], v[180:183], 0
	v_mfma_f32_32x32x16_bf16 v[0:15], v[164:167], v[180:183], 0
	ds_read_b128 v[160:163], v186
	ds_read_b128 v[168:171], v190
	ds_read_b128 v[164:167], v186 offset:4096
	ds_read_b128 v[172:175], v190 offset:4096
	ds_read_b128 v[176:179], v190 offset:8192
	ds_read_b128 v[180:183], v190 offset:12288
	s_waitcnt lgkmcnt(6)
	v_mfma_f32_32x32x16_bf16 v[112:127], v[128:131], v[136:139], v[112:127]
	v_mfma_f32_32x32x16_bf16 v[48:63], v[132:135], v[136:139], v[48:63]
	v_mfma_f32_32x32x16_bf16 v[96:111], v[128:131], v[140:143], v[96:111]
	v_mfma_f32_32x32x16_bf16 v[32:47], v[132:135], v[140:143], v[32:47]
	v_mfma_f32_32x32x16_bf16 v[80:95], v[128:131], v[144:147], v[80:95]
	v_mfma_f32_32x32x16_bf16 v[16:31], v[132:135], v[144:147], v[16:31]
	v_mfma_f32_32x32x16_bf16 v[64:79], v[128:131], v[148:151], v[64:79]
	v_mfma_f32_32x32x16_bf16 v[0:15], v[132:135], v[148:151], v[0:15]
	ds_read_b128 v[128:131], v187
	ds_read_b128 v[136:139], v191
	ds_read_b128 v[132:135], v187 offset:4096
	ds_read_b128 v[140:143], v191 offset:4096
	ds_read_b128 v[144:147], v191 offset:8192
	ds_read_b128 v[148:151], v191 offset:12288
	s_waitcnt lgkmcnt(6)
	v_mfma_f32_32x32x16_bf16 v[112:127], v[160:163], v[168:171], v[112:127]
	v_mfma_f32_32x32x16_bf16 v[48:63], v[164:167], v[168:171], v[48:63]
	v_mfma_f32_32x32x16_bf16 v[96:111], v[160:163], v[172:175], v[96:111]
	v_mfma_f32_32x32x16_bf16 v[32:47], v[164:167], v[172:175], v[32:47]
	v_mfma_f32_32x32x16_bf16 v[80:95], v[160:163], v[176:179], v[80:95]
	v_mfma_f32_32x32x16_bf16 v[16:31], v[164:167], v[176:179], v[16:31]
	v_mfma_f32_32x32x16_bf16 v[64:79], v[160:163], v[180:183], v[64:79]
	v_mfma_f32_32x32x16_bf16 v[0:15], v[164:167], v[180:183], v[0:15]
	s_waitcnt vmcnt(0) lgkmcnt(0)
	s_barrier
	ds_read_b128 v[160:163], v246
	ds_read_b128 v[168:171], v250
	ds_read_b128 v[164:167], v246 offset:4096
	ds_read_b128 v[172:175], v250 offset:4096
	ds_read_b128 v[176:179], v250 offset:8192
	ds_read_b128 v[180:183], v250 offset:12288
	s_add_u32 s20, s16, 256
	s_addc_u32 s21, s17, 0
	s_add_u32 s24, s18, 256
	s_addc_u32 s25, s19, 0
	s_add_u32 m0, s88, 0
	v_mfma_f32_32x32x16_bf16 v[112:127], v[128:131], v[136:139], v[112:127]
	global_load_lds_dwordx4 v192, s[20:21]
	s_add_u32 m0, s88, 32768
	v_mfma_f32_32x32x16_bf16 v[48:63], v[132:135], v[136:139], v[48:63]
	global_load_lds_dwordx4 v192, s[24:25]
	s_add_u32 m0, s88, 8192
	v_mfma_f32_32x32x16_bf16 v[96:111], v[128:131], v[140:143], v[96:111]
	global_load_lds_dwordx4 v194, s[20:21]
	s_add_u32 m0, s88, 40960
	v_mfma_f32_32x32x16_bf16 v[32:47], v[132:135], v[140:143], v[32:47]
	global_load_lds_dwordx4 v194, s[24:25]
	s_add_u32 m0, s88, 16384
	v_mfma_f32_32x32x16_bf16 v[80:95], v[128:131], v[144:147], v[80:95]
	global_load_lds_dwordx4 v196, s[20:21]
	s_add_u32 m0, s88, 49152
	v_mfma_f32_32x32x16_bf16 v[16:31], v[132:135], v[144:147], v[16:31]
	global_load_lds_dwordx4 v196, s[24:25]
	s_add_u32 m0, s88, 24576
	v_mfma_f32_32x32x16_bf16 v[64:79], v[128:131], v[148:151], v[64:79]
	global_load_lds_dwordx4 v198, s[20:21]
	s_add_u32 m0, s88, 57344
	v_mfma_f32_32x32x16_bf16 v[0:15], v[132:135], v[148:151], v[0:15]
	global_load_lds_dwordx4 v198, s[24:25]
	ds_read_b128 v[128:131], v247
	ds_read_b128 v[136:139], v251
	ds_read_b128 v[132:135], v247 offset:4096
	ds_read_b128 v[140:143], v251 offset:4096
	ds_read_b128 v[144:147], v251 offset:8192
	ds_read_b128 v[148:151], v251 offset:12288
	s_waitcnt lgkmcnt(6)
	v_mfma_f32_32x32x16_bf16 v[112:127], v[160:163], v[168:171], v[112:127]
	v_mfma_f32_32x32x16_bf16 v[48:63], v[164:167], v[168:171], v[48:63]
	v_mfma_f32_32x32x16_bf16 v[96:111], v[160:163], v[172:175], v[96:111]
	v_mfma_f32_32x32x16_bf16 v[32:47], v[164:167], v[172:175], v[32:47]
	v_mfma_f32_32x32x16_bf16 v[80:95], v[160:163], v[176:179], v[80:95]
	v_mfma_f32_32x32x16_bf16 v[16:31], v[164:167], v[176:179], v[16:31]
	v_mfma_f32_32x32x16_bf16 v[64:79], v[160:163], v[180:183], v[64:79]
	v_mfma_f32_32x32x16_bf16 v[0:15], v[164:167], v[180:183], v[0:15]
	ds_read_b128 v[160:163], v248
	ds_read_b128 v[168:171], v252
	ds_read_b128 v[164:167], v248 offset:4096
	ds_read_b128 v[172:175], v252 offset:4096
	ds_read_b128 v[176:179], v252 offset:8192
	ds_read_b128 v[180:183], v252 offset:12288
	s_waitcnt lgkmcnt(6)
	v_mfma_f32_32x32x16_bf16 v[112:127], v[128:131], v[136:139], v[112:127]
	v_mfma_f32_32x32x16_bf16 v[48:63], v[132:135], v[136:139], v[48:63]
	v_mfma_f32_32x32x16_bf16 v[96:111], v[128:131], v[140:143], v[96:111]
	v_mfma_f32_32x32x16_bf16 v[32:47], v[132:135], v[140:143], v[32:47]
	v_mfma_f32_32x32x16_bf16 v[80:95], v[128:131], v[144:147], v[80:95]
	v_mfma_f32_32x32x16_bf16 v[16:31], v[132:135], v[144:147], v[16:31]
	v_mfma_f32_32x32x16_bf16 v[64:79], v[128:131], v[148:151], v[64:79]
	v_mfma_f32_32x32x16_bf16 v[0:15], v[132:135], v[148:151], v[0:15]
	ds_read_b128 v[128:131], v249
	ds_read_b128 v[136:139], v253
	ds_read_b128 v[132:135], v249 offset:4096
	ds_read_b128 v[140:143], v253 offset:4096
	ds_read_b128 v[144:147], v253 offset:8192
	ds_read_b128 v[148:151], v253 offset:12288
	s_waitcnt lgkmcnt(6)
	v_mfma_f32_32x32x16_bf16 v[112:127], v[160:163], v[168:171], v[112:127]
	v_mfma_f32_32x32x16_bf16 v[48:63], v[164:167], v[168:171], v[48:63]
	v_mfma_f32_32x32x16_bf16 v[96:111], v[160:163], v[172:175], v[96:111]
	v_mfma_f32_32x32x16_bf16 v[32:47], v[164:167], v[172:175], v[32:47]
	v_mfma_f32_32x32x16_bf16 v[80:95], v[160:163], v[176:179], v[80:95]
	v_mfma_f32_32x32x16_bf16 v[16:31], v[164:167], v[176:179], v[16:31]
	v_mfma_f32_32x32x16_bf16 v[64:79], v[160:163], v[180:183], v[64:79]
	v_mfma_f32_32x32x16_bf16 v[0:15], v[164:167], v[180:183], v[0:15]
	s_waitcnt vmcnt(0) lgkmcnt(0)
	s_barrier
	ds_read_b128 v[160:163], v184
	ds_read_b128 v[168:171], v188
	ds_read_b128 v[164:167], v184 offset:4096
	ds_read_b128 v[172:175], v188 offset:4096
	ds_read_b128 v[176:179], v188 offset:8192
	ds_read_b128 v[180:183], v188 offset:12288
	s_add_u32 s20, s16, 384
	s_addc_u32 s21, s17, 0
	s_add_u32 s24, s18, 384
	s_addc_u32 s25, s19, 0
	s_add_u32 m0, s88, 65536
	v_mfma_f32_32x32x16_bf16 v[112:127], v[128:131], v[136:139], v[112:127]
	global_load_lds_dwordx4 v192, s[20:21]
	s_add_u32 m0, s88, 98304
	v_mfma_f32_32x32x16_bf16 v[48:63], v[132:135], v[136:139], v[48:63]
	global_load_lds_dwordx4 v192, s[24:25]
	s_add_u32 m0, s88, 73728
	v_mfma_f32_32x32x16_bf16 v[96:111], v[128:131], v[140:143], v[96:111]
	global_load_lds_dwordx4 v194, s[20:21]
	s_add_u32 m0, s88, 106496
	v_mfma_f32_32x32x16_bf16 v[32:47], v[132:135], v[140:143], v[32:47]
	global_load_lds_dwordx4 v194, s[24:25]
	s_add_u32 m0, s88, 81920
	v_mfma_f32_32x32x16_bf16 v[80:95], v[128:131], v[144:147], v[80:95]
	global_load_lds_dwordx4 v196, s[20:21]
	s_add_u32 m0, s88, 114688
	v_mfma_f32_32x32x16_bf16 v[16:31], v[132:135], v[144:147], v[16:31]
	global_load_lds_dwordx4 v196, s[24:25]
	s_add_u32 m0, s88, 90112
	v_mfma_f32_32x32x16_bf16 v[64:79], v[128:131], v[148:151], v[64:79]
	global_load_lds_dwordx4 v198, s[20:21]
	s_add_u32 m0, s88, 122880
	v_mfma_f32_32x32x16_bf16 v[0:15], v[132:135], v[148:151], v[0:15]
	global_load_lds_dwordx4 v198, s[24:25]
	ds_read_b128 v[128:131], v185
	ds_read_b128 v[136:139], v189
	ds_read_b128 v[132:135], v185 offset:4096
	ds_read_b128 v[140:143], v189 offset:4096
	ds_read_b128 v[144:147], v189 offset:8192
	ds_read_b128 v[148:151], v189 offset:12288
	s_waitcnt lgkmcnt(6)
	v_mfma_f32_32x32x16_bf16 v[112:127], v[160:163], v[168:171], v[112:127]
	v_mfma_f32_32x32x16_bf16 v[48:63], v[164:167], v[168:171], v[48:63]
	v_mfma_f32_32x32x16_bf16 v[96:111], v[160:163], v[172:175], v[96:111]
	v_mfma_f32_32x32x16_bf16 v[32:47], v[164:167], v[172:175], v[32:47]
	v_mfma_f32_32x32x16_bf16 v[80:95], v[160:163], v[176:179], v[80:95]
	v_mfma_f32_32x32x16_bf16 v[16:31], v[164:167], v[176:179], v[16:31]
	v_mfma_f32_32x32x16_bf16 v[64:79], v[160:163], v[180:183], v[64:79]
	v_mfma_f32_32x32x16_bf16 v[0:15], v[164:167], v[180:183], v[0:15]
	ds_read_b128 v[160:163], v186
	ds_read_b128 v[168:171], v190
	ds_read_b128 v[164:167], v186 offset:4096
	ds_read_b128 v[172:175], v190 offset:4096
	ds_read_b128 v[176:179], v190 offset:8192
	ds_read_b128 v[180:183], v190 offset:12288
	s_waitcnt lgkmcnt(6)
	v_mfma_f32_32x32x16_bf16 v[112:127], v[128:131], v[136:139], v[112:127]
	v_mfma_f32_32x32x16_bf16 v[48:63], v[132:135], v[136:139], v[48:63]
	v_mfma_f32_32x32x16_bf16 v[96:111], v[128:131], v[140:143], v[96:111]
	v_mfma_f32_32x32x16_bf16 v[32:47], v[132:135], v[140:143], v[32:47]
	v_mfma_f32_32x32x16_bf16 v[80:95], v[128:131], v[144:147], v[80:95]
	v_mfma_f32_32x32x16_bf16 v[16:31], v[132:135], v[144:147], v[16:31]
	v_mfma_f32_32x32x16_bf16 v[64:79], v[128:131], v[148:151], v[64:79]
	v_mfma_f32_32x32x16_bf16 v[0:15], v[132:135], v[148:151], v[0:15]
	ds_read_b128 v[128:131], v187
	ds_read_b128 v[136:139], v191
	ds_read_b128 v[132:135], v187 offset:4096
	ds_read_b128 v[140:143], v191 offset:4096
	ds_read_b128 v[144:147], v191 offset:8192
	ds_read_b128 v[148:151], v191 offset:12288
	s_waitcnt lgkmcnt(6)
	v_mfma_f32_32x32x16_bf16 v[112:127], v[160:163], v[168:171], v[112:127]
	v_mfma_f32_32x32x16_bf16 v[48:63], v[164:167], v[168:171], v[48:63]
	v_mfma_f32_32x32x16_bf16 v[96:111], v[160:163], v[172:175], v[96:111]
	v_mfma_f32_32x32x16_bf16 v[32:47], v[164:167], v[172:175], v[32:47]
	v_mfma_f32_32x32x16_bf16 v[80:95], v[160:163], v[176:179], v[80:95]
	v_mfma_f32_32x32x16_bf16 v[16:31], v[164:167], v[176:179], v[16:31]
	v_mfma_f32_32x32x16_bf16 v[64:79], v[160:163], v[180:183], v[64:79]
	v_mfma_f32_32x32x16_bf16 v[0:15], v[164:167], v[180:183], v[0:15]
	s_waitcnt vmcnt(0) lgkmcnt(0)
	s_barrier
	ds_read_b128 v[160:163], v246
	ds_read_b128 v[168:171], v250
	ds_read_b128 v[164:167], v246 offset:4096
	ds_read_b128 v[172:175], v250 offset:4096
	ds_read_b128 v[176:179], v250 offset:8192
	ds_read_b128 v[180:183], v250 offset:12288
	s_add_u32 s37, s30, s42
	s_cmp_ge_u32 s37, 768
	s_cbranch_scc1 .Lmq3q_nonext2
	s_mul_hi_u32 s38, s37, 0xaaaaaaab
	s_lshr_b32 s38, s38, 2
	s_mul_i32 s39, s38, 6
	s_sub_u32 s39, s37, s39
	s_lshl_b32 s98, s38, 17
	s_add_u32 s16, s4, s98
	s_addc_u32 s17, s5, 0
	s_lshl_b32 s98, s39, 17
	s_add_u32 s18, s6, s98
	s_addc_u32 s19, s7, 0
	s_add_u32 m0, s88, 0
	v_mfma_f32_32x32x16_bf16 v[112:127], v[128:131], v[136:139], v[112:127]
	global_load_lds_dwordx4 v192, s[16:17]
	s_add_u32 m0, s88, 32768
	v_mfma_f32_32x32x16_bf16 v[48:63], v[132:135], v[136:139], v[48:63]
	global_load_lds_dwordx4 v192, s[18:19]
	s_add_u32 m0, s88, 8192
	v_mfma_f32_32x32x16_bf16 v[96:111], v[128:131], v[140:143], v[96:111]
	global_load_lds_dwordx4 v194, s[16:17]
	s_add_u32 m0, s88, 40960
	v_mfma_f32_32x32x16_bf16 v[32:47], v[132:135], v[140:143], v[32:47]
	global_load_lds_dwordx4 v194, s[18:19]
	s_add_u32 m0, s88, 16384
	v_mfma_f32_32x32x16_bf16 v[80:95], v[128:131], v[144:147], v[80:95]
	global_load_lds_dwordx4 v196, s[16:17]
	s_add_u32 m0, s88, 49152
	v_mfma_f32_32x32x16_bf16 v[16:31], v[132:135], v[144:147], v[16:31]
	global_load_lds_dwordx4 v196, s[18:19]
	s_add_u32 m0, s88, 24576
	v_mfma_f32_32x32x16_bf16 v[64:79], v[128:131], v[148:151], v[64:79]
	global_load_lds_dwordx4 v198, s[16:17]
	s_add_u32 m0, s88, 57344
	v_mfma_f32_32x32x16_bf16 v[0:15], v[132:135], v[148:151], v[0:15]
	global_load_lds_dwordx4 v198, s[18:19]
	s_branch .Lmq3q_join2
.Lmq3q_nonext2:
	v_mfma_f32_32x32x16_bf16 v[112:127], v[128:131], v[136:139], v[112:127]
	v_mfma_f32_32x32x16_bf16 v[48:63], v[132:135], v[136:139], v[48:63]
	v_mfma_f32_32x32x16_bf16 v[96:111], v[128:131], v[140:143], v[96:111]
	v_mfma_f32_32x32x16_bf16 v[32:47], v[132:135], v[140:143], v[32:47]
	v_mfma_f32_32x32x16_bf16 v[80:95], v[128:131], v[144:147], v[80:95]
	v_mfma_f32_32x32x16_bf16 v[16:31], v[132:135], v[144:147], v[16:31]
	v_mfma_f32_32x32x16_bf16 v[64:79], v[128:131], v[148:151], v[64:79]
	v_mfma_f32_32x32x16_bf16 v[0:15], v[132:135], v[148:151], v[0:15]
.Lmq3q_join2:
	ds_read_b128 v[128:131], v247
	ds_read_b128 v[136:139], v251
	ds_read_b128 v[132:135], v247 offset:4096
	ds_read_b128 v[140:143], v251 offset:4096
	ds_read_b128 v[144:147], v251 offset:8192
	ds_read_b128 v[148:151], v251 offset:12288
	s_waitcnt lgkmcnt(6)
	v_mfma_f32_32x32x16_bf16 v[112:127], v[160:163], v[168:171], v[112:127]
	v_mfma_f32_32x32x16_bf16 v[48:63], v[164:167], v[168:171], v[48:63]
	v_mfma_f32_32x32x16_bf16 v[96:111], v[160:163], v[172:175], v[96:111]
	v_mfma_f32_32x32x16_bf16 v[32:47], v[164:167], v[172:175], v[32:47]
	v_mfma_f32_32x32x16_bf16 v[80:95], v[160:163], v[176:179], v[80:95]
	v_mfma_f32_32x32x16_bf16 v[16:31], v[164:167], v[176:179], v[16:31]
	v_mfma_f32_32x32x16_bf16 v[64:79], v[160:163], v[180:183], v[64:79]
	v_mfma_f32_32x32x16_bf16 v[0:15], v[164:167], v[180:183], v[0:15]
	ds_read_b128 v[160:163], v248
	ds_read_b128 v[168:171], v252
	ds_read_b128 v[164:167], v248 offset:4096
	ds_read_b128 v[172:175], v252 offset:4096
	ds_read_b128 v[176:179], v252 offset:8192
	ds_read_b128 v[180:183], v252 offset:12288
	s_waitcnt lgkmcnt(6)
	v_mfma_f32_32x32x16_bf16 v[112:127], v[128:131], v[136:139], v[112:127]
	v_mfma_f32_32x32x16_bf16 v[48:63], v[132:135], v[136:139], v[48:63]
	v_mfma_f32_32x32x16_bf16 v[96:111], v[128:131], v[140:143], v[96:111]
	v_mfma_f32_32x32x16_bf16 v[32:47], v[132:135], v[140:143], v[32:47]
	v_mfma_f32_32x32x16_bf16 v[80:95], v[128:131], v[144:147], v[80:95]
	v_mfma_f32_32x32x16_bf16 v[16:31], v[132:135], v[144:147], v[16:31]
	v_mfma_f32_32x32x16_bf16 v[64:79], v[128:131], v[148:151], v[64:79]
	v_mfma_f32_32x32x16_bf16 v[0:15], v[132:135], v[148:151], v[0:15]
	ds_read_b128 v[128:131], v249
	ds_read_b128 v[136:139], v253
	ds_read_b128 v[132:135], v249 offset:4096
	ds_read_b128 v[140:143], v253 offset:4096
	ds_read_b128 v[144:147], v253 offset:8192
	ds_read_b128 v[148:151], v253 offset:12288
	s_waitcnt lgkmcnt(6)
	v_mfma_f32_32x32x16_bf16 v[112:127], v[160:163], v[168:171], v[112:127]
	v_mfma_f32_32x32x16_bf16 v[48:63], v[164:167], v[168:171], v[48:63]
	v_mfma_f32_32x32x16_bf16 v[96:111], v[160:163], v[172:175], v[96:111]
	v_mfma_f32_32x32x16_bf16 v[32:47], v[164:167], v[172:175], v[32:47]
	v_mfma_f32_32x32x16_bf16 v[80:95], v[160:163], v[176:179], v[80:95]
	v_mfma_f32_32x32x16_bf16 v[16:31], v[164:167], v[176:179], v[16:31]
	v_mfma_f32_32x32x16_bf16 v[64:79], v[160:163], v[180:183], v[64:79]
	v_mfma_f32_32x32x16_bf16 v[0:15], v[164:167], v[180:183], v[0:15]
	s_waitcnt vmcnt(0) lgkmcnt(0)
	s_barrier
	v_mfma_f32_32x32x16_bf16 v[112:127], v[128:131], v[136:139], v[112:127]
	v_mul_f32_e32 v213, 0x3b800000, v213
	v_mul_f32_e32 v214, 0x3b800000, v214
	v_mul_f32_e32 v215, 0x3b800000, v215
	v_mul_f32_e32 v216, 0x3b800000, v216
	v_add_f32_e32 v213, 0x358637bd, v213
	v_add_f32_e32 v214, 0x358637bd, v214
	v_add_f32_e32 v215, 0x358637bd, v215
	v_add_f32_e32 v216, 0x358637bd, v216
	v_rsq_f32_e32 v213, v213
	v_rsq_f32_e32 v214, v214
	v_rsq_f32_e32 v215, v215
	v_rsq_f32_e32 v216, v216
	v_mul_f32_e32 v213, 0x3dd53b94, v213
	v_mul_f32_e32 v214, 0x3dd53b94, v214
	v_mul_f32_e32 v215, 0x3dd53b94, v215
	v_mul_f32_e32 v216, 0x3dd53b94, v216
	v_mfma_f32_32x32x16_bf16 v[48:63], v[132:135], v[136:139], v[48:63]
	v_mul_f32_e32 v217, 0x3b800000, v217
	v_mul_f32_e32 v218, 0x3b800000, v218
	v_mul_f32_e32 v219, 0x3b800000, v219
	v_mul_f32_e32 v220, 0x3b800000, v220
	v_add_f32_e32 v217, 0x358637bd, v217
	v_add_f32_e32 v218, 0x358637bd, v218
	v_add_f32_e32 v219, 0x358637bd, v219
	v_add_f32_e32 v220, 0x358637bd, v220
	v_rsq_f32_e32 v217, v217
	v_rsq_f32_e32 v218, v218
	v_rsq_f32_e32 v219, v219
	v_rsq_f32_e32 v220, v220
	v_mul_f32_e32 v217, 0x3dd53b94, v217
	v_mul_f32_e32 v218, 0x3dd53b94, v218
	v_mul_f32_e32 v219, 0x3dd53b94, v219
	v_mul_f32_e32 v220, 0x3dd53b94, v220
	v_mfma_f32_32x32x16_bf16 v[96:111], v[128:131], v[140:143], v[96:111]
	v_mul_f32_e32 v221, 0x3b800000, v221
	v_mul_f32_e32 v222, 0x3b800000, v222
	v_mul_f32_e32 v223, 0x3b800000, v223
	v_mul_f32_e32 v224, 0x3b800000, v224
	v_add_f32_e32 v221, 0x358637bd, v221
	v_add_f32_e32 v222, 0x358637bd, v222
	v_add_f32_e32 v223, 0x358637bd, v223
	v_add_f32_e32 v224, 0x358637bd, v224
	v_rsq_f32_e32 v221, v221
	v_rsq_f32_e32 v222, v222
	v_rsq_f32_e32 v223, v223
	v_rsq_f32_e32 v224, v224
	v_mul_f32_e32 v221, 0x3dd53b94, v221
	v_mul_f32_e32 v222, 0x3dd53b94, v222
	v_mul_f32_e32 v223, 0x3dd53b94, v223
	v_mul_f32_e32 v224, 0x3dd53b94, v224
	v_mfma_f32_32x32x16_bf16 v[32:47], v[132:135], v[140:143], v[32:47]
	v_mul_f32_e32 v225, 0x3b800000, v225
	v_mul_f32_e32 v226, 0x3b800000, v226
	v_mul_f32_e32 v227, 0x3b800000, v227
	v_mul_f32_e32 v228, 0x3b800000, v228
	v_add_f32_e32 v225, 0x358637bd, v225
	v_add_f32_e32 v226, 0x358637bd, v226
	v_add_f32_e32 v227, 0x358637bd, v227
	v_add_f32_e32 v228, 0x358637bd, v228
	v_rsq_f32_e32 v225, v225
	v_rsq_f32_e32 v226, v226
	v_rsq_f32_e32 v227, v227
	v_rsq_f32_e32 v228, v228
	v_mul_f32_e32 v225, 0x3dd53b94, v225
	v_mul_f32_e32 v226, 0x3dd53b94, v226
	v_mul_f32_e32 v227, 0x3dd53b94, v227
	v_mul_f32_e32 v228, 0x3dd53b94, v228
	v_mfma_f32_32x32x16_bf16 v[80:95], v[128:131], v[144:147], v[80:95]
	v_mul_f32_e32 v229, 0x3b800000, v229
	v_mul_f32_e32 v230, 0x3b800000, v230
	v_mul_f32_e32 v231, 0x3b800000, v231
	v_mul_f32_e32 v232, 0x3b800000, v232
	v_add_f32_e32 v229, 0x358637bd, v229
	v_add_f32_e32 v230, 0x358637bd, v230
	v_add_f32_e32 v231, 0x358637bd, v231
	v_add_f32_e32 v232, 0x358637bd, v232
	v_rsq_f32_e32 v229, v229
	v_rsq_f32_e32 v230, v230
	v_rsq_f32_e32 v231, v231
	v_rsq_f32_e32 v232, v232
	v_mul_f32_e32 v229, 0x3dd53b94, v229
	v_mul_f32_e32 v230, 0x3dd53b94, v230
	v_mul_f32_e32 v231, 0x3dd53b94, v231
	v_mul_f32_e32 v232, 0x3dd53b94, v232
	v_mfma_f32_32x32x16_bf16 v[16:31], v[132:135], v[144:147], v[16:31]
	v_mul_f32_e32 v233, 0x3b800000, v233
	v_mul_f32_e32 v234, 0x3b800000, v234
	v_mul_f32_e32 v235, 0x3b800000, v235
	v_mul_f32_e32 v236, 0x3b800000, v236
	v_add_f32_e32 v233, 0x358637bd, v233
	v_add_f32_e32 v234, 0x358637bd, v234
	v_add_f32_e32 v235, 0x358637bd, v235
	v_add_f32_e32 v236, 0x358637bd, v236
	v_rsq_f32_e32 v233, v233
	v_rsq_f32_e32 v234, v234
	v_rsq_f32_e32 v235, v235
	v_rsq_f32_e32 v236, v236
	v_mul_f32_e32 v233, 0x3dd53b94, v233
	v_mul_f32_e32 v234, 0x3dd53b94, v234
	v_mul_f32_e32 v235, 0x3dd53b94, v235
	v_mul_f32_e32 v236, 0x3dd53b94, v236
	v_mfma_f32_32x32x16_bf16 v[64:79], v[128:131], v[148:151], v[64:79]
	v_mul_f32_e32 v237, 0x3b800000, v237
	v_mul_f32_e32 v238, 0x3b800000, v238
	v_mul_f32_e32 v239, 0x3b800000, v239
	v_mul_f32_e32 v240, 0x3b800000, v240
	v_add_f32_e32 v237, 0x358637bd, v237
	v_add_f32_e32 v238, 0x358637bd, v238
	v_add_f32_e32 v239, 0x358637bd, v239
	v_add_f32_e32 v240, 0x358637bd, v240
	v_rsq_f32_e32 v237, v237
	v_rsq_f32_e32 v238, v238
	v_rsq_f32_e32 v239, v239
	v_rsq_f32_e32 v240, v240
	v_mul_f32_e32 v237, 0x3dd53b94, v237
	v_mul_f32_e32 v238, 0x3dd53b94, v238
	v_mul_f32_e32 v239, 0x3dd53b94, v239
	v_mul_f32_e32 v240, 0x3dd53b94, v240
	v_mfma_f32_32x32x16_bf16 v[0:15], v[132:135], v[148:151], v[0:15]
	v_mul_f32_e32 v241, 0x3b800000, v241
	v_mul_f32_e32 v242, 0x3b800000, v242
	v_mul_f32_e32 v243, 0x3b800000, v243
	v_mul_f32_e32 v244, 0x3b800000, v244
	v_add_f32_e32 v241, 0x358637bd, v241
	v_add_f32_e32 v242, 0x358637bd, v242
	v_add_f32_e32 v243, 0x358637bd, v243
	v_add_f32_e32 v244, 0x358637bd, v244
	v_rsq_f32_e32 v241, v241
	v_rsq_f32_e32 v242, v242
	v_rsq_f32_e32 v243, v243
	v_rsq_f32_e32 v244, v244
	v_mul_f32_e32 v241, 0x3dd53b94, v241
	v_mul_f32_e32 v242, 0x3dd53b94, v242
	v_mul_f32_e32 v243, 0x3dd53b94, v243
	v_mul_f32_e32 v244, 0x3dd53b94, v244
	s_nop 7
	s_add_u32 s94, s92, 0
	s_add_u32 s95, s93, 0
	s_lshr_b32 s90, s95, 6
	s_lshr_b32 s96, s94, 12
	s_and_b32 s97, s94, 0xfff
	s_mul_i32 s91, s90, 11
	s_lshr_b32 s91, s91, 5
	s_mul_i32 s98, s91, 3
	s_sub_u32 s98, s90, s98
	s_mul_i32 s89, s96, 0xc00000
	s_mul_i32 s91, s91, 0x180000
	s_add_u32 s89, s89, s91
	s_lshl_b32 s91, s98, 7
	s_add_u32 s89, s89, s91
	s_mul_i32 s91, s97, 0x180
	s_add_u32 s89, s89, s91
	s_movk_i32 s99, 0x180
	s_mov_b64 s[2:3], s[12:13]
	s_cmp_eq_u32 s98, 2
	s_cbranch_scc1 .Lmq3q_e00_rope

.Lmq3k_tile:
	s_lshr_b32 s35, s30, 3
	s_mul_i32 s36, s35, 8
	s_sub_u32 s36, s30, s36
	s_lshl_b32 s92, s35, 8
	s_add_u32 s92, s92, s31
	s_lshl_b32 s93, s36, 8
	s_add_u32 s93, s93, s34
	s_lshl_b32 s96, s92, 2
	v_lshl_add_u32 v212, v203, 2, s96
	s_waitcnt vmcnt(0)
	s_barrier
	s_add_u32 s20, s16, 128
	s_addc_u32 s21, s17, 0
	s_add_u32 s24, s18, 128
	s_addc_u32 s25, s19, 0
	s_add_u32 m0, s88, 65536
	s_nop 0
	global_load_lds_dwordx4 v192, s[20:21]
	s_add_u32 m0, s88, 98304
	s_nop 0
	global_load_lds_dwordx4 v192, s[24:25]
	s_add_u32 m0, s88, 73728
	s_nop 0
	global_load_lds_dwordx4 v194, s[20:21]
	s_add_u32 m0, s88, 106496
	s_nop 0
	global_load_lds_dwordx4 v194, s[24:25]
	s_add_u32 m0, s88, 81920
	s_nop 0
	global_load_lds_dwordx4 v196, s[20:21]
	s_add_u32 m0, s88, 114688
	s_nop 0
	global_load_lds_dwordx4 v196, s[24:25]
	s_add_u32 m0, s88, 90112
	s_nop 0
	global_load_lds_dwordx4 v198, s[20:21]
	s_add_u32 m0, s88, 122880
	s_nop 0
	global_load_lds_dwordx4 v198, s[24:25]
	global_load_dword v213, v212, s[8:9] offset:0
	global_load_dword v214, v212, s[8:9] offset:4
	global_load_dword v215, v212, s[8:9] offset:8
	global_load_dword v216, v212, s[8:9] offset:12
	global_load_dword v217, v212, s[8:9] offset:32
	global_load_dword v218, v212, s[8:9] offset:36
	global_load_dword v219, v212, s[8:9] offset:40
	global_load_dword v220, v212, s[8:9] offset:44
	global_load_dword v221, v212, s[8:9] offset:64
	global_load_dword v222, v212, s[8:9] offset:68
	global_load_dword v223, v212, s[8:9] offset:72
	global_load_dword v224, v212, s[8:9] offset:76
	global_load_dword v225, v212, s[8:9] offset:96
	global_load_dword v226, v212, s[8:9] offset:100
	global_load_dword v227, v212, s[8:9] offset:104
	global_load_dword v228, v212, s[8:9] offset:108
	global_load_dword v229, v212, s[8:9] offset:128
	global_load_dword v230, v212, s[8:9] offset:132
	global_load_dword v231, v212, s[8:9] offset:136
	global_load_dword v232, v212, s[8:9] offset:140
	global_load_dword v233, v212, s[8:9] offset:160
	global_load_dword v234, v212, s[8:9] offset:164
	global_load_dword v235, v212, s[8:9] offset:168
	global_load_dword v236, v212, s[8:9] offset:172
	global_load_dword v237, v212, s[8:9] offset:192
	global_load_dword v238, v212, s[8:9] offset:196
	global_load_dword v239, v212, s[8:9] offset:200
	global_load_dword v240, v212, s[8:9] offset:204
	global_load_dword v241, v212, s[8:9] offset:224
	global_load_dword v242, v212, s[8:9] offset:228
	global_load_dword v243, v212, s[8:9] offset:232
	global_load_dword v244, v212, s[8:9] offset:236
	ds_read_b128 v[160:163], v184
	ds_read_b128 v[168:171], v188
	ds_read_b128 v[164:167], v184 offset:4096
	ds_read_b128 v[172:175], v188 offset:4096
	ds_read_b128 v[176:179], v188 offset:8192
	ds_read_b128 v[180:183], v188 offset:12288
	ds_read_b128 v[128:131], v185
	ds_read_b128 v[136:139], v189
	ds_read_b128 v[132:135], v185 offset:4096
	ds_read_b128 v[140:143], v189 offset:4096
	ds_read_b128 v[144:147], v189 offset:8192
	ds_read_b128 v[148:151], v189 offset:12288
	s_waitcnt lgkmcnt(6)
	v_mfma_f32_32x32x16_bf16 v[112:127], v[160:163], v[168:171], 0
	v_mfma_f32_32x32x16_bf16 v[48:63], v[164:167], v[168:171], 0
	v_mfma_f32_32x32x16_bf16 v[96:111], v[160:163], v[172:175], 0
	v_mfma_f32_32x32x16_bf16 v[32:47], v[164:167], v[172:175], 0
	v_mfma_f32_32x32x16_bf16 v[80:95], v[160:163], v[176:179], 0
	v_mfma_f32_32x32x16_bf16 v[16:31], v[164:167], v[176:179], 0
	v_mfma_f32_32x32x16_bf16 v[64:79], v[160:163], v[180:183], 0
	v_mfma_f32_32x32x16_bf16 v[0:15], v[164:167], v[180:183], 0
	ds_read_b128 v[160:163], v186
	ds_read_b128 v[168:171], v190
	ds_read_b128 v[164:167], v186 offset:4096
	ds_read_b128 v[172:175], v190 offset:4096
	ds_read_b128 v[176:179], v190 offset:8192
	ds_read_b128 v[180:183], v190 offset:12288
	s_waitcnt lgkmcnt(6)
	v_mfma_f32_32x32x16_bf16 v[112:127], v[128:131], v[136:139], v[112:127]
	v_mfma_f32_32x32x16_bf16 v[48:63], v[132:135], v[136:139], v[48:63]
	v_mfma_f32_32x32x16_bf16 v[96:111], v[128:131], v[140:143], v[96:111]
	v_mfma_f32_32x32x16_bf16 v[32:47], v[132:135], v[140:143], v[32:47]
	v_mfma_f32_32x32x16_bf16 v[80:95], v[128:131], v[144:147], v[80:95]
	v_mfma_f32_32x32x16_bf16 v[16:31], v[132:135], v[144:147], v[16:31]
	v_mfma_f32_32x32x16_bf16 v[64:79], v[128:131], v[148:151], v[64:79]
	v_mfma_f32_32x32x16_bf16 v[0:15], v[132:135], v[148:151], v[0:15]
	ds_read_b128 v[128:131], v187
	ds_read_b128 v[136:139], v191
	ds_read_b128 v[132:135], v187 offset:4096
	ds_read_b128 v[140:143], v191 offset:4096
	ds_read_b128 v[144:147], v191 offset:8192
	ds_read_b128 v[148:151], v191 offset:12288
	s_waitcnt lgkmcnt(6)
	v_mfma_f32_32x32x16_bf16 v[112:127], v[160:163], v[168:171], v[112:127]
	v_mfma_f32_32x32x16_bf16 v[48:63], v[164:167], v[168:171], v[48:63]
	v_mfma_f32_32x32x16_bf16 v[96:111], v[160:163], v[172:175], v[96:111]
	v_mfma_f32_32x32x16_bf16 v[32:47], v[164:167], v[172:175], v[32:47]
	v_mfma_f32_32x32x16_bf16 v[80:95], v[160:163], v[176:179], v[80:95]
	v_mfma_f32_32x32x16_bf16 v[16:31], v[164:167], v[176:179], v[16:31]
	v_mfma_f32_32x32x16_bf16 v[64:79], v[160:163], v[180:183], v[64:79]
	v_mfma_f32_32x32x16_bf16 v[0:15], v[164:167], v[180:183], v[0:15]
	s_waitcnt vmcnt(0) lgkmcnt(0)
	s_barrier
	ds_read_b128 v[160:163], v246
	ds_read_b128 v[168:171], v250
	ds_read_b128 v[164:167], v246 offset:4096
	ds_read_b128 v[172:175], v250 offset:4096
	ds_read_b128 v[176:179], v250 offset:8192
	ds_read_b128 v[180:183], v250 offset:12288
	s_add_u32 s37, s30, s42
	s_cmp_ge_u32 s37, 1024
	s_cbranch_scc1 .Lmq3k_nonext0
	s_lshr_b32 s38, s37, 3
	s_mul_i32 s39, s38, 8
	s_sub_u32 s39, s37, s39
	s_lshl_b32 s98, s38, 16
	s_add_u32 s16, s4, s98
	s_addc_u32 s17, s5, 0
	s_lshl_b32 s98, s39, 16
	s_add_u32 s18, s6, s98
	s_addc_u32 s19, s7, 0
	s_add_u32 m0, s88, 0
	v_mfma_f32_32x32x16_bf16 v[112:127], v[128:131], v[136:139], v[112:127]
	global_load_lds_dwordx4 v192, s[16:17]
	s_add_u32 m0, s88, 32768
	v_mfma_f32_32x32x16_bf16 v[48:63], v[132:135], v[136:139], v[48:63]
	global_load_lds_dwordx4 v192, s[18:19]
	s_add_u32 m0, s88, 8192
	v_mfma_f32_32x32x16_bf16 v[96:111], v[128:131], v[140:143], v[96:111]
	global_load_lds_dwordx4 v194, s[16:17]
	s_add_u32 m0, s88, 40960
	v_mfma_f32_32x32x16_bf16 v[32:47], v[132:135], v[140:143], v[32:47]
	global_load_lds_dwordx4 v194, s[18:19]
	s_add_u32 m0, s88, 16384
	v_mfma_f32_32x32x16_bf16 v[80:95], v[128:131], v[144:147], v[80:95]
	global_load_lds_dwordx4 v196, s[16:17]
	s_add_u32 m0, s88, 49152
	v_mfma_f32_32x32x16_bf16 v[16:31], v[132:135], v[144:147], v[16:31]
	global_load_lds_dwordx4 v196, s[18:19]
	s_add_u32 m0, s88, 24576
	v_mfma_f32_32x32x16_bf16 v[64:79], v[128:131], v[148:151], v[64:79]
	global_load_lds_dwordx4 v198, s[16:17]
	s_add_u32 m0, s88, 57344
	v_mfma_f32_32x32x16_bf16 v[0:15], v[132:135], v[148:151], v[0:15]
	global_load_lds_dwordx4 v198, s[18:19]
	s_branch .Lmq3k_join0

.Lmq3k_join0:
	ds_read_b128 v[128:131], v247
	ds_read_b128 v[136:139], v251
	ds_read_b128 v[132:135], v247 offset:4096
	ds_read_b128 v[140:143], v251 offset:4096
	ds_read_b128 v[144:147], v251 offset:8192
	ds_read_b128 v[148:151], v251 offset:12288
	s_waitcnt lgkmcnt(6)
	v_mfma_f32_32x32x16_bf16 v[112:127], v[160:163], v[168:171], v[112:127]
	v_mfma_f32_32x32x16_bf16 v[48:63], v[164:167], v[168:171], v[48:63]
	v_mfma_f32_32x32x16_bf16 v[96:111], v[160:163], v[172:175], v[96:111]
	v_mfma_f32_32x32x16_bf16 v[32:47], v[164:167], v[172:175], v[32:47]
	v_mfma_f32_32x32x16_bf16 v[80:95], v[160:163], v[176:179], v[80:95]
	v_mfma_f32_32x32x16_bf16 v[16:31], v[164:167], v[176:179], v[16:31]
	v_mfma_f32_32x32x16_bf16 v[64:79], v[160:163], v[180:183], v[64:79]
	v_mfma_f32_32x32x16_bf16 v[0:15], v[164:167], v[180:183], v[0:15]
	ds_read_b128 v[160:163], v248
	ds_read_b128 v[168:171], v252
	ds_read_b128 v[164:167], v248 offset:4096
	ds_read_b128 v[172:175], v252 offset:4096
	ds_read_b128 v[176:179], v252 offset:8192
	ds_read_b128 v[180:183], v252 offset:12288
	s_waitcnt lgkmcnt(6)
	v_mfma_f32_32x32x16_bf16 v[112:127], v[128:131], v[136:139], v[112:127]
	v_mfma_f32_32x32x16_bf16 v[48:63], v[132:135], v[136:139], v[48:63]
	v_mfma_f32_32x32x16_bf16 v[96:111], v[128:131], v[140:143], v[96:111]
	v_mfma_f32_32x32x16_bf16 v[32:47], v[132:135], v[140:143], v[32:47]
	v_mfma_f32_32x32x16_bf16 v[80:95], v[128:131], v[144:147], v[80:95]
	v_mfma_f32_32x32x16_bf16 v[16:31], v[132:135], v[144:147], v[16:31]
	v_mfma_f32_32x32x16_bf16 v[64:79], v[128:131], v[148:151], v[64:79]
	v_mfma_f32_32x32x16_bf16 v[0:15], v[132:135], v[148:151], v[0:15]
	ds_read_b128 v[128:131], v249
	ds_read_b128 v[136:139], v253
	ds_read_b128 v[132:135], v249 offset:4096
	ds_read_b128 v[140:143], v253 offset:4096
	ds_read_b128 v[144:147], v253 offset:8192
	ds_read_b128 v[148:151], v253 offset:12288
	s_waitcnt lgkmcnt(6)
	v_mfma_f32_32x32x16_bf16 v[112:127], v[160:163], v[168:171], v[112:127]
	v_mfma_f32_32x32x16_bf16 v[48:63], v[164:167], v[168:171], v[48:63]
	v_mfma_f32_32x32x16_bf16 v[96:111], v[160:163], v[172:175], v[96:111]
	v_mfma_f32_32x32x16_bf16 v[32:47], v[164:167], v[172:175], v[32:47]
	v_mfma_f32_32x32x16_bf16 v[80:95], v[160:163], v[176:179], v[80:95]
	v_mfma_f32_32x32x16_bf16 v[16:31], v[164:167], v[176:179], v[16:31]
	v_mfma_f32_32x32x16_bf16 v[64:79], v[160:163], v[180:183], v[64:79]
	v_mfma_f32_32x32x16_bf16 v[0:15], v[164:167], v[180:183], v[0:15]
	s_waitcnt vmcnt(0) lgkmcnt(0)
	s_barrier
	v_mfma_f32_32x32x16_bf16 v[112:127], v[128:131], v[136:139], v[112:127]
	v_mul_f32_e32 v213, 0x3c000000, v213
	v_mul_f32_e32 v214, 0x3c000000, v214
	v_mul_f32_e32 v215, 0x3c000000, v215
	v_mul_f32_e32 v216, 0x3c000000, v216
	v_add_f32_e32 v213, 0x358637bd, v213
	v_add_f32_e32 v214, 0x358637bd, v214
	v_add_f32_e32 v215, 0x358637bd, v215
	v_add_f32_e32 v216, 0x358637bd, v216
	v_rsq_f32_e32 v213, v213
	v_rsq_f32_e32 v214, v214
	v_rsq_f32_e32 v215, v215
	v_rsq_f32_e32 v216, v216
	v_mfma_f32_32x32x16_bf16 v[48:63], v[132:135], v[136:139], v[48:63]
	v_mul_f32_e32 v217, 0x3c000000, v217
	v_mul_f32_e32 v218, 0x3c000000, v218
	v_mul_f32_e32 v219, 0x3c000000, v219
	v_mul_f32_e32 v220, 0x3c000000, v220
	v_add_f32_e32 v217, 0x358637bd, v217
	v_add_f32_e32 v218, 0x358637bd, v218
	v_add_f32_e32 v219, 0x358637bd, v219
	v_add_f32_e32 v220, 0x358637bd, v220
	v_rsq_f32_e32 v217, v217
	v_rsq_f32_e32 v218, v218
	v_rsq_f32_e32 v219, v219
	v_rsq_f32_e32 v220, v220
	v_mfma_f32_32x32x16_bf16 v[96:111], v[128:131], v[140:143], v[96:111]
	v_mul_f32_e32 v221, 0x3c000000, v221
	v_mul_f32_e32 v222, 0x3c000000, v222
	v_mul_f32_e32 v223, 0x3c000000, v223
	v_mul_f32_e32 v224, 0x3c000000, v224
	v_add_f32_e32 v221, 0x358637bd, v221
	v_add_f32_e32 v222, 0x358637bd, v222
	v_add_f32_e32 v223, 0x358637bd, v223
	v_add_f32_e32 v224, 0x358637bd, v224
	v_rsq_f32_e32 v221, v221
	v_rsq_f32_e32 v222, v222
	v_rsq_f32_e32 v223, v223
	v_rsq_f32_e32 v224, v224
	v_mfma_f32_32x32x16_bf16 v[32:47], v[132:135], v[140:143], v[32:47]
	v_mul_f32_e32 v225, 0x3c000000, v225
	v_mul_f32_e32 v226, 0x3c000000, v226
	v_mul_f32_e32 v227, 0x3c000000, v227
	v_mul_f32_e32 v228, 0x3c000000, v228
	v_add_f32_e32 v225, 0x358637bd, v225
	v_add_f32_e32 v226, 0x358637bd, v226
	v_add_f32_e32 v227, 0x358637bd, v227
	v_add_f32_e32 v228, 0x358637bd, v228
	v_rsq_f32_e32 v225, v225
	v_rsq_f32_e32 v226, v226
	v_rsq_f32_e32 v227, v227
	v_rsq_f32_e32 v228, v228
	v_mfma_f32_32x32x16_bf16 v[80:95], v[128:131], v[144:147], v[80:95]
	v_mul_f32_e32 v229, 0x3c000000, v229
	v_mul_f32_e32 v230, 0x3c000000, v230
	v_mul_f32_e32 v231, 0x3c000000, v231
	v_mul_f32_e32 v232, 0x3c000000, v232
	v_add_f32_e32 v229, 0x358637bd, v229
	v_add_f32_e32 v230, 0x358637bd, v230
	v_add_f32_e32 v231, 0x358637bd, v231
	v_add_f32_e32 v232, 0x358637bd, v232
	v_rsq_f32_e32 v229, v229
	v_rsq_f32_e32 v230, v230
	v_rsq_f32_e32 v231, v231
	v_rsq_f32_e32 v232, v232
	v_mfma_f32_32x32x16_bf16 v[16:31], v[132:135], v[144:147], v[16:31]
	v_mul_f32_e32 v233, 0x3c000000, v233
	v_mul_f32_e32 v234, 0x3c000000, v234
	v_mul_f32_e32 v235, 0x3c000000, v235
	v_mul_f32_e32 v236, 0x3c000000, v236
	v_add_f32_e32 v233, 0x358637bd, v233
	v_add_f32_e32 v234, 0x358637bd, v234
	v_add_f32_e32 v235, 0x358637bd, v235
	v_add_f32_e32 v236, 0x358637bd, v236
	v_rsq_f32_e32 v233, v233
	v_rsq_f32_e32 v234, v234
	v_rsq_f32_e32 v235, v235
	v_rsq_f32_e32 v236, v236
	v_mfma_f32_32x32x16_bf16 v[64:79], v[128:131], v[148:151], v[64:79]
	v_mul_f32_e32 v237, 0x3c000000, v237
	v_mul_f32_e32 v238, 0x3c000000, v238
	v_mul_f32_e32 v239, 0x3c000000, v239
	v_mul_f32_e32 v240, 0x3c000000, v240
	v_add_f32_e32 v237, 0x358637bd, v237
	v_add_f32_e32 v238, 0x358637bd, v238
	v_add_f32_e32 v239, 0x358637bd, v239
	v_add_f32_e32 v240, 0x358637bd, v240
	v_rsq_f32_e32 v237, v237
	v_rsq_f32_e32 v238, v238
	v_rsq_f32_e32 v239, v239
	v_rsq_f32_e32 v240, v240
	v_mfma_f32_32x32x16_bf16 v[0:15], v[132:135], v[148:151], v[0:15]
	v_mul_f32_e32 v241, 0x3c000000, v241
	v_mul_f32_e32 v242, 0x3c000000, v242
	v_mul_f32_e32 v243, 0x3c000000, v243
	v_mul_f32_e32 v244, 0x3c000000, v244
	v_add_f32_e32 v241, 0x358637bd, v241
	v_add_f32_e32 v242, 0x358637bd, v242
	v_add_f32_e32 v243, 0x358637bd, v243
	v_add_f32_e32 v244, 0x358637bd, v244
	v_rsq_f32_e32 v241, v241
	v_rsq_f32_e32 v242, v242
	v_rsq_f32_e32 v243, v243
	v_rsq_f32_e32 v244, v244
	s_nop 7
	s_add_u32 s94, s92, 0
	s_add_u32 s95, s93, 0
	s_lshr_b32 s90, s95, 6
	s_lshr_b32 s96, s94, 12
	s_and_b32 s97, s94, 0xfff
	s_lshr_b32 s91, s90, 2
	s_and_b32 s98, s90, 3
	s_cmp_lt_u32 s98, 2
	s_cbranch_scc0 .Lmq3k_e00_v
	s_mul_i32 s89, s96, 0xc00000
	s_mul_i32 s91, s91, 0x180000
	s_add_u32 s89, s89, s91
	s_lshl_b32 s91, s98, 7
	s_add_u32 s89, s89, s91
	s_mul_i32 s91, s97, 0x180
	s_add_u32 s89, s89, s91
	s_movk_i32 s99, 0x180
	s_mov_b64 s[2:3], s[12:13]
	s_branch .Lmq3k_e00_plain

.Lgk1_loop:
	ds_read_b128 v[128:131], v231
	ds_read_b128 v[136:139], v235
	ds_read_b128 v[132:135], v231 offset:4096
	ds_read_b128 v[140:143], v235 offset:4096
	ds_read_b128 v[144:147], v235 offset:8192
	ds_read_b128 v[148:151], v235 offset:12288
	s_waitcnt lgkmcnt(6)
	v_mfma_f32_32x32x16_bf16 v[112:127], v[188:191], v[196:199], v[112:127]
	v_mfma_f32_32x32x16_bf16 v[48:63], v[192:195], v[196:199], v[48:63]
	v_mfma_f32_32x32x16_bf16 v[96:111], v[188:191], v[200:203], v[96:111]
	v_mfma_f32_32x32x16_bf16 v[32:47], v[192:195], v[200:203], v[32:47]
	v_mfma_f32_32x32x16_bf16 v[80:95], v[188:191], v[204:207], v[80:95]
	v_mfma_f32_32x32x16_bf16 v[16:31], v[192:195], v[204:207], v[16:31]
	v_mfma_f32_32x32x16_bf16 v[64:79], v[188:191], v[226:229], v[64:79]
	v_mfma_f32_32x32x16_bf16 v[0:15], v[192:195], v[226:229], v[0:15]
	ds_read_b128 v[188:191], v232
	ds_read_b128 v[196:199], v236
	ds_read_b128 v[192:195], v232 offset:4096
	ds_read_b128 v[200:203], v236 offset:4096
	ds_read_b128 v[204:207], v236 offset:8192
	ds_read_b128 v[226:229], v236 offset:12288
	s_waitcnt lgkmcnt(6)
	v_mfma_f32_32x32x16_bf16 v[112:127], v[128:131], v[136:139], v[112:127]
	v_mfma_f32_32x32x16_bf16 v[48:63], v[132:135], v[136:139], v[48:63]
	v_mfma_f32_32x32x16_bf16 v[96:111], v[128:131], v[140:143], v[96:111]
	v_mfma_f32_32x32x16_bf16 v[32:47], v[132:135], v[140:143], v[32:47]
	v_mfma_f32_32x32x16_bf16 v[80:95], v[128:131], v[144:147], v[80:95]
	v_mfma_f32_32x32x16_bf16 v[16:31], v[132:135], v[144:147], v[16:31]
	v_mfma_f32_32x32x16_bf16 v[64:79], v[128:131], v[148:151], v[64:79]
	v_mfma_f32_32x32x16_bf16 v[0:15], v[132:135], v[148:151], v[0:15]
	ds_read_b128 v[128:131], v233
	ds_read_b128 v[136:139], v237
	ds_read_b128 v[132:135], v233 offset:4096
	ds_read_b128 v[140:143], v237 offset:4096
	ds_read_b128 v[144:147], v237 offset:8192
	ds_read_b128 v[148:151], v237 offset:12288
	s_waitcnt lgkmcnt(6)
	v_mfma_f32_32x32x16_bf16 v[112:127], v[188:191], v[196:199], v[112:127]
	v_mfma_f32_32x32x16_bf16 v[48:63], v[192:195], v[196:199], v[48:63]
	v_mfma_f32_32x32x16_bf16 v[96:111], v[188:191], v[200:203], v[96:111]
	v_mfma_f32_32x32x16_bf16 v[32:47], v[192:195], v[200:203], v[32:47]
	v_mfma_f32_32x32x16_bf16 v[80:95], v[188:191], v[204:207], v[80:95]
	v_mfma_f32_32x32x16_bf16 v[16:31], v[192:195], v[204:207], v[16:31]
	v_mfma_f32_32x32x16_bf16 v[64:79], v[188:191], v[226:229], v[64:79]
	v_mfma_f32_32x32x16_bf16 v[0:15], v[192:195], v[226:229], v[0:15]
	s_waitcnt vmcnt(0) lgkmcnt(0)
	s_barrier
	v_xor_b32_e32 v230, 0x10000, v230
	v_xor_b32_e32 v234, 0x10000, v234
	ds_read_b128 v[188:191], v230
	ds_read_b128 v[196:199], v234
	ds_read_b128 v[192:195], v230 offset:4096
	ds_read_b128 v[200:203], v234 offset:4096
	ds_read_b128 v[204:207], v234 offset:8192
	ds_read_b128 v[226:229], v234 offset:12288
	s_cmpk_eq_i32 s2, 0x700
	s_cbranch_scc1 .Lgk1_nodma
	s_add_u32 s94, s2, s92
	s_add_u32 s94, s94, 0x100
	s_and_b32 s94, s94, 0x780
	s_sub_u32 s94, s94, 0x80
	s_subb_u32 s95, 0, 0
	s_add_u32 s100, s96, s94
	s_addc_u32 s101, s97, s95
	s_add_u32 s94, s98, s94
	s_addc_u32 s95, s99, s95
	s_add_u32 s90, s88, s89
	s_add_u32 m0, s90, 0
	v_mfma_f32_32x32x16_bf16 v[112:127], v[128:131], v[136:139], v[112:127]
	v_xor_b32_e32 v231, 0x10000, v231
	v_xor_b32_e32 v235, 0x10000, v235
	global_load_lds_dwordx4 v152, s[100:101]
	s_add_u32 m0, s90, 32768
	v_mfma_f32_32x32x16_bf16 v[48:63], v[132:135], v[136:139], v[48:63]
	v_xor_b32_e32 v232, 0x10000, v232
	v_xor_b32_e32 v236, 0x10000, v236
	global_load_lds_dwordx4 v153, s[94:95]
	s_add_u32 m0, s90, 8192
	v_mfma_f32_32x32x16_bf16 v[96:111], v[128:131], v[140:143], v[96:111]
	v_xor_b32_e32 v233, 0x10000, v233
	v_xor_b32_e32 v237, 0x10000, v237
	global_load_lds_dwordx4 v154, s[100:101]
	s_add_u32 m0, s90, 40960
	v_mfma_f32_32x32x16_bf16 v[32:47], v[132:135], v[140:143], v[32:47]
	global_load_lds_dwordx4 v155, s[94:95]
	s_add_u32 m0, s90, 16384
	v_mfma_f32_32x32x16_bf16 v[80:95], v[128:131], v[144:147], v[80:95]
	global_load_lds_dwordx4 v156, s[100:101]
	s_add_u32 m0, s90, 49152
	v_mfma_f32_32x32x16_bf16 v[16:31], v[132:135], v[144:147], v[16:31]
	global_load_lds_dwordx4 v157, s[94:95]
	s_add_u32 m0, s90, 24576
	v_mfma_f32_32x32x16_bf16 v[64:79], v[128:131], v[148:151], v[64:79]
	global_load_lds_dwordx4 v158, s[100:101]
	s_add_u32 m0, s90, 57344
	v_mfma_f32_32x32x16_bf16 v[0:15], v[132:135], v[148:151], v[0:15]
	global_load_lds_dwordx4 v168, s[94:95]
	s_branch .Lgk1_join

.Lgk2_loop:
	ds_read_b128 v[128:131], v233
	ds_read_b128 v[136:139], v237
	ds_read_b128 v[132:135], v233 offset:4096
	ds_read_b128 v[140:143], v237 offset:4096
	ds_read_b128 v[144:147], v237 offset:8192
	ds_read_b128 v[148:151], v237 offset:12288
	s_waitcnt lgkmcnt(6)
	v_mfma_f32_32x32x16_bf16 v[112:127], v[188:191], v[216:219], v[112:127]
	v_mfma_f32_32x32x16_bf16 v[48:63], v[212:215], v[216:219], v[48:63]
	v_mfma_f32_32x32x16_bf16 v[96:111], v[188:191], v[220:223], v[96:111]
	v_mfma_f32_32x32x16_bf16 v[32:47], v[212:215], v[220:223], v[32:47]
	v_mfma_f32_32x32x16_bf16 v[80:95], v[188:191], v[224:227], v[80:95]
	v_mfma_f32_32x32x16_bf16 v[16:31], v[212:215], v[224:227], v[16:31]
	v_mfma_f32_32x32x16_bf16 v[64:79], v[188:191], v[228:231], v[64:79]
	v_mfma_f32_32x32x16_bf16 v[0:15], v[212:215], v[228:231], v[0:15]
	ds_read_b128 v[188:191], v234
	ds_read_b128 v[216:219], v238
	ds_read_b128 v[212:215], v234 offset:4096
	ds_read_b128 v[220:223], v238 offset:4096
	ds_read_b128 v[224:227], v238 offset:8192
	ds_read_b128 v[228:231], v238 offset:12288
	s_waitcnt lgkmcnt(6)
	v_mfma_f32_32x32x16_bf16 v[112:127], v[128:131], v[136:139], v[112:127]
	v_mfma_f32_32x32x16_bf16 v[48:63], v[132:135], v[136:139], v[48:63]
	v_mfma_f32_32x32x16_bf16 v[96:111], v[128:131], v[140:143], v[96:111]
	v_mfma_f32_32x32x16_bf16 v[32:47], v[132:135], v[140:143], v[32:47]
	v_mfma_f32_32x32x16_bf16 v[80:95], v[128:131], v[144:147], v[80:95]
	v_mfma_f32_32x32x16_bf16 v[16:31], v[132:135], v[144:147], v[16:31]
	v_mfma_f32_32x32x16_bf16 v[64:79], v[128:131], v[148:151], v[64:79]
	v_mfma_f32_32x32x16_bf16 v[0:15], v[132:135], v[148:151], v[0:15]
	ds_read_b128 v[128:131], v235
	ds_read_b128 v[136:139], v239
	ds_read_b128 v[132:135], v235 offset:4096
	ds_read_b128 v[140:143], v239 offset:4096
	ds_read_b128 v[144:147], v239 offset:8192
	ds_read_b128 v[148:151], v239 offset:12288
	s_waitcnt lgkmcnt(6)
	v_mfma_f32_32x32x16_bf16 v[112:127], v[188:191], v[216:219], v[112:127]
	v_mfma_f32_32x32x16_bf16 v[48:63], v[212:215], v[216:219], v[48:63]
	v_mfma_f32_32x32x16_bf16 v[96:111], v[188:191], v[220:223], v[96:111]
	v_mfma_f32_32x32x16_bf16 v[32:47], v[212:215], v[220:223], v[32:47]
	v_mfma_f32_32x32x16_bf16 v[80:95], v[188:191], v[224:227], v[80:95]
	v_mfma_f32_32x32x16_bf16 v[16:31], v[212:215], v[224:227], v[16:31]
	v_mfma_f32_32x32x16_bf16 v[64:79], v[188:191], v[228:231], v[64:79]
	v_mfma_f32_32x32x16_bf16 v[0:15], v[212:215], v[228:231], v[0:15]
	s_waitcnt vmcnt(0) lgkmcnt(0)
	s_barrier
	v_xor_b32_e32 v232, 0x10000, v232
	v_xor_b32_e32 v236, 0x10000, v236
	ds_read_b128 v[188:191], v232
	ds_read_b128 v[216:219], v236
	ds_read_b128 v[212:215], v232 offset:4096
	ds_read_b128 v[220:223], v236 offset:4096
	ds_read_b128 v[224:227], v236 offset:8192
	ds_read_b128 v[228:231], v236 offset:12288
	s_cmpk_eq_i32 s2, 0x700
	s_cbranch_scc1 .Lgk2_nodma
	s_add_u32 s94, s2, s92
	s_add_u32 s94, s94, 0x100
	s_and_b32 s94, s94, 0x780
	s_sub_u32 s94, s94, 0x80
	s_subb_u32 s95, 0, 0
	s_add_u32 s100, s96, s94
	s_addc_u32 s101, s97, s95
	s_add_u32 s94, s98, s94
	s_addc_u32 s95, s99, s95
	s_add_u32 s90, s88, s89
	s_add_u32 m0, s90, 0
	v_mfma_f32_32x32x16_bf16 v[112:127], v[128:131], v[136:139], v[112:127]
	v_xor_b32_e32 v233, 0x10000, v233
	v_xor_b32_e32 v237, 0x10000, v237
	global_load_lds_dwordx4 v152, s[100:101]
	s_add_u32 m0, s90, 32768
	v_mfma_f32_32x32x16_bf16 v[48:63], v[132:135], v[136:139], v[48:63]
	v_xor_b32_e32 v234, 0x10000, v234
	v_xor_b32_e32 v238, 0x10000, v238
	global_load_lds_dwordx4 v153, s[94:95]
	s_add_u32 m0, s90, 8192
	v_mfma_f32_32x32x16_bf16 v[96:111], v[128:131], v[140:143], v[96:111]
	v_xor_b32_e32 v235, 0x10000, v235
	v_xor_b32_e32 v239, 0x10000, v239
	global_load_lds_dwordx4 v154, s[100:101]
	s_add_u32 m0, s90, 40960
	v_mfma_f32_32x32x16_bf16 v[32:47], v[132:135], v[140:143], v[32:47]
	global_load_lds_dwordx4 v155, s[94:95]
	s_add_u32 m0, s90, 16384
	v_mfma_f32_32x32x16_bf16 v[80:95], v[128:131], v[144:147], v[80:95]
	global_load_lds_dwordx4 v156, s[100:101]
	s_add_u32 m0, s90, 49152
	v_mfma_f32_32x32x16_bf16 v[16:31], v[132:135], v[144:147], v[16:31]
	global_load_lds_dwordx4 v157, s[94:95]
	s_add_u32 m0, s90, 24576
	v_mfma_f32_32x32x16_bf16 v[64:79], v[128:131], v[148:151], v[64:79]
	global_load_lds_dwordx4 v158, s[100:101]
	s_add_u32 m0, s90, 57344
	v_mfma_f32_32x32x16_bf16 v[0:15], v[132:135], v[148:151], v[0:15]
	global_load_lds_dwordx4 v160, s[94:95]
	s_branch .Lgk2_join

.Lip11_vb:
	s_load_dwordx2 s[4:5], s[0:1], 0x158
	s_load_dwordx2 s[6:7], s[0:1], 0x110
	v_mbcnt_hi_u32_b32 v234, -1, v210
	s_lshr_b32 s29, s70, 6
	s_lshl_b32 s27, s70, 4
	s_and_b32 s90, s70, 0x40
	v_and_b32_e32 v200, 48, v234
	v_or_b32_e32 v200, s90, v200
	v_and_b32_e32 v235, 31, v234
	v_lshrrev_b32_e32 v236, 5, v234
	v_bfe_u32 v237, v234, 1, 3
	v_lshlrev_b32_e32 v238, 7, v235
	s_lshr_b32 s91, s70, 7
	s_lshl_b32 s91, s91, 13
	s_and_b32 s31, s29, 1
	s_lshl_b32 s90, s90, 8
	s_add_u32 s90, s90, 0x8000
	v_xor_b32_e32 v239, v236, v237
	v_lshl_add_u32 v239, v239, 4, v238
	v_add_u32_e32 v184, s91, v239
	v_add_u32_e32 v188, s90, v239
	v_add_u32_e32 v240, 0x10000, v184
	v_add_u32_e32 v244, 0x10000, v188
	v_or_b32_e32 v239, 2, v236
	v_xor_b32_e32 v239, v239, v237
	v_lshl_add_u32 v239, v239, 4, v238
	v_add_u32_e32 v185, s91, v239
	v_add_u32_e32 v189, s90, v239
	v_add_u32_e32 v241, 0x10000, v185
	v_add_u32_e32 v245, 0x10000, v189
	v_or_b32_e32 v239, 4, v236
	v_xor_b32_e32 v239, v239, v237
	v_lshl_add_u32 v239, v239, 4, v238
	v_add_u32_e32 v186, s91, v239
	v_add_u32_e32 v190, s90, v239
	v_add_u32_e32 v242, 0x10000, v186
	v_add_u32_e32 v246, 0x10000, v190
	v_or_b32_e32 v239, 6, v236
	v_xor_b32_e32 v239, v239, v237
	v_lshl_add_u32 v239, v239, 4, v238
	v_add_u32_e32 v187, s91, v239
	v_add_u32_e32 v191, s90, v239
	v_add_u32_e32 v243, 0x10000, v187
	v_add_u32_e32 v247, 0x10000, v191
	v_lshrrev_b32_e32 v238, 3, v234
	s_lshl_b32 s96, s29, 3
	v_add_u32_e32 v238, s96, v238
	v_and_b32_e32 v239, 7, v234
	v_lshlrev_b32_e32 v239, 4, v239
	v_xor_b32_e32 v239, v200, v239
	v_lshl_add_u32 v192, v238, 11, v239
	v_mov_b32_e32 v193, 0
	v_add_u32_e32 v237, 64, v238
	v_lshl_add_u32 v194, v237, 11, v239
	v_mov_b32_e32 v195, 0
	v_add_u32_e32 v237, 128, v238
	v_lshl_add_u32 v196, v237, 11, v239
	v_mov_b32_e32 v197, 0
	v_add_u32_e32 v237, 192, v238
	v_lshl_add_u32 v198, v237, 11, v239
	v_mov_b32_e32 v199, 0
	s_mov_b32 s30, s28
	s_cmpk_ge_u32 s30, 0x780
	s_cbranch_scc1 .Lip11_done
	s_waitcnt lgkmcnt(0)
	s_mul_hi_u32 s35, s30, 0x92492493
	s_lshr_b32 s35, s35, 3
	s_mul_i32 s36, s35, 14
	s_sub_u32 s36, s30, s36
	s_sub_u32 s98, s30, 0x700
	s_cmpk_lt_u32 s30, 0x700
	s_cselect_b32 s36, s36, 14
	s_cselect_b32 s35, s35, s98
	s_lshl_b32 s98, s35, 19
	s_add_u32 s16, s4, s98
	s_addc_u32 s17, s5, 0
	s_lshl_b32 s98, s36, 19
	s_add_u32 s18, s6, s98
	s_addc_u32 s19, s7, 0
	s_add_u32 m0, s27, 0
	s_nop 0
	global_load_lds_dwordx4 v192, s[16:17]
	s_add_u32 m0, s27, 32768
	s_nop 0
	global_load_lds_dwordx4 v192, s[18:19]
	s_add_u32 m0, s27, 8192
	s_nop 0
	global_load_lds_dwordx4 v194, s[16:17]
	s_add_u32 m0, s27, 40960
	s_nop 0
	global_load_lds_dwordx4 v194, s[18:19]
	s_add_u32 m0, s27, 16384
	s_nop 0
	global_load_lds_dwordx4 v196, s[16:17]
	s_add_u32 m0, s27, 49152
	s_nop 0
	global_load_lds_dwordx4 v196, s[18:19]
	s_add_u32 m0, s27, 24576
	s_nop 0
	global_load_lds_dwordx4 v198, s[16:17]
	s_add_u32 m0, s27, 57344
	s_nop 0
	global_load_lds_dwordx4 v198, s[18:19]
.Lip11_tile:
	s_mul_hi_u32 s35, s30, 0x92492493
	s_lshr_b32 s35, s35, 3
	s_mul_i32 s36, s35, 14
	s_sub_u32 s36, s30, s36
	s_sub_u32 s98, s30, 0x700
	s_cmpk_lt_u32 s30, 0x700
	s_cselect_b32 s36, s36, 14
	s_cselect_b32 s35, s35, s98
	s_waitcnt vmcnt(0)
	s_barrier
	s_add_u32 s20, s16, 128
	s_addc_u32 s21, s17, 0
	s_add_u32 s24, s18, 128
	s_addc_u32 s25, s19, 0
	s_add_u32 m0, s27, 65536
	s_nop 0
	global_load_lds_dwordx4 v192, s[20:21]
	s_add_u32 m0, s27, 98304
	s_nop 0
	global_load_lds_dwordx4 v192, s[24:25]
	s_add_u32 m0, s27, 73728
	s_nop 0
	global_load_lds_dwordx4 v194, s[20:21]
	s_add_u32 m0, s27, 106496
	s_nop 0
	global_load_lds_dwordx4 v194, s[24:25]
	s_add_u32 m0, s27, 81920
	s_nop 0
	global_load_lds_dwordx4 v196, s[20:21]
	s_add_u32 m0, s27, 114688
	s_nop 0
	global_load_lds_dwordx4 v196, s[24:25]
	s_add_u32 m0, s27, 90112
	s_nop 0
	global_load_lds_dwordx4 v198, s[20:21]
	s_add_u32 m0, s27, 122880
	s_nop 0
	global_load_lds_dwordx4 v198, s[24:25]
	s_cmp_eq_u32 s36, 14
	s_cbranch_scc1 .Lip11_light
	ds_read_b128 v[160:163], v184
	ds_read_b128 v[168:171], v188
	ds_read_b128 v[164:167], v184 offset:4096
	ds_read_b128 v[172:175], v188 offset:4096
	ds_read_b128 v[176:179], v188 offset:8192
	ds_read_b128 v[180:183], v188 offset:12288
	ds_read_b128 v[128:131], v185
	ds_read_b128 v[136:139], v189
	ds_read_b128 v[132:135], v185 offset:4096
	ds_read_b128 v[140:143], v189 offset:4096
	ds_read_b128 v[144:147], v189 offset:8192
	ds_read_b128 v[148:151], v189 offset:12288
	s_waitcnt lgkmcnt(6)
	v_mfma_f32_32x32x16_bf16 v[112:127], v[160:163], v[168:171], 0
	v_mfma_f32_32x32x16_bf16 v[48:63], v[164:167], v[168:171], 0
	v_mfma_f32_32x32x16_bf16 v[96:111], v[160:163], v[172:175], 0
	v_mfma_f32_32x32x16_bf16 v[32:47], v[164:167], v[172:175], 0
	v_mfma_f32_32x32x16_bf16 v[80:95], v[160:163], v[176:179], 0
	v_mfma_f32_32x32x16_bf16 v[16:31], v[164:167], v[176:179], 0
	v_mfma_f32_32x32x16_bf16 v[64:79], v[160:163], v[180:183], 0
	v_mfma_f32_32x32x16_bf16 v[0:15], v[164:167], v[180:183], 0
	ds_read_b128 v[160:163], v186
	ds_read_b128 v[168:171], v190
	ds_read_b128 v[164:167], v186 offset:4096
	ds_read_b128 v[172:175], v190 offset:4096
	ds_read_b128 v[176:179], v190 offset:8192
	ds_read_b128 v[180:183], v190 offset:12288
	s_waitcnt lgkmcnt(6)
	v_mfma_f32_32x32x16_bf16 v[112:127], v[128:131], v[136:139], v[112:127]
	v_mfma_f32_32x32x16_bf16 v[48:63], v[132:135], v[136:139], v[48:63]
	v_mfma_f32_32x32x16_bf16 v[96:111], v[128:131], v[140:143], v[96:111]
	v_mfma_f32_32x32x16_bf16 v[32:47], v[132:135], v[140:143], v[32:47]
	v_mfma_f32_32x32x16_bf16 v[80:95], v[128:131], v[144:147], v[80:95]
	v_mfma_f32_32x32x16_bf16 v[16:31], v[132:135], v[144:147], v[16:31]
	v_mfma_f32_32x32x16_bf16 v[64:79], v[128:131], v[148:151], v[64:79]
	v_mfma_f32_32x32x16_bf16 v[0:15], v[132:135], v[148:151], v[0:15]
	ds_read_b128 v[128:131], v187
	ds_read_b128 v[136:139], v191
	ds_read_b128 v[132:135], v187 offset:4096
	ds_read_b128 v[140:143], v191 offset:4096
	ds_read_b128 v[144:147], v191 offset:8192
	ds_read_b128 v[148:151], v191 offset:12288
	s_waitcnt lgkmcnt(6)
	v_mfma_f32_32x32x16_bf16 v[112:127], v[160:163], v[168:171], v[112:127]
	v_mfma_f32_32x32x16_bf16 v[48:63], v[164:167], v[168:171], v[48:63]
	v_mfma_f32_32x32x16_bf16 v[96:111], v[160:163], v[172:175], v[96:111]
	v_mfma_f32_32x32x16_bf16 v[32:47], v[164:167], v[172:175], v[32:47]
	v_mfma_f32_32x32x16_bf16 v[80:95], v[160:163], v[176:179], v[80:95]
	v_mfma_f32_32x32x16_bf16 v[16:31], v[164:167], v[176:179], v[16:31]
	v_mfma_f32_32x32x16_bf16 v[64:79], v[160:163], v[180:183], v[64:79]
	v_mfma_f32_32x32x16_bf16 v[0:15], v[164:167], v[180:183], v[0:15]
	s_waitcnt vmcnt(0) lgkmcnt(0)
	s_barrier
	ds_read_b128 v[160:163], v240
	ds_read_b128 v[168:171], v244
	ds_read_b128 v[164:167], v240 offset:4096
	ds_read_b128 v[172:175], v244 offset:4096
	ds_read_b128 v[176:179], v244 offset:8192
	ds_read_b128 v[180:183], v244 offset:12288
	s_add_u32 s20, s16, 256
	s_addc_u32 s21, s17, 0
	s_add_u32 s24, s18, 256
	s_addc_u32 s25, s19, 0
	s_add_u32 m0, s27, 0
	v_mfma_f32_32x32x16_bf16 v[112:127], v[128:131], v[136:139], v[112:127]
	global_load_lds_dwordx4 v192, s[20:21]
	s_add_u32 m0, s27, 32768
	v_mfma_f32_32x32x16_bf16 v[48:63], v[132:135], v[136:139], v[48:63]
	global_load_lds_dwordx4 v192, s[24:25]
	s_add_u32 m0, s27, 8192
	v_mfma_f32_32x32x16_bf16 v[96:111], v[128:131], v[140:143], v[96:111]
	global_load_lds_dwordx4 v194, s[20:21]
	s_add_u32 m0, s27, 40960
	v_mfma_f32_32x32x16_bf16 v[32:47], v[132:135], v[140:143], v[32:47]
	global_load_lds_dwordx4 v194, s[24:25]
	s_add_u32 m0, s27, 16384
	v_mfma_f32_32x32x16_bf16 v[80:95], v[128:131], v[144:147], v[80:95]
	global_load_lds_dwordx4 v196, s[20:21]
	s_add_u32 m0, s27, 49152
	v_mfma_f32_32x32x16_bf16 v[16:31], v[132:135], v[144:147], v[16:31]
	global_load_lds_dwordx4 v196, s[24:25]
	s_add_u32 m0, s27, 24576
	v_mfma_f32_32x32x16_bf16 v[64:79], v[128:131], v[148:151], v[64:79]
	global_load_lds_dwordx4 v198, s[20:21]
	s_add_u32 m0, s27, 57344
	v_mfma_f32_32x32x16_bf16 v[0:15], v[132:135], v[148:151], v[0:15]
	global_load_lds_dwordx4 v198, s[24:25]
	ds_read_b128 v[128:131], v241
	ds_read_b128 v[136:139], v245
	ds_read_b128 v[132:135], v241 offset:4096
	ds_read_b128 v[140:143], v245 offset:4096
	ds_read_b128 v[144:147], v245 offset:8192
	ds_read_b128 v[148:151], v245 offset:12288
	s_waitcnt lgkmcnt(6)
	v_mfma_f32_32x32x16_bf16 v[112:127], v[160:163], v[168:171], v[112:127]
	v_mfma_f32_32x32x16_bf16 v[48:63], v[164:167], v[168:171], v[48:63]
	v_mfma_f32_32x32x16_bf16 v[96:111], v[160:163], v[172:175], v[96:111]
	v_mfma_f32_32x32x16_bf16 v[32:47], v[164:167], v[172:175], v[32:47]
	v_mfma_f32_32x32x16_bf16 v[80:95], v[160:163], v[176:179], v[80:95]
	v_mfma_f32_32x32x16_bf16 v[16:31], v[164:167], v[176:179], v[16:31]
	v_mfma_f32_32x32x16_bf16 v[64:79], v[160:163], v[180:183], v[64:79]
	v_mfma_f32_32x32x16_bf16 v[0:15], v[164:167], v[180:183], v[0:15]
	ds_read_b128 v[160:163], v242
	ds_read_b128 v[168:171], v246
	ds_read_b128 v[164:167], v242 offset:4096
	ds_read_b128 v[172:175], v246 offset:4096
	ds_read_b128 v[176:179], v246 offset:8192
	ds_read_b128 v[180:183], v246 offset:12288
	s_waitcnt lgkmcnt(6)
	v_mfma_f32_32x32x16_bf16 v[112:127], v[128:131], v[136:139], v[112:127]
	v_mfma_f32_32x32x16_bf16 v[48:63], v[132:135], v[136:139], v[48:63]
	v_mfma_f32_32x32x16_bf16 v[96:111], v[128:131], v[140:143], v[96:111]
	v_mfma_f32_32x32x16_bf16 v[32:47], v[132:135], v[140:143], v[32:47]
	v_mfma_f32_32x32x16_bf16 v[80:95], v[128:131], v[144:147], v[80:95]
	v_mfma_f32_32x32x16_bf16 v[16:31], v[132:135], v[144:147], v[16:31]
	v_mfma_f32_32x32x16_bf16 v[64:79], v[128:131], v[148:151], v[64:79]
	v_mfma_f32_32x32x16_bf16 v[0:15], v[132:135], v[148:151], v[0:15]
	ds_read_b128 v[128:131], v243
	ds_read_b128 v[136:139], v247
	ds_read_b128 v[132:135], v243 offset:4096
	ds_read_b128 v[140:143], v247 offset:4096
	ds_read_b128 v[144:147], v247 offset:8192
	ds_read_b128 v[148:151], v247 offset:12288
	s_waitcnt lgkmcnt(6)
	v_mfma_f32_32x32x16_bf16 v[112:127], v[160:163], v[168:171], v[112:127]
	v_mfma_f32_32x32x16_bf16 v[48:63], v[164:167], v[168:171], v[48:63]
	v_mfma_f32_32x32x16_bf16 v[96:111], v[160:163], v[172:175], v[96:111]
	v_mfma_f32_32x32x16_bf16 v[32:47], v[164:167], v[172:175], v[32:47]
	v_mfma_f32_32x32x16_bf16 v[80:95], v[160:163], v[176:179], v[80:95]
	v_mfma_f32_32x32x16_bf16 v[16:31], v[164:167], v[176:179], v[16:31]
	v_mfma_f32_32x32x16_bf16 v[64:79], v[160:163], v[180:183], v[64:79]
	v_mfma_f32_32x32x16_bf16 v[0:15], v[164:167], v[180:183], v[0:15]
	s_waitcnt vmcnt(0) lgkmcnt(0)
	s_barrier
	ds_read_b128 v[160:163], v184
	ds_read_b128 v[168:171], v188
	ds_read_b128 v[164:167], v184 offset:4096
	ds_read_b128 v[172:175], v188 offset:4096
	ds_read_b128 v[176:179], v188 offset:8192
	ds_read_b128 v[180:183], v188 offset:12288
	s_add_u32 s20, s16, 384
	s_addc_u32 s21, s17, 0
	s_add_u32 s24, s18, 384
	s_addc_u32 s25, s19, 0
	s_add_u32 m0, s27, 65536
	v_mfma_f32_32x32x16_bf16 v[112:127], v[128:131], v[136:139], v[112:127]
	global_load_lds_dwordx4 v192, s[20:21]
	s_add_u32 m0, s27, 98304
	v_mfma_f32_32x32x16_bf16 v[48:63], v[132:135], v[136:139], v[48:63]
	global_load_lds_dwordx4 v192, s[24:25]
	s_add_u32 m0, s27, 73728
	v_mfma_f32_32x32x16_bf16 v[96:111], v[128:131], v[140:143], v[96:111]
	global_load_lds_dwordx4 v194, s[20:21]
	s_add_u32 m0, s27, 106496
	v_mfma_f32_32x32x16_bf16 v[32:47], v[132:135], v[140:143], v[32:47]
	global_load_lds_dwordx4 v194, s[24:25]
	s_add_u32 m0, s27, 81920
	v_mfma_f32_32x32x16_bf16 v[80:95], v[128:131], v[144:147], v[80:95]
	global_load_lds_dwordx4 v196, s[20:21]
	s_add_u32 m0, s27, 114688
	v_mfma_f32_32x32x16_bf16 v[16:31], v[132:135], v[144:147], v[16:31]
	global_load_lds_dwordx4 v196, s[24:25]
	s_add_u32 m0, s27, 90112
	v_mfma_f32_32x32x16_bf16 v[64:79], v[128:131], v[148:151], v[64:79]
	global_load_lds_dwordx4 v198, s[20:21]
	s_add_u32 m0, s27, 122880
	v_mfma_f32_32x32x16_bf16 v[0:15], v[132:135], v[148:151], v[0:15]
	global_load_lds_dwordx4 v198, s[24:25]
	ds_read_b128 v[128:131], v185
	ds_read_b128 v[136:139], v189
	ds_read_b128 v[132:135], v185 offset:4096
	ds_read_b128 v[140:143], v189 offset:4096
	ds_read_b128 v[144:147], v189 offset:8192
	ds_read_b128 v[148:151], v189 offset:12288
	s_waitcnt lgkmcnt(6)
	v_mfma_f32_32x32x16_bf16 v[112:127], v[160:163], v[168:171], v[112:127]
	v_mfma_f32_32x32x16_bf16 v[48:63], v[164:167], v[168:171], v[48:63]
	v_mfma_f32_32x32x16_bf16 v[96:111], v[160:163], v[172:175], v[96:111]
	v_mfma_f32_32x32x16_bf16 v[32:47], v[164:167], v[172:175], v[32:47]
	v_mfma_f32_32x32x16_bf16 v[80:95], v[160:163], v[176:179], v[80:95]
	v_mfma_f32_32x32x16_bf16 v[16:31], v[164:167], v[176:179], v[16:31]
	v_mfma_f32_32x32x16_bf16 v[64:79], v[160:163], v[180:183], v[64:79]
	v_mfma_f32_32x32x16_bf16 v[0:15], v[164:167], v[180:183], v[0:15]
	ds_read_b128 v[160:163], v186
	ds_read_b128 v[168:171], v190
	ds_read_b128 v[164:167], v186 offset:4096
	ds_read_b128 v[172:175], v190 offset:4096
	ds_read_b128 v[176:179], v190 offset:8192
	ds_read_b128 v[180:183], v190 offset:12288
	s_waitcnt lgkmcnt(6)
	v_mfma_f32_32x32x16_bf16 v[112:127], v[128:131], v[136:139], v[112:127]
	v_mfma_f32_32x32x16_bf16 v[48:63], v[132:135], v[136:139], v[48:63]
	v_mfma_f32_32x32x16_bf16 v[96:111], v[128:131], v[140:143], v[96:111]
	v_mfma_f32_32x32x16_bf16 v[32:47], v[132:135], v[140:143], v[32:47]
	v_mfma_f32_32x32x16_bf16 v[80:95], v[128:131], v[144:147], v[80:95]
	v_mfma_f32_32x32x16_bf16 v[16:31], v[132:135], v[144:147], v[16:31]
	v_mfma_f32_32x32x16_bf16 v[64:79], v[128:131], v[148:151], v[64:79]
	v_mfma_f32_32x32x16_bf16 v[0:15], v[132:135], v[148:151], v[0:15]
	ds_read_b128 v[128:131], v187
	ds_read_b128 v[136:139], v191
	ds_read_b128 v[132:135], v187 offset:4096
	ds_read_b128 v[140:143], v191 offset:4096
	ds_read_b128 v[144:147], v191 offset:8192
	ds_read_b128 v[148:151], v191 offset:12288
	s_waitcnt lgkmcnt(6)
	v_mfma_f32_32x32x16_bf16 v[112:127], v[160:163], v[168:171], v[112:127]
	v_mfma_f32_32x32x16_bf16 v[48:63], v[164:167], v[168:171], v[48:63]
	v_mfma_f32_32x32x16_bf16 v[96:111], v[160:163], v[172:175], v[96:111]
	v_mfma_f32_32x32x16_bf16 v[32:47], v[164:167], v[172:175], v[32:47]
	v_mfma_f32_32x32x16_bf16 v[80:95], v[160:163], v[176:179], v[80:95]
	v_mfma_f32_32x32x16_bf16 v[16:31], v[164:167], v[176:179], v[16:31]
	v_mfma_f32_32x32x16_bf16 v[64:79], v[160:163], v[180:183], v[64:79]
	v_mfma_f32_32x32x16_bf16 v[0:15], v[164:167], v[180:183], v[0:15]
	s_waitcnt vmcnt(0) lgkmcnt(0)
	s_barrier
	ds_read_b128 v[160:163], v240
	ds_read_b128 v[168:171], v244
	ds_read_b128 v[164:167], v240 offset:4096
	ds_read_b128 v[172:175], v244 offset:4096
	ds_read_b128 v[176:179], v244 offset:8192
	ds_read_b128 v[180:183], v244 offset:12288
	s_add_u32 s20, s16, 512
	s_addc_u32 s21, s17, 0
	s_add_u32 s24, s18, 512
	s_addc_u32 s25, s19, 0
	s_add_u32 m0, s27, 0
	v_mfma_f32_32x32x16_bf16 v[112:127], v[128:131], v[136:139], v[112:127]
	global_load_lds_dwordx4 v192, s[20:21]
	s_add_u32 m0, s27, 32768
	v_mfma_f32_32x32x16_bf16 v[48:63], v[132:135], v[136:139], v[48:63]
	global_load_lds_dwordx4 v192, s[24:25]
	s_add_u32 m0, s27, 8192
	v_mfma_f32_32x32x16_bf16 v[96:111], v[128:131], v[140:143], v[96:111]
	global_load_lds_dwordx4 v194, s[20:21]
	s_add_u32 m0, s27, 40960
	v_mfma_f32_32x32x16_bf16 v[32:47], v[132:135], v[140:143], v[32:47]
	global_load_lds_dwordx4 v194, s[24:25]
	s_add_u32 m0, s27, 16384
	v_mfma_f32_32x32x16_bf16 v[80:95], v[128:131], v[144:147], v[80:95]
	global_load_lds_dwordx4 v196, s[20:21]
	s_add_u32 m0, s27, 49152
	v_mfma_f32_32x32x16_bf16 v[16:31], v[132:135], v[144:147], v[16:31]
	global_load_lds_dwordx4 v196, s[24:25]
	s_add_u32 m0, s27, 24576
	v_mfma_f32_32x32x16_bf16 v[64:79], v[128:131], v[148:151], v[64:79]
	global_load_lds_dwordx4 v198, s[20:21]
	s_add_u32 m0, s27, 57344
	v_mfma_f32_32x32x16_bf16 v[0:15], v[132:135], v[148:151], v[0:15]
	global_load_lds_dwordx4 v198, s[24:25]
	ds_read_b128 v[128:131], v241
	ds_read_b128 v[136:139], v245
	ds_read_b128 v[132:135], v241 offset:4096
	ds_read_b128 v[140:143], v245 offset:4096
	ds_read_b128 v[144:147], v245 offset:8192
	ds_read_b128 v[148:151], v245 offset:12288
	s_waitcnt lgkmcnt(6)
	v_mfma_f32_32x32x16_bf16 v[112:127], v[160:163], v[168:171], v[112:127]
	v_mfma_f32_32x32x16_bf16 v[48:63], v[164:167], v[168:171], v[48:63]
	v_mfma_f32_32x32x16_bf16 v[96:111], v[160:163], v[172:175], v[96:111]
	v_mfma_f32_32x32x16_bf16 v[32:47], v[164:167], v[172:175], v[32:47]
	v_mfma_f32_32x32x16_bf16 v[80:95], v[160:163], v[176:179], v[80:95]
	v_mfma_f32_32x32x16_bf16 v[16:31], v[164:167], v[176:179], v[16:31]
	v_mfma_f32_32x32x16_bf16 v[64:79], v[160:163], v[180:183], v[64:79]
	v_mfma_f32_32x32x16_bf16 v[0:15], v[164:167], v[180:183], v[0:15]
	ds_read_b128 v[160:163], v242
	ds_read_b128 v[168:171], v246
	ds_read_b128 v[164:167], v242 offset:4096
	ds_read_b128 v[172:175], v246 offset:4096
	ds_read_b128 v[176:179], v246 offset:8192
	ds_read_b128 v[180:183], v246 offset:12288
	s_waitcnt lgkmcnt(6)
	v_mfma_f32_32x32x16_bf16 v[112:127], v[128:131], v[136:139], v[112:127]
	v_mfma_f32_32x32x16_bf16 v[48:63], v[132:135], v[136:139], v[48:63]
	v_mfma_f32_32x32x16_bf16 v[96:111], v[128:131], v[140:143], v[96:111]
	v_mfma_f32_32x32x16_bf16 v[32:47], v[132:135], v[140:143], v[32:47]
	v_mfma_f32_32x32x16_bf16 v[80:95], v[128:131], v[144:147], v[80:95]
	v_mfma_f32_32x32x16_bf16 v[16:31], v[132:135], v[144:147], v[16:31]
	v_mfma_f32_32x32x16_bf16 v[64:79], v[128:131], v[148:151], v[64:79]
	v_mfma_f32_32x32x16_bf16 v[0:15], v[132:135], v[148:151], v[0:15]
	ds_read_b128 v[128:131], v243
	ds_read_b128 v[136:139], v247
	ds_read_b128 v[132:135], v243 offset:4096
	ds_read_b128 v[140:143], v247 offset:4096
	ds_read_b128 v[144:147], v247 offset:8192
	ds_read_b128 v[148:151], v247 offset:12288
	s_waitcnt lgkmcnt(6)
	v_mfma_f32_32x32x16_bf16 v[112:127], v[160:163], v[168:171], v[112:127]
	v_mfma_f32_32x32x16_bf16 v[48:63], v[164:167], v[168:171], v[48:63]
	v_mfma_f32_32x32x16_bf16 v[96:111], v[160:163], v[172:175], v[96:111]
	v_mfma_f32_32x32x16_bf16 v[32:47], v[164:167], v[172:175], v[32:47]
	v_mfma_f32_32x32x16_bf16 v[80:95], v[160:163], v[176:179], v[80:95]
	v_mfma_f32_32x32x16_bf16 v[16:31], v[164:167], v[176:179], v[16:31]
	v_mfma_f32_32x32x16_bf16 v[64:79], v[160:163], v[180:183], v[64:79]
	v_mfma_f32_32x32x16_bf16 v[0:15], v[164:167], v[180:183], v[0:15]
	s_waitcnt vmcnt(0) lgkmcnt(0)
	s_barrier
	ds_read_b128 v[160:163], v184
	ds_read_b128 v[168:171], v188
	ds_read_b128 v[164:167], v184 offset:4096
	ds_read_b128 v[172:175], v188 offset:4096
	ds_read_b128 v[176:179], v188 offset:8192
	ds_read_b128 v[180:183], v188 offset:12288
	s_add_u32 s20, s16, 640
	s_addc_u32 s21, s17, 0
	s_add_u32 s24, s18, 640
	s_addc_u32 s25, s19, 0
	s_add_u32 m0, s27, 65536
	v_mfma_f32_32x32x16_bf16 v[112:127], v[128:131], v[136:139], v[112:127]
	global_load_lds_dwordx4 v192, s[20:21]
	s_add_u32 m0, s27, 98304
	v_mfma_f32_32x32x16_bf16 v[48:63], v[132:135], v[136:139], v[48:63]
	global_load_lds_dwordx4 v192, s[24:25]
	s_add_u32 m0, s27, 73728
	v_mfma_f32_32x32x16_bf16 v[96:111], v[128:131], v[140:143], v[96:111]
	global_load_lds_dwordx4 v194, s[20:21]
	s_add_u32 m0, s27, 106496
	v_mfma_f32_32x32x16_bf16 v[32:47], v[132:135], v[140:143], v[32:47]
	global_load_lds_dwordx4 v194, s[24:25]
	s_add_u32 m0, s27, 81920
	v_mfma_f32_32x32x16_bf16 v[80:95], v[128:131], v[144:147], v[80:95]
	global_load_lds_dwordx4 v196, s[20:21]
	s_add_u32 m0, s27, 114688
	v_mfma_f32_32x32x16_bf16 v[16:31], v[132:135], v[144:147], v[16:31]
	global_load_lds_dwordx4 v196, s[24:25]
	s_add_u32 m0, s27, 90112
	v_mfma_f32_32x32x16_bf16 v[64:79], v[128:131], v[148:151], v[64:79]
	global_load_lds_dwordx4 v198, s[20:21]
	s_add_u32 m0, s27, 122880
	v_mfma_f32_32x32x16_bf16 v[0:15], v[132:135], v[148:151], v[0:15]
	global_load_lds_dwordx4 v198, s[24:25]
	ds_read_b128 v[128:131], v185
	ds_read_b128 v[136:139], v189
	ds_read_b128 v[132:135], v185 offset:4096
	ds_read_b128 v[140:143], v189 offset:4096
	ds_read_b128 v[144:147], v189 offset:8192
	ds_read_b128 v[148:151], v189 offset:12288
	s_waitcnt lgkmcnt(6)
	v_mfma_f32_32x32x16_bf16 v[112:127], v[160:163], v[168:171], v[112:127]
	v_mfma_f32_32x32x16_bf16 v[48:63], v[164:167], v[168:171], v[48:63]
	v_mfma_f32_32x32x16_bf16 v[96:111], v[160:163], v[172:175], v[96:111]
	v_mfma_f32_32x32x16_bf16 v[32:47], v[164:167], v[172:175], v[32:47]
	v_mfma_f32_32x32x16_bf16 v[80:95], v[160:163], v[176:179], v[80:95]
	v_mfma_f32_32x32x16_bf16 v[16:31], v[164:167], v[176:179], v[16:31]
	v_mfma_f32_32x32x16_bf16 v[64:79], v[160:163], v[180:183], v[64:79]
	v_mfma_f32_32x32x16_bf16 v[0:15], v[164:167], v[180:183], v[0:15]
	ds_read_b128 v[160:163], v186
	ds_read_b128 v[168:171], v190
	ds_read_b128 v[164:167], v186 offset:4096
	ds_read_b128 v[172:175], v190 offset:4096
	ds_read_b128 v[176:179], v190 offset:8192
	ds_read_b128 v[180:183], v190 offset:12288
	s_waitcnt lgkmcnt(6)
	v_mfma_f32_32x32x16_bf16 v[112:127], v[128:131], v[136:139], v[112:127]
	v_mfma_f32_32x32x16_bf16 v[48:63], v[132:135], v[136:139], v[48:63]
	v_mfma_f32_32x32x16_bf16 v[96:111], v[128:131], v[140:143], v[96:111]
	v_mfma_f32_32x32x16_bf16 v[32:47], v[132:135], v[140:143], v[32:47]
	v_mfma_f32_32x32x16_bf16 v[80:95], v[128:131], v[144:147], v[80:95]
	v_mfma_f32_32x32x16_bf16 v[16:31], v[132:135], v[144:147], v[16:31]
	v_mfma_f32_32x32x16_bf16 v[64:79], v[128:131], v[148:151], v[64:79]
	v_mfma_f32_32x32x16_bf16 v[0:15], v[132:135], v[148:151], v[0:15]
	ds_read_b128 v[128:131], v187
	ds_read_b128 v[136:139], v191
	ds_read_b128 v[132:135], v187 offset:4096
	ds_read_b128 v[140:143], v191 offset:4096
	ds_read_b128 v[144:147], v191 offset:8192
	ds_read_b128 v[148:151], v191 offset:12288
	s_waitcnt lgkmcnt(6)
	v_mfma_f32_32x32x16_bf16 v[112:127], v[160:163], v[168:171], v[112:127]
	v_mfma_f32_32x32x16_bf16 v[48:63], v[164:167], v[168:171], v[48:63]
	v_mfma_f32_32x32x16_bf16 v[96:111], v[160:163], v[172:175], v[96:111]
	v_mfma_f32_32x32x16_bf16 v[32:47], v[164:167], v[172:175], v[32:47]
	v_mfma_f32_32x32x16_bf16 v[80:95], v[160:163], v[176:179], v[80:95]
	v_mfma_f32_32x32x16_bf16 v[16:31], v[164:167], v[176:179], v[16:31]
	v_mfma_f32_32x32x16_bf16 v[64:79], v[160:163], v[180:183], v[64:79]
	v_mfma_f32_32x32x16_bf16 v[0:15], v[164:167], v[180:183], v[0:15]
	s_waitcnt vmcnt(0) lgkmcnt(0)
	s_barrier
	ds_read_b128 v[160:163], v240
	ds_read_b128 v[168:171], v244
	ds_read_b128 v[164:167], v240 offset:4096
	ds_read_b128 v[172:175], v244 offset:4096
	ds_read_b128 v[176:179], v244 offset:8192
	ds_read_b128 v[180:183], v244 offset:12288
	s_add_u32 s20, s16, 768
	s_addc_u32 s21, s17, 0
	s_add_u32 s24, s18, 768
	s_addc_u32 s25, s19, 0
	s_add_u32 m0, s27, 0
	v_mfma_f32_32x32x16_bf16 v[112:127], v[128:131], v[136:139], v[112:127]
	global_load_lds_dwordx4 v192, s[20:21]
	s_add_u32 m0, s27, 32768
	v_mfma_f32_32x32x16_bf16 v[48:63], v[132:135], v[136:139], v[48:63]
	global_load_lds_dwordx4 v192, s[24:25]
	s_add_u32 m0, s27, 8192
	v_mfma_f32_32x32x16_bf16 v[96:111], v[128:131], v[140:143], v[96:111]
	global_load_lds_dwordx4 v194, s[20:21]
	s_add_u32 m0, s27, 40960
	v_mfma_f32_32x32x16_bf16 v[32:47], v[132:135], v[140:143], v[32:47]
	global_load_lds_dwordx4 v194, s[24:25]
	s_add_u32 m0, s27, 16384
	v_mfma_f32_32x32x16_bf16 v[80:95], v[128:131], v[144:147], v[80:95]
	global_load_lds_dwordx4 v196, s[20:21]
	s_add_u32 m0, s27, 49152
	v_mfma_f32_32x32x16_bf16 v[16:31], v[132:135], v[144:147], v[16:31]
	global_load_lds_dwordx4 v196, s[24:25]
	s_add_u32 m0, s27, 24576
	v_mfma_f32_32x32x16_bf16 v[64:79], v[128:131], v[148:151], v[64:79]
	global_load_lds_dwordx4 v198, s[20:21]
	s_add_u32 m0, s27, 57344
	v_mfma_f32_32x32x16_bf16 v[0:15], v[132:135], v[148:151], v[0:15]
	global_load_lds_dwordx4 v198, s[24:25]
	ds_read_b128 v[128:131], v241
	ds_read_b128 v[136:139], v245
	ds_read_b128 v[132:135], v241 offset:4096
	ds_read_b128 v[140:143], v245 offset:4096
	ds_read_b128 v[144:147], v245 offset:8192
	ds_read_b128 v[148:151], v245 offset:12288
	s_waitcnt lgkmcnt(6)
	v_mfma_f32_32x32x16_bf16 v[112:127], v[160:163], v[168:171], v[112:127]
	v_mfma_f32_32x32x16_bf16 v[48:63], v[164:167], v[168:171], v[48:63]
	v_mfma_f32_32x32x16_bf16 v[96:111], v[160:163], v[172:175], v[96:111]
	v_mfma_f32_32x32x16_bf16 v[32:47], v[164:167], v[172:175], v[32:47]
	v_mfma_f32_32x32x16_bf16 v[80:95], v[160:163], v[176:179], v[80:95]
	v_mfma_f32_32x32x16_bf16 v[16:31], v[164:167], v[176:179], v[16:31]
	v_mfma_f32_32x32x16_bf16 v[64:79], v[160:163], v[180:183], v[64:79]
	v_mfma_f32_32x32x16_bf16 v[0:15], v[164:167], v[180:183], v[0:15]
	ds_read_b128 v[160:163], v242
	ds_read_b128 v[168:171], v246
	ds_read_b128 v[164:167], v242 offset:4096
	ds_read_b128 v[172:175], v246 offset:4096
	ds_read_b128 v[176:179], v246 offset:8192
	ds_read_b128 v[180:183], v246 offset:12288
	s_waitcnt lgkmcnt(6)
	v_mfma_f32_32x32x16_bf16 v[112:127], v[128:131], v[136:139], v[112:127]
	v_mfma_f32_32x32x16_bf16 v[48:63], v[132:135], v[136:139], v[48:63]
	v_mfma_f32_32x32x16_bf16 v[96:111], v[128:131], v[140:143], v[96:111]
	v_mfma_f32_32x32x16_bf16 v[32:47], v[132:135], v[140:143], v[32:47]
	v_mfma_f32_32x32x16_bf16 v[80:95], v[128:131], v[144:147], v[80:95]
	v_mfma_f32_32x32x16_bf16 v[16:31], v[132:135], v[144:147], v[16:31]
	v_mfma_f32_32x32x16_bf16 v[64:79], v[128:131], v[148:151], v[64:79]
	v_mfma_f32_32x32x16_bf16 v[0:15], v[132:135], v[148:151], v[0:15]
	ds_read_b128 v[128:131], v243
	ds_read_b128 v[136:139], v247
	ds_read_b128 v[132:135], v243 offset:4096
	ds_read_b128 v[140:143], v247 offset:4096
	ds_read_b128 v[144:147], v247 offset:8192
	ds_read_b128 v[148:151], v247 offset:12288
	s_waitcnt lgkmcnt(6)
	v_mfma_f32_32x32x16_bf16 v[112:127], v[160:163], v[168:171], v[112:127]
	v_mfma_f32_32x32x16_bf16 v[48:63], v[164:167], v[168:171], v[48:63]
	v_mfma_f32_32x32x16_bf16 v[96:111], v[160:163], v[172:175], v[96:111]
	v_mfma_f32_32x32x16_bf16 v[32:47], v[164:167], v[172:175], v[32:47]
	v_mfma_f32_32x32x16_bf16 v[80:95], v[160:163], v[176:179], v[80:95]
	v_mfma_f32_32x32x16_bf16 v[16:31], v[164:167], v[176:179], v[16:31]
	v_mfma_f32_32x32x16_bf16 v[64:79], v[160:163], v[180:183], v[64:79]
	v_mfma_f32_32x32x16_bf16 v[0:15], v[164:167], v[180:183], v[0:15]
	s_waitcnt vmcnt(0) lgkmcnt(0)
	s_barrier
	ds_read_b128 v[160:163], v184
	ds_read_b128 v[168:171], v188
	ds_read_b128 v[164:167], v184 offset:4096
	ds_read_b128 v[172:175], v188 offset:4096
	ds_read_b128 v[176:179], v188 offset:8192
	ds_read_b128 v[180:183], v188 offset:12288
	s_add_u32 s20, s16, 896
	s_addc_u32 s21, s17, 0
	s_add_u32 s24, s18, 896
	s_addc_u32 s25, s19, 0
	s_add_u32 m0, s27, 65536
	v_mfma_f32_32x32x16_bf16 v[112:127], v[128:131], v[136:139], v[112:127]
	global_load_lds_dwordx4 v192, s[20:21]
	s_add_u32 m0, s27, 98304
	v_mfma_f32_32x32x16_bf16 v[48:63], v[132:135], v[136:139], v[48:63]
	global_load_lds_dwordx4 v192, s[24:25]
	s_add_u32 m0, s27, 73728
	v_mfma_f32_32x32x16_bf16 v[96:111], v[128:131], v[140:143], v[96:111]
	global_load_lds_dwordx4 v194, s[20:21]
	s_add_u32 m0, s27, 106496
	v_mfma_f32_32x32x16_bf16 v[32:47], v[132:135], v[140:143], v[32:47]
	global_load_lds_dwordx4 v194, s[24:25]
	s_add_u32 m0, s27, 81920
	v_mfma_f32_32x32x16_bf16 v[80:95], v[128:131], v[144:147], v[80:95]
	global_load_lds_dwordx4 v196, s[20:21]
	s_add_u32 m0, s27, 114688
	v_mfma_f32_32x32x16_bf16 v[16:31], v[132:135], v[144:147], v[16:31]
	global_load_lds_dwordx4 v196, s[24:25]
	s_add_u32 m0, s27, 90112
	v_mfma_f32_32x32x16_bf16 v[64:79], v[128:131], v[148:151], v[64:79]
	global_load_lds_dwordx4 v198, s[20:21]
	s_add_u32 m0, s27, 122880
	v_mfma_f32_32x32x16_bf16 v[0:15], v[132:135], v[148:151], v[0:15]
	global_load_lds_dwordx4 v198, s[24:25]
	ds_read_b128 v[128:131], v185
	ds_read_b128 v[136:139], v189
	ds_read_b128 v[132:135], v185 offset:4096
	ds_read_b128 v[140:143], v189 offset:4096
	ds_read_b128 v[144:147], v189 offset:8192
	ds_read_b128 v[148:151], v189 offset:12288
	s_waitcnt lgkmcnt(6)
	v_mfma_f32_32x32x16_bf16 v[112:127], v[160:163], v[168:171], v[112:127]
	v_mfma_f32_32x32x16_bf16 v[48:63], v[164:167], v[168:171], v[48:63]
	v_mfma_f32_32x32x16_bf16 v[96:111], v[160:163], v[172:175], v[96:111]
	v_mfma_f32_32x32x16_bf16 v[32:47], v[164:167], v[172:175], v[32:47]
	v_mfma_f32_32x32x16_bf16 v[80:95], v[160:163], v[176:179], v[80:95]
	v_mfma_f32_32x32x16_bf16 v[16:31], v[164:167], v[176:179], v[16:31]
	v_mfma_f32_32x32x16_bf16 v[64:79], v[160:163], v[180:183], v[64:79]
	v_mfma_f32_32x32x16_bf16 v[0:15], v[164:167], v[180:183], v[0:15]
	ds_read_b128 v[160:163], v186
	ds_read_b128 v[168:171], v190
	ds_read_b128 v[164:167], v186 offset:4096
	ds_read_b128 v[172:175], v190 offset:4096
	ds_read_b128 v[176:179], v190 offset:8192
	ds_read_b128 v[180:183], v190 offset:12288
	s_waitcnt lgkmcnt(6)
	v_mfma_f32_32x32x16_bf16 v[112:127], v[128:131], v[136:139], v[112:127]
	v_mfma_f32_32x32x16_bf16 v[48:63], v[132:135], v[136:139], v[48:63]
	v_mfma_f32_32x32x16_bf16 v[96:111], v[128:131], v[140:143], v[96:111]
	v_mfma_f32_32x32x16_bf16 v[32:47], v[132:135], v[140:143], v[32:47]
	v_mfma_f32_32x32x16_bf16 v[80:95], v[128:131], v[144:147], v[80:95]
	v_mfma_f32_32x32x16_bf16 v[16:31], v[132:135], v[144:147], v[16:31]
	v_mfma_f32_32x32x16_bf16 v[64:79], v[128:131], v[148:151], v[64:79]
	v_mfma_f32_32x32x16_bf16 v[0:15], v[132:135], v[148:151], v[0:15]
	ds_read_b128 v[128:131], v187
	ds_read_b128 v[136:139], v191
	ds_read_b128 v[132:135], v187 offset:4096
	ds_read_b128 v[140:143], v191 offset:4096
	ds_read_b128 v[144:147], v191 offset:8192
	ds_read_b128 v[148:151], v191 offset:12288
	s_waitcnt lgkmcnt(6)
	v_mfma_f32_32x32x16_bf16 v[112:127], v[160:163], v[168:171], v[112:127]
	v_mfma_f32_32x32x16_bf16 v[48:63], v[164:167], v[168:171], v[48:63]
	v_mfma_f32_32x32x16_bf16 v[96:111], v[160:163], v[172:175], v[96:111]
	v_mfma_f32_32x32x16_bf16 v[32:47], v[164:167], v[172:175], v[32:47]
	v_mfma_f32_32x32x16_bf16 v[80:95], v[160:163], v[176:179], v[80:95]
	v_mfma_f32_32x32x16_bf16 v[16:31], v[164:167], v[176:179], v[16:31]
	v_mfma_f32_32x32x16_bf16 v[64:79], v[160:163], v[180:183], v[64:79]
	v_mfma_f32_32x32x16_bf16 v[0:15], v[164:167], v[180:183], v[0:15]
	s_waitcnt vmcnt(0) lgkmcnt(0)
	s_barrier
	ds_read_b128 v[160:163], v240
	ds_read_b128 v[168:171], v244
	ds_read_b128 v[164:167], v240 offset:4096
	ds_read_b128 v[172:175], v244 offset:4096
	ds_read_b128 v[176:179], v244 offset:8192
	ds_read_b128 v[180:183], v244 offset:12288
	s_add_u32 s20, s16, 1024
	s_addc_u32 s21, s17, 0
	s_add_u32 s24, s18, 1024
	s_addc_u32 s25, s19, 0
	s_add_u32 m0, s27, 0
	v_mfma_f32_32x32x16_bf16 v[112:127], v[128:131], v[136:139], v[112:127]
	global_load_lds_dwordx4 v192, s[20:21]
	s_add_u32 m0, s27, 32768
	v_mfma_f32_32x32x16_bf16 v[48:63], v[132:135], v[136:139], v[48:63]
	global_load_lds_dwordx4 v192, s[24:25]
	s_add_u32 m0, s27, 8192
	v_mfma_f32_32x32x16_bf16 v[96:111], v[128:131], v[140:143], v[96:111]
	global_load_lds_dwordx4 v194, s[20:21]
	s_add_u32 m0, s27, 40960
	v_mfma_f32_32x32x16_bf16 v[32:47], v[132:135], v[140:143], v[32:47]
	global_load_lds_dwordx4 v194, s[24:25]
	s_add_u32 m0, s27, 16384
	v_mfma_f32_32x32x16_bf16 v[80:95], v[128:131], v[144:147], v[80:95]
	global_load_lds_dwordx4 v196, s[20:21]
	s_add_u32 m0, s27, 49152
	v_mfma_f32_32x32x16_bf16 v[16:31], v[132:135], v[144:147], v[16:31]
	global_load_lds_dwordx4 v196, s[24:25]
	s_add_u32 m0, s27, 24576
	v_mfma_f32_32x32x16_bf16 v[64:79], v[128:131], v[148:151], v[64:79]
	global_load_lds_dwordx4 v198, s[20:21]
	s_add_u32 m0, s27, 57344
	v_mfma_f32_32x32x16_bf16 v[0:15], v[132:135], v[148:151], v[0:15]
	global_load_lds_dwordx4 v198, s[24:25]
	ds_read_b128 v[128:131], v241
	ds_read_b128 v[136:139], v245
	ds_read_b128 v[132:135], v241 offset:4096
	ds_read_b128 v[140:143], v245 offset:4096
	ds_read_b128 v[144:147], v245 offset:8192
	ds_read_b128 v[148:151], v245 offset:12288
	s_waitcnt lgkmcnt(6)
	v_mfma_f32_32x32x16_bf16 v[112:127], v[160:163], v[168:171], v[112:127]
	v_mfma_f32_32x32x16_bf16 v[48:63], v[164:167], v[168:171], v[48:63]
	v_mfma_f32_32x32x16_bf16 v[96:111], v[160:163], v[172:175], v[96:111]
	v_mfma_f32_32x32x16_bf16 v[32:47], v[164:167], v[172:175], v[32:47]
	v_mfma_f32_32x32x16_bf16 v[80:95], v[160:163], v[176:179], v[80:95]
	v_mfma_f32_32x32x16_bf16 v[16:31], v[164:167], v[176:179], v[16:31]
	v_mfma_f32_32x32x16_bf16 v[64:79], v[160:163], v[180:183], v[64:79]
	v_mfma_f32_32x32x16_bf16 v[0:15], v[164:167], v[180:183], v[0:15]
	ds_read_b128 v[160:163], v242
	ds_read_b128 v[168:171], v246
	ds_read_b128 v[164:167], v242 offset:4096
	ds_read_b128 v[172:175], v246 offset:4096
	ds_read_b128 v[176:179], v246 offset:8192
	ds_read_b128 v[180:183], v246 offset:12288
	s_waitcnt lgkmcnt(6)
	v_mfma_f32_32x32x16_bf16 v[112:127], v[128:131], v[136:139], v[112:127]
	v_mfma_f32_32x32x16_bf16 v[48:63], v[132:135], v[136:139], v[48:63]
	v_mfma_f32_32x32x16_bf16 v[96:111], v[128:131], v[140:143], v[96:111]
	v_mfma_f32_32x32x16_bf16 v[32:47], v[132:135], v[140:143], v[32:47]
	v_mfma_f32_32x32x16_bf16 v[80:95], v[128:131], v[144:147], v[80:95]
	v_mfma_f32_32x32x16_bf16 v[16:31], v[132:135], v[144:147], v[16:31]
	v_mfma_f32_32x32x16_bf16 v[64:79], v[128:131], v[148:151], v[64:79]
	v_mfma_f32_32x32x16_bf16 v[0:15], v[132:135], v[148:151], v[0:15]
	ds_read_b128 v[128:131], v243
	ds_read_b128 v[136:139], v247
	ds_read_b128 v[132:135], v243 offset:4096
	ds_read_b128 v[140:143], v247 offset:4096
	ds_read_b128 v[144:147], v247 offset:8192
	ds_read_b128 v[148:151], v247 offset:12288
	s_waitcnt lgkmcnt(6)
	v_mfma_f32_32x32x16_bf16 v[112:127], v[160:163], v[168:171], v[112:127]
	v_mfma_f32_32x32x16_bf16 v[48:63], v[164:167], v[168:171], v[48:63]
	v_mfma_f32_32x32x16_bf16 v[96:111], v[160:163], v[172:175], v[96:111]
	v_mfma_f32_32x32x16_bf16 v[32:47], v[164:167], v[172:175], v[32:47]
	v_mfma_f32_32x32x16_bf16 v[80:95], v[160:163], v[176:179], v[80:95]
	v_mfma_f32_32x32x16_bf16 v[16:31], v[164:167], v[176:179], v[16:31]
	v_mfma_f32_32x32x16_bf16 v[64:79], v[160:163], v[180:183], v[64:79]
	v_mfma_f32_32x32x16_bf16 v[0:15], v[164:167], v[180:183], v[0:15]
	s_waitcnt vmcnt(0) lgkmcnt(0)
	s_barrier
	ds_read_b128 v[160:163], v184
	ds_read_b128 v[168:171], v188
	ds_read_b128 v[164:167], v184 offset:4096
	ds_read_b128 v[172:175], v188 offset:4096
	ds_read_b128 v[176:179], v188 offset:8192
	ds_read_b128 v[180:183], v188 offset:12288
	s_add_u32 s20, s16, 1152
	s_addc_u32 s21, s17, 0
	s_add_u32 s24, s18, 1152
	s_addc_u32 s25, s19, 0
	s_add_u32 m0, s27, 65536
	v_mfma_f32_32x32x16_bf16 v[112:127], v[128:131], v[136:139], v[112:127]
	global_load_lds_dwordx4 v192, s[20:21]
	s_add_u32 m0, s27, 98304
	v_mfma_f32_32x32x16_bf16 v[48:63], v[132:135], v[136:139], v[48:63]
	global_load_lds_dwordx4 v192, s[24:25]
	s_add_u32 m0, s27, 73728
	v_mfma_f32_32x32x16_bf16 v[96:111], v[128:131], v[140:143], v[96:111]
	global_load_lds_dwordx4 v194, s[20:21]
	s_add_u32 m0, s27, 106496
	v_mfma_f32_32x32x16_bf16 v[32:47], v[132:135], v[140:143], v[32:47]
	global_load_lds_dwordx4 v194, s[24:25]
	s_add_u32 m0, s27, 81920
	v_mfma_f32_32x32x16_bf16 v[80:95], v[128:131], v[144:147], v[80:95]
	global_load_lds_dwordx4 v196, s[20:21]
	s_add_u32 m0, s27, 114688
	v_mfma_f32_32x32x16_bf16 v[16:31], v[132:135], v[144:147], v[16:31]
	global_load_lds_dwordx4 v196, s[24:25]
	s_add_u32 m0, s27, 90112
	v_mfma_f32_32x32x16_bf16 v[64:79], v[128:131], v[148:151], v[64:79]
	global_load_lds_dwordx4 v198, s[20:21]
	s_add_u32 m0, s27, 122880
	v_mfma_f32_32x32x16_bf16 v[0:15], v[132:135], v[148:151], v[0:15]
	global_load_lds_dwordx4 v198, s[24:25]
	ds_read_b128 v[128:131], v185
	ds_read_b128 v[136:139], v189
	ds_read_b128 v[132:135], v185 offset:4096
	ds_read_b128 v[140:143], v189 offset:4096
	ds_read_b128 v[144:147], v189 offset:8192
	ds_read_b128 v[148:151], v189 offset:12288
	s_waitcnt lgkmcnt(6)
	v_mfma_f32_32x32x16_bf16 v[112:127], v[160:163], v[168:171], v[112:127]
	v_mfma_f32_32x32x16_bf16 v[48:63], v[164:167], v[168:171], v[48:63]
	v_mfma_f32_32x32x16_bf16 v[96:111], v[160:163], v[172:175], v[96:111]
	v_mfma_f32_32x32x16_bf16 v[32:47], v[164:167], v[172:175], v[32:47]
	v_mfma_f32_32x32x16_bf16 v[80:95], v[160:163], v[176:179], v[80:95]
	v_mfma_f32_32x32x16_bf16 v[16:31], v[164:167], v[176:179], v[16:31]
	v_mfma_f32_32x32x16_bf16 v[64:79], v[160:163], v[180:183], v[64:79]
	v_mfma_f32_32x32x16_bf16 v[0:15], v[164:167], v[180:183], v[0:15]
	ds_read_b128 v[160:163], v186
	ds_read_b128 v[168:171], v190
	ds_read_b128 v[164:167], v186 offset:4096
	ds_read_b128 v[172:175], v190 offset:4096
	ds_read_b128 v[176:179], v190 offset:8192
	ds_read_b128 v[180:183], v190 offset:12288
	s_waitcnt lgkmcnt(6)
	v_mfma_f32_32x32x16_bf16 v[112:127], v[128:131], v[136:139], v[112:127]
	v_mfma_f32_32x32x16_bf16 v[48:63], v[132:135], v[136:139], v[48:63]
	v_mfma_f32_32x32x16_bf16 v[96:111], v[128:131], v[140:143], v[96:111]
	v_mfma_f32_32x32x16_bf16 v[32:47], v[132:135], v[140:143], v[32:47]
	v_mfma_f32_32x32x16_bf16 v[80:95], v[128:131], v[144:147], v[80:95]
	v_mfma_f32_32x32x16_bf16 v[16:31], v[132:135], v[144:147], v[16:31]
	v_mfma_f32_32x32x16_bf16 v[64:79], v[128:131], v[148:151], v[64:79]
	v_mfma_f32_32x32x16_bf16 v[0:15], v[132:135], v[148:151], v[0:15]
	ds_read_b128 v[128:131], v187
	ds_read_b128 v[136:139], v191
	ds_read_b128 v[132:135], v187 offset:4096
	ds_read_b128 v[140:143], v191 offset:4096
	ds_read_b128 v[144:147], v191 offset:8192
	ds_read_b128 v[148:151], v191 offset:12288
	s_waitcnt lgkmcnt(6)
	v_mfma_f32_32x32x16_bf16 v[112:127], v[160:163], v[168:171], v[112:127]
	v_mfma_f32_32x32x16_bf16 v[48:63], v[164:167], v[168:171], v[48:63]
	v_mfma_f32_32x32x16_bf16 v[96:111], v[160:163], v[172:175], v[96:111]
	v_mfma_f32_32x32x16_bf16 v[32:47], v[164:167], v[172:175], v[32:47]
	v_mfma_f32_32x32x16_bf16 v[80:95], v[160:163], v[176:179], v[80:95]
	v_mfma_f32_32x32x16_bf16 v[16:31], v[164:167], v[176:179], v[16:31]
	v_mfma_f32_32x32x16_bf16 v[64:79], v[160:163], v[180:183], v[64:79]
	v_mfma_f32_32x32x16_bf16 v[0:15], v[164:167], v[180:183], v[0:15]
	s_waitcnt vmcnt(0) lgkmcnt(0)
	s_barrier
	ds_read_b128 v[160:163], v240
	ds_read_b128 v[168:171], v244
	ds_read_b128 v[164:167], v240 offset:4096
	ds_read_b128 v[172:175], v244 offset:4096
	ds_read_b128 v[176:179], v244 offset:8192
	ds_read_b128 v[180:183], v244 offset:12288
	s_add_u32 s20, s16, 1280
	s_addc_u32 s21, s17, 0
	s_add_u32 s24, s18, 1280
	s_addc_u32 s25, s19, 0
	s_add_u32 m0, s27, 0
	v_mfma_f32_32x32x16_bf16 v[112:127], v[128:131], v[136:139], v[112:127]
	global_load_lds_dwordx4 v192, s[20:21]
	s_add_u32 m0, s27, 32768
	v_mfma_f32_32x32x16_bf16 v[48:63], v[132:135], v[136:139], v[48:63]
	global_load_lds_dwordx4 v192, s[24:25]
	s_add_u32 m0, s27, 8192
	v_mfma_f32_32x32x16_bf16 v[96:111], v[128:131], v[140:143], v[96:111]
	global_load_lds_dwordx4 v194, s[20:21]
	s_add_u32 m0, s27, 40960
	v_mfma_f32_32x32x16_bf16 v[32:47], v[132:135], v[140:143], v[32:47]
	global_load_lds_dwordx4 v194, s[24:25]
	s_add_u32 m0, s27, 16384
	v_mfma_f32_32x32x16_bf16 v[80:95], v[128:131], v[144:147], v[80:95]
	global_load_lds_dwordx4 v196, s[20:21]
	s_add_u32 m0, s27, 49152
	v_mfma_f32_32x32x16_bf16 v[16:31], v[132:135], v[144:147], v[16:31]
	global_load_lds_dwordx4 v196, s[24:25]
	s_add_u32 m0, s27, 24576
	v_mfma_f32_32x32x16_bf16 v[64:79], v[128:131], v[148:151], v[64:79]
	global_load_lds_dwordx4 v198, s[20:21]
	s_add_u32 m0, s27, 57344
	v_mfma_f32_32x32x16_bf16 v[0:15], v[132:135], v[148:151], v[0:15]
	global_load_lds_dwordx4 v198, s[24:25]
	ds_read_b128 v[128:131], v241
	ds_read_b128 v[136:139], v245
	ds_read_b128 v[132:135], v241 offset:4096
	ds_read_b128 v[140:143], v245 offset:4096
	ds_read_b128 v[144:147], v245 offset:8192
	ds_read_b128 v[148:151], v245 offset:12288
	s_waitcnt lgkmcnt(6)
	v_mfma_f32_32x32x16_bf16 v[112:127], v[160:163], v[168:171], v[112:127]
	v_mfma_f32_32x32x16_bf16 v[48:63], v[164:167], v[168:171], v[48:63]
	v_mfma_f32_32x32x16_bf16 v[96:111], v[160:163], v[172:175], v[96:111]
	v_mfma_f32_32x32x16_bf16 v[32:47], v[164:167], v[172:175], v[32:47]
	v_mfma_f32_32x32x16_bf16 v[80:95], v[160:163], v[176:179], v[80:95]
	v_mfma_f32_32x32x16_bf16 v[16:31], v[164:167], v[176:179], v[16:31]
	v_mfma_f32_32x32x16_bf16 v[64:79], v[160:163], v[180:183], v[64:79]
	v_mfma_f32_32x32x16_bf16 v[0:15], v[164:167], v[180:183], v[0:15]
	ds_read_b128 v[160:163], v242
	ds_read_b128 v[168:171], v246
	ds_read_b128 v[164:167], v242 offset:4096
	ds_read_b128 v[172:175], v246 offset:4096
	ds_read_b128 v[176:179], v246 offset:8192
	ds_read_b128 v[180:183], v246 offset:12288
	s_waitcnt lgkmcnt(6)
	v_mfma_f32_32x32x16_bf16 v[112:127], v[128:131], v[136:139], v[112:127]
	v_mfma_f32_32x32x16_bf16 v[48:63], v[132:135], v[136:139], v[48:63]
	v_mfma_f32_32x32x16_bf16 v[96:111], v[128:131], v[140:143], v[96:111]
	v_mfma_f32_32x32x16_bf16 v[32:47], v[132:135], v[140:143], v[32:47]
	v_mfma_f32_32x32x16_bf16 v[80:95], v[128:131], v[144:147], v[80:95]
	v_mfma_f32_32x32x16_bf16 v[16:31], v[132:135], v[144:147], v[16:31]
	v_mfma_f32_32x32x16_bf16 v[64:79], v[128:131], v[148:151], v[64:79]
	v_mfma_f32_32x32x16_bf16 v[0:15], v[132:135], v[148:151], v[0:15]
	ds_read_b128 v[128:131], v243
	ds_read_b128 v[136:139], v247
	ds_read_b128 v[132:135], v243 offset:4096
	ds_read_b128 v[140:143], v247 offset:4096
	ds_read_b128 v[144:147], v247 offset:8192
	ds_read_b128 v[148:151], v247 offset:12288
	s_waitcnt lgkmcnt(6)
	v_mfma_f32_32x32x16_bf16 v[112:127], v[160:163], v[168:171], v[112:127]
	v_mfma_f32_32x32x16_bf16 v[48:63], v[164:167], v[168:171], v[48:63]
	v_mfma_f32_32x32x16_bf16 v[96:111], v[160:163], v[172:175], v[96:111]
	v_mfma_f32_32x32x16_bf16 v[32:47], v[164:167], v[172:175], v[32:47]
	v_mfma_f32_32x32x16_bf16 v[80:95], v[160:163], v[176:179], v[80:95]
	v_mfma_f32_32x32x16_bf16 v[16:31], v[164:167], v[176:179], v[16:31]
	v_mfma_f32_32x32x16_bf16 v[64:79], v[160:163], v[180:183], v[64:79]
	v_mfma_f32_32x32x16_bf16 v[0:15], v[164:167], v[180:183], v[0:15]
	s_waitcnt vmcnt(0) lgkmcnt(0)
	s_barrier
	ds_read_b128 v[160:163], v184
	ds_read_b128 v[168:171], v188
	ds_read_b128 v[164:167], v184 offset:4096
	ds_read_b128 v[172:175], v188 offset:4096
	ds_read_b128 v[176:179], v188 offset:8192
	ds_read_b128 v[180:183], v188 offset:12288
	s_add_u32 s20, s16, 1408
	s_addc_u32 s21, s17, 0
	s_add_u32 s24, s18, 1408
	s_addc_u32 s25, s19, 0
	s_add_u32 m0, s27, 65536
	v_mfma_f32_32x32x16_bf16 v[112:127], v[128:131], v[136:139], v[112:127]
	global_load_lds_dwordx4 v192, s[20:21]
	s_add_u32 m0, s27, 98304
	v_mfma_f32_32x32x16_bf16 v[48:63], v[132:135], v[136:139], v[48:63]
	global_load_lds_dwordx4 v192, s[24:25]
	s_add_u32 m0, s27, 73728
	v_mfma_f32_32x32x16_bf16 v[96:111], v[128:131], v[140:143], v[96:111]
	global_load_lds_dwordx4 v194, s[20:21]
	s_add_u32 m0, s27, 106496
	v_mfma_f32_32x32x16_bf16 v[32:47], v[132:135], v[140:143], v[32:47]
	global_load_lds_dwordx4 v194, s[24:25]
	s_add_u32 m0, s27, 81920
	v_mfma_f32_32x32x16_bf16 v[80:95], v[128:131], v[144:147], v[80:95]
	global_load_lds_dwordx4 v196, s[20:21]
	s_add_u32 m0, s27, 114688
	v_mfma_f32_32x32x16_bf16 v[16:31], v[132:135], v[144:147], v[16:31]
	global_load_lds_dwordx4 v196, s[24:25]
	s_add_u32 m0, s27, 90112
	v_mfma_f32_32x32x16_bf16 v[64:79], v[128:131], v[148:151], v[64:79]
	global_load_lds_dwordx4 v198, s[20:21]
	s_add_u32 m0, s27, 122880
	v_mfma_f32_32x32x16_bf16 v[0:15], v[132:135], v[148:151], v[0:15]
	global_load_lds_dwordx4 v198, s[24:25]
	ds_read_b128 v[128:131], v185
	ds_read_b128 v[136:139], v189
	ds_read_b128 v[132:135], v185 offset:4096
	ds_read_b128 v[140:143], v189 offset:4096
	ds_read_b128 v[144:147], v189 offset:8192
	ds_read_b128 v[148:151], v189 offset:12288
	s_waitcnt lgkmcnt(6)
	v_mfma_f32_32x32x16_bf16 v[112:127], v[160:163], v[168:171], v[112:127]
	v_mfma_f32_32x32x16_bf16 v[48:63], v[164:167], v[168:171], v[48:63]
	v_mfma_f32_32x32x16_bf16 v[96:111], v[160:163], v[172:175], v[96:111]
	v_mfma_f32_32x32x16_bf16 v[32:47], v[164:167], v[172:175], v[32:47]
	v_mfma_f32_32x32x16_bf16 v[80:95], v[160:163], v[176:179], v[80:95]
	v_mfma_f32_32x32x16_bf16 v[16:31], v[164:167], v[176:179], v[16:31]
	v_mfma_f32_32x32x16_bf16 v[64:79], v[160:163], v[180:183], v[64:79]
	v_mfma_f32_32x32x16_bf16 v[0:15], v[164:167], v[180:183], v[0:15]
	ds_read_b128 v[160:163], v186
	ds_read_b128 v[168:171], v190
	ds_read_b128 v[164:167], v186 offset:4096
	ds_read_b128 v[172:175], v190 offset:4096
	ds_read_b128 v[176:179], v190 offset:8192
	ds_read_b128 v[180:183], v190 offset:12288
	s_waitcnt lgkmcnt(6)
	v_mfma_f32_32x32x16_bf16 v[112:127], v[128:131], v[136:139], v[112:127]
	v_mfma_f32_32x32x16_bf16 v[48:63], v[132:135], v[136:139], v[48:63]
	v_mfma_f32_32x32x16_bf16 v[96:111], v[128:131], v[140:143], v[96:111]
	v_mfma_f32_32x32x16_bf16 v[32:47], v[132:135], v[140:143], v[32:47]
	v_mfma_f32_32x32x16_bf16 v[80:95], v[128:131], v[144:147], v[80:95]
	v_mfma_f32_32x32x16_bf16 v[16:31], v[132:135], v[144:147], v[16:31]
	v_mfma_f32_32x32x16_bf16 v[64:79], v[128:131], v[148:151], v[64:79]
	v_mfma_f32_32x32x16_bf16 v[0:15], v[132:135], v[148:151], v[0:15]
	ds_read_b128 v[128:131], v187
	ds_read_b128 v[136:139], v191
	ds_read_b128 v[132:135], v187 offset:4096
	ds_read_b128 v[140:143], v191 offset:4096
	ds_read_b128 v[144:147], v191 offset:8192
	ds_read_b128 v[148:151], v191 offset:12288
	s_waitcnt lgkmcnt(6)
	v_mfma_f32_32x32x16_bf16 v[112:127], v[160:163], v[168:171], v[112:127]
	v_mfma_f32_32x32x16_bf16 v[48:63], v[164:167], v[168:171], v[48:63]
	v_mfma_f32_32x32x16_bf16 v[96:111], v[160:163], v[172:175], v[96:111]
	v_mfma_f32_32x32x16_bf16 v[32:47], v[164:167], v[172:175], v[32:47]
	v_mfma_f32_32x32x16_bf16 v[80:95], v[160:163], v[176:179], v[80:95]
	v_mfma_f32_32x32x16_bf16 v[16:31], v[164:167], v[176:179], v[16:31]
	v_mfma_f32_32x32x16_bf16 v[64:79], v[160:163], v[180:183], v[64:79]
	v_mfma_f32_32x32x16_bf16 v[0:15], v[164:167], v[180:183], v[0:15]
	s_waitcnt vmcnt(0) lgkmcnt(0)
	s_barrier
	ds_read_b128 v[160:163], v240
	ds_read_b128 v[168:171], v244
	ds_read_b128 v[164:167], v240 offset:4096
	ds_read_b128 v[172:175], v244 offset:4096
	ds_read_b128 v[176:179], v244 offset:8192
	ds_read_b128 v[180:183], v244 offset:12288
	s_add_u32 s20, s16, 1536
	s_addc_u32 s21, s17, 0
	s_add_u32 s24, s18, 1536
	s_addc_u32 s25, s19, 0
	s_add_u32 m0, s27, 0
	v_mfma_f32_32x32x16_bf16 v[112:127], v[128:131], v[136:139], v[112:127]
	global_load_lds_dwordx4 v192, s[20:21]
	s_add_u32 m0, s27, 32768
	v_mfma_f32_32x32x16_bf16 v[48:63], v[132:135], v[136:139], v[48:63]
	global_load_lds_dwordx4 v192, s[24:25]
	s_add_u32 m0, s27, 8192
	v_mfma_f32_32x32x16_bf16 v[96:111], v[128:131], v[140:143], v[96:111]
	global_load_lds_dwordx4 v194, s[20:21]
	s_add_u32 m0, s27, 40960
	v_mfma_f32_32x32x16_bf16 v[32:47], v[132:135], v[140:143], v[32:47]
	global_load_lds_dwordx4 v194, s[24:25]
	s_add_u32 m0, s27, 16384
	v_mfma_f32_32x32x16_bf16 v[80:95], v[128:131], v[144:147], v[80:95]
	global_load_lds_dwordx4 v196, s[20:21]
	s_add_u32 m0, s27, 49152
	v_mfma_f32_32x32x16_bf16 v[16:31], v[132:135], v[144:147], v[16:31]
	global_load_lds_dwordx4 v196, s[24:25]
	s_add_u32 m0, s27, 24576
	v_mfma_f32_32x32x16_bf16 v[64:79], v[128:131], v[148:151], v[64:79]
	global_load_lds_dwordx4 v198, s[20:21]
	s_add_u32 m0, s27, 57344
	v_mfma_f32_32x32x16_bf16 v[0:15], v[132:135], v[148:151], v[0:15]
	global_load_lds_dwordx4 v198, s[24:25]
	ds_read_b128 v[128:131], v241
	ds_read_b128 v[136:139], v245
	ds_read_b128 v[132:135], v241 offset:4096
	ds_read_b128 v[140:143], v245 offset:4096
	ds_read_b128 v[144:147], v245 offset:8192
	ds_read_b128 v[148:151], v245 offset:12288
	s_waitcnt lgkmcnt(6)
	v_mfma_f32_32x32x16_bf16 v[112:127], v[160:163], v[168:171], v[112:127]
	v_mfma_f32_32x32x16_bf16 v[48:63], v[164:167], v[168:171], v[48:63]
	v_mfma_f32_32x32x16_bf16 v[96:111], v[160:163], v[172:175], v[96:111]
	v_mfma_f32_32x32x16_bf16 v[32:47], v[164:167], v[172:175], v[32:47]
	v_mfma_f32_32x32x16_bf16 v[80:95], v[160:163], v[176:179], v[80:95]
	v_mfma_f32_32x32x16_bf16 v[16:31], v[164:167], v[176:179], v[16:31]
	v_mfma_f32_32x32x16_bf16 v[64:79], v[160:163], v[180:183], v[64:79]
	v_mfma_f32_32x32x16_bf16 v[0:15], v[164:167], v[180:183], v[0:15]
	ds_read_b128 v[160:163], v242
	ds_read_b128 v[168:171], v246
	ds_read_b128 v[164:167], v242 offset:4096
	ds_read_b128 v[172:175], v246 offset:4096
	ds_read_b128 v[176:179], v246 offset:8192
	ds_read_b128 v[180:183], v246 offset:12288
	s_waitcnt lgkmcnt(6)
	v_mfma_f32_32x32x16_bf16 v[112:127], v[128:131], v[136:139], v[112:127]
	v_mfma_f32_32x32x16_bf16 v[48:63], v[132:135], v[136:139], v[48:63]
	v_mfma_f32_32x32x16_bf16 v[96:111], v[128:131], v[140:143], v[96:111]
	v_mfma_f32_32x32x16_bf16 v[32:47], v[132:135], v[140:143], v[32:47]
	v_mfma_f32_32x32x16_bf16 v[80:95], v[128:131], v[144:147], v[80:95]
	v_mfma_f32_32x32x16_bf16 v[16:31], v[132:135], v[144:147], v[16:31]
	v_mfma_f32_32x32x16_bf16 v[64:79], v[128:131], v[148:151], v[64:79]
	v_mfma_f32_32x32x16_bf16 v[0:15], v[132:135], v[148:151], v[0:15]
	ds_read_b128 v[128:131], v243
	ds_read_b128 v[136:139], v247
	ds_read_b128 v[132:135], v243 offset:4096
	ds_read_b128 v[140:143], v247 offset:4096
	ds_read_b128 v[144:147], v247 offset:8192
	ds_read_b128 v[148:151], v247 offset:12288
	s_waitcnt lgkmcnt(6)
	v_mfma_f32_32x32x16_bf16 v[112:127], v[160:163], v[168:171], v[112:127]
	v_mfma_f32_32x32x16_bf16 v[48:63], v[164:167], v[168:171], v[48:63]
	v_mfma_f32_32x32x16_bf16 v[96:111], v[160:163], v[172:175], v[96:111]
	v_mfma_f32_32x32x16_bf16 v[32:47], v[164:167], v[172:175], v[32:47]
	v_mfma_f32_32x32x16_bf16 v[80:95], v[160:163], v[176:179], v[80:95]
	v_mfma_f32_32x32x16_bf16 v[16:31], v[164:167], v[176:179], v[16:31]
	v_mfma_f32_32x32x16_bf16 v[64:79], v[160:163], v[180:183], v[64:79]
	v_mfma_f32_32x32x16_bf16 v[0:15], v[164:167], v[180:183], v[0:15]
	s_waitcnt vmcnt(0) lgkmcnt(0)
	s_barrier
	ds_read_b128 v[160:163], v184
	ds_read_b128 v[168:171], v188
	ds_read_b128 v[164:167], v184 offset:4096
	ds_read_b128 v[172:175], v188 offset:4096
	ds_read_b128 v[176:179], v188 offset:8192
	ds_read_b128 v[180:183], v188 offset:12288
	s_add_u32 s20, s16, 1664
	s_addc_u32 s21, s17, 0
	s_add_u32 s24, s18, 1664
	s_addc_u32 s25, s19, 0
	s_add_u32 m0, s27, 65536
	v_mfma_f32_32x32x16_bf16 v[112:127], v[128:131], v[136:139], v[112:127]
	global_load_lds_dwordx4 v192, s[20:21]
	s_add_u32 m0, s27, 98304
	v_mfma_f32_32x32x16_bf16 v[48:63], v[132:135], v[136:139], v[48:63]
	global_load_lds_dwordx4 v192, s[24:25]
	s_add_u32 m0, s27, 73728
	v_mfma_f32_32x32x16_bf16 v[96:111], v[128:131], v[140:143], v[96:111]
	global_load_lds_dwordx4 v194, s[20:21]
	s_add_u32 m0, s27, 106496
	v_mfma_f32_32x32x16_bf16 v[32:47], v[132:135], v[140:143], v[32:47]
	global_load_lds_dwordx4 v194, s[24:25]
	s_add_u32 m0, s27, 81920
	v_mfma_f32_32x32x16_bf16 v[80:95], v[128:131], v[144:147], v[80:95]
	global_load_lds_dwordx4 v196, s[20:21]
	s_add_u32 m0, s27, 114688
	v_mfma_f32_32x32x16_bf16 v[16:31], v[132:135], v[144:147], v[16:31]
	global_load_lds_dwordx4 v196, s[24:25]
	s_add_u32 m0, s27, 90112
	v_mfma_f32_32x32x16_bf16 v[64:79], v[128:131], v[148:151], v[64:79]
	global_load_lds_dwordx4 v198, s[20:21]
	s_add_u32 m0, s27, 122880
	v_mfma_f32_32x32x16_bf16 v[0:15], v[132:135], v[148:151], v[0:15]
	global_load_lds_dwordx4 v198, s[24:25]
	ds_read_b128 v[128:131], v185
	ds_read_b128 v[136:139], v189
	ds_read_b128 v[132:135], v185 offset:4096
	ds_read_b128 v[140:143], v189 offset:4096
	ds_read_b128 v[144:147], v189 offset:8192
	ds_read_b128 v[148:151], v189 offset:12288
	s_waitcnt lgkmcnt(6)
	v_mfma_f32_32x32x16_bf16 v[112:127], v[160:163], v[168:171], v[112:127]
	v_mfma_f32_32x32x16_bf16 v[48:63], v[164:167], v[168:171], v[48:63]
	v_mfma_f32_32x32x16_bf16 v[96:111], v[160:163], v[172:175], v[96:111]
	v_mfma_f32_32x32x16_bf16 v[32:47], v[164:167], v[172:175], v[32:47]
	v_mfma_f32_32x32x16_bf16 v[80:95], v[160:163], v[176:179], v[80:95]
	v_mfma_f32_32x32x16_bf16 v[16:31], v[164:167], v[176:179], v[16:31]
	v_mfma_f32_32x32x16_bf16 v[64:79], v[160:163], v[180:183], v[64:79]
	v_mfma_f32_32x32x16_bf16 v[0:15], v[164:167], v[180:183], v[0:15]
	ds_read_b128 v[160:163], v186
	ds_read_b128 v[168:171], v190
	ds_read_b128 v[164:167], v186 offset:4096
	ds_read_b128 v[172:175], v190 offset:4096
	ds_read_b128 v[176:179], v190 offset:8192
	ds_read_b128 v[180:183], v190 offset:12288
	s_waitcnt lgkmcnt(6)
	v_mfma_f32_32x32x16_bf16 v[112:127], v[128:131], v[136:139], v[112:127]
	v_mfma_f32_32x32x16_bf16 v[48:63], v[132:135], v[136:139], v[48:63]
	v_mfma_f32_32x32x16_bf16 v[96:111], v[128:131], v[140:143], v[96:111]
	v_mfma_f32_32x32x16_bf16 v[32:47], v[132:135], v[140:143], v[32:47]
	v_mfma_f32_32x32x16_bf16 v[80:95], v[128:131], v[144:147], v[80:95]
	v_mfma_f32_32x32x16_bf16 v[16:31], v[132:135], v[144:147], v[16:31]
	v_mfma_f32_32x32x16_bf16 v[64:79], v[128:131], v[148:151], v[64:79]
	v_mfma_f32_32x32x16_bf16 v[0:15], v[132:135], v[148:151], v[0:15]
	ds_read_b128 v[128:131], v187
	ds_read_b128 v[136:139], v191
	ds_read_b128 v[132:135], v187 offset:4096
	ds_read_b128 v[140:143], v191 offset:4096
	ds_read_b128 v[144:147], v191 offset:8192
	ds_read_b128 v[148:151], v191 offset:12288
	s_waitcnt lgkmcnt(6)
	v_mfma_f32_32x32x16_bf16 v[112:127], v[160:163], v[168:171], v[112:127]
	v_mfma_f32_32x32x16_bf16 v[48:63], v[164:167], v[168:171], v[48:63]
	v_mfma_f32_32x32x16_bf16 v[96:111], v[160:163], v[172:175], v[96:111]
	v_mfma_f32_32x32x16_bf16 v[32:47], v[164:167], v[172:175], v[32:47]
	v_mfma_f32_32x32x16_bf16 v[80:95], v[160:163], v[176:179], v[80:95]
	v_mfma_f32_32x32x16_bf16 v[16:31], v[164:167], v[176:179], v[16:31]
	v_mfma_f32_32x32x16_bf16 v[64:79], v[160:163], v[180:183], v[64:79]
	v_mfma_f32_32x32x16_bf16 v[0:15], v[164:167], v[180:183], v[0:15]
	s_waitcnt vmcnt(0) lgkmcnt(0)
	s_barrier
	ds_read_b128 v[160:163], v240
	ds_read_b128 v[168:171], v244
	ds_read_b128 v[164:167], v240 offset:4096
	ds_read_b128 v[172:175], v244 offset:4096
	ds_read_b128 v[176:179], v244 offset:8192
	ds_read_b128 v[180:183], v244 offset:12288
	s_add_u32 s20, s16, 1792
	s_addc_u32 s21, s17, 0
	s_add_u32 s24, s18, 1792
	s_addc_u32 s25, s19, 0
	s_add_u32 m0, s27, 0
	v_mfma_f32_32x32x16_bf16 v[112:127], v[128:131], v[136:139], v[112:127]
	global_load_lds_dwordx4 v192, s[20:21]
	s_add_u32 m0, s27, 32768
	v_mfma_f32_32x32x16_bf16 v[48:63], v[132:135], v[136:139], v[48:63]
	global_load_lds_dwordx4 v192, s[24:25]
	s_add_u32 m0, s27, 8192
	v_mfma_f32_32x32x16_bf16 v[96:111], v[128:131], v[140:143], v[96:111]
	global_load_lds_dwordx4 v194, s[20:21]
	s_add_u32 m0, s27, 40960
	v_mfma_f32_32x32x16_bf16 v[32:47], v[132:135], v[140:143], v[32:47]
	global_load_lds_dwordx4 v194, s[24:25]
	s_add_u32 m0, s27, 16384
	v_mfma_f32_32x32x16_bf16 v[80:95], v[128:131], v[144:147], v[80:95]
	global_load_lds_dwordx4 v196, s[20:21]
	s_add_u32 m0, s27, 49152
	v_mfma_f32_32x32x16_bf16 v[16:31], v[132:135], v[144:147], v[16:31]
	global_load_lds_dwordx4 v196, s[24:25]
	s_add_u32 m0, s27, 24576
	v_mfma_f32_32x32x16_bf16 v[64:79], v[128:131], v[148:151], v[64:79]
	global_load_lds_dwordx4 v198, s[20:21]
	s_add_u32 m0, s27, 57344
	v_mfma_f32_32x32x16_bf16 v[0:15], v[132:135], v[148:151], v[0:15]
	global_load_lds_dwordx4 v198, s[24:25]
	ds_read_b128 v[128:131], v241
	ds_read_b128 v[136:139], v245
	ds_read_b128 v[132:135], v241 offset:4096
	ds_read_b128 v[140:143], v245 offset:4096
	ds_read_b128 v[144:147], v245 offset:8192
	ds_read_b128 v[148:151], v245 offset:12288
	s_waitcnt lgkmcnt(6)
	v_mfma_f32_32x32x16_bf16 v[112:127], v[160:163], v[168:171], v[112:127]
	v_mfma_f32_32x32x16_bf16 v[48:63], v[164:167], v[168:171], v[48:63]
	v_mfma_f32_32x32x16_bf16 v[96:111], v[160:163], v[172:175], v[96:111]
	v_mfma_f32_32x32x16_bf16 v[32:47], v[164:167], v[172:175], v[32:47]
	v_mfma_f32_32x32x16_bf16 v[80:95], v[160:163], v[176:179], v[80:95]
	v_mfma_f32_32x32x16_bf16 v[16:31], v[164:167], v[176:179], v[16:31]
	v_mfma_f32_32x32x16_bf16 v[64:79], v[160:163], v[180:183], v[64:79]
	v_mfma_f32_32x32x16_bf16 v[0:15], v[164:167], v[180:183], v[0:15]
	ds_read_b128 v[160:163], v242
	ds_read_b128 v[168:171], v246
	ds_read_b128 v[164:167], v242 offset:4096
	ds_read_b128 v[172:175], v246 offset:4096
	ds_read_b128 v[176:179], v246 offset:8192
	ds_read_b128 v[180:183], v246 offset:12288
	s_waitcnt lgkmcnt(6)
	v_mfma_f32_32x32x16_bf16 v[112:127], v[128:131], v[136:139], v[112:127]
	v_mfma_f32_32x32x16_bf16 v[48:63], v[132:135], v[136:139], v[48:63]
	v_mfma_f32_32x32x16_bf16 v[96:111], v[128:131], v[140:143], v[96:111]
	v_mfma_f32_32x32x16_bf16 v[32:47], v[132:135], v[140:143], v[32:47]
	v_mfma_f32_32x32x16_bf16 v[80:95], v[128:131], v[144:147], v[80:95]
	v_mfma_f32_32x32x16_bf16 v[16:31], v[132:135], v[144:147], v[16:31]
	v_mfma_f32_32x32x16_bf16 v[64:79], v[128:131], v[148:151], v[64:79]
	v_mfma_f32_32x32x16_bf16 v[0:15], v[132:135], v[148:151], v[0:15]
	ds_read_b128 v[128:131], v243
	ds_read_b128 v[136:139], v247
	ds_read_b128 v[132:135], v243 offset:4096
	ds_read_b128 v[140:143], v247 offset:4096
	ds_read_b128 v[144:147], v247 offset:8192
	ds_read_b128 v[148:151], v247 offset:12288
	s_waitcnt lgkmcnt(6)
	v_mfma_f32_32x32x16_bf16 v[112:127], v[160:163], v[168:171], v[112:127]
	v_mfma_f32_32x32x16_bf16 v[48:63], v[164:167], v[168:171], v[48:63]
	v_mfma_f32_32x32x16_bf16 v[96:111], v[160:163], v[172:175], v[96:111]
	v_mfma_f32_32x32x16_bf16 v[32:47], v[164:167], v[172:175], v[32:47]
	v_mfma_f32_32x32x16_bf16 v[80:95], v[160:163], v[176:179], v[80:95]
	v_mfma_f32_32x32x16_bf16 v[16:31], v[164:167], v[176:179], v[16:31]
	v_mfma_f32_32x32x16_bf16 v[64:79], v[160:163], v[180:183], v[64:79]
	v_mfma_f32_32x32x16_bf16 v[0:15], v[164:167], v[180:183], v[0:15]
	s_waitcnt vmcnt(0) lgkmcnt(0)
	s_barrier
	ds_read_b128 v[160:163], v184
	ds_read_b128 v[168:171], v188
	ds_read_b128 v[164:167], v184 offset:4096
	ds_read_b128 v[172:175], v188 offset:4096
	ds_read_b128 v[176:179], v188 offset:8192
	ds_read_b128 v[180:183], v188 offset:12288
	s_add_u32 s20, s16, 1920
	s_addc_u32 s21, s17, 0
	s_add_u32 s24, s18, 1920
	s_addc_u32 s25, s19, 0
	s_add_u32 m0, s27, 65536
	v_mfma_f32_32x32x16_bf16 v[112:127], v[128:131], v[136:139], v[112:127]
	global_load_lds_dwordx4 v192, s[20:21]
	s_add_u32 m0, s27, 98304
	v_mfma_f32_32x32x16_bf16 v[48:63], v[132:135], v[136:139], v[48:63]
	global_load_lds_dwordx4 v192, s[24:25]
	s_add_u32 m0, s27, 73728
	v_mfma_f32_32x32x16_bf16 v[96:111], v[128:131], v[140:143], v[96:111]
	global_load_lds_dwordx4 v194, s[20:21]
	s_add_u32 m0, s27, 106496
	v_mfma_f32_32x32x16_bf16 v[32:47], v[132:135], v[140:143], v[32:47]
	global_load_lds_dwordx4 v194, s[24:25]
	s_add_u32 m0, s27, 81920
	v_mfma_f32_32x32x16_bf16 v[80:95], v[128:131], v[144:147], v[80:95]
	global_load_lds_dwordx4 v196, s[20:21]
	s_add_u32 m0, s27, 114688
	v_mfma_f32_32x32x16_bf16 v[16:31], v[132:135], v[144:147], v[16:31]
	global_load_lds_dwordx4 v196, s[24:25]
	s_add_u32 m0, s27, 90112
	v_mfma_f32_32x32x16_bf16 v[64:79], v[128:131], v[148:151], v[64:79]
	global_load_lds_dwordx4 v198, s[20:21]
	s_add_u32 m0, s27, 122880
	v_mfma_f32_32x32x16_bf16 v[0:15], v[132:135], v[148:151], v[0:15]
	global_load_lds_dwordx4 v198, s[24:25]
	ds_read_b128 v[128:131], v185
	ds_read_b128 v[136:139], v189
	ds_read_b128 v[132:135], v185 offset:4096
	ds_read_b128 v[140:143], v189 offset:4096
	ds_read_b128 v[144:147], v189 offset:8192
	ds_read_b128 v[148:151], v189 offset:12288
	s_waitcnt lgkmcnt(6)
	v_mfma_f32_32x32x16_bf16 v[112:127], v[160:163], v[168:171], v[112:127]
	v_mfma_f32_32x32x16_bf16 v[48:63], v[164:167], v[168:171], v[48:63]
	v_mfma_f32_32x32x16_bf16 v[96:111], v[160:163], v[172:175], v[96:111]
	v_mfma_f32_32x32x16_bf16 v[32:47], v[164:167], v[172:175], v[32:47]
	v_mfma_f32_32x32x16_bf16 v[80:95], v[160:163], v[176:179], v[80:95]
	v_mfma_f32_32x32x16_bf16 v[16:31], v[164:167], v[176:179], v[16:31]
	v_mfma_f32_32x32x16_bf16 v[64:79], v[160:163], v[180:183], v[64:79]
	v_mfma_f32_32x32x16_bf16 v[0:15], v[164:167], v[180:183], v[0:15]
	ds_read_b128 v[160:163], v186
	ds_read_b128 v[168:171], v190
	ds_read_b128 v[164:167], v186 offset:4096
	ds_read_b128 v[172:175], v190 offset:4096
	ds_read_b128 v[176:179], v190 offset:8192
	ds_read_b128 v[180:183], v190 offset:12288
	s_waitcnt lgkmcnt(6)
	v_mfma_f32_32x32x16_bf16 v[112:127], v[128:131], v[136:139], v[112:127]
	v_mfma_f32_32x32x16_bf16 v[48:63], v[132:135], v[136:139], v[48:63]
	v_mfma_f32_32x32x16_bf16 v[96:111], v[128:131], v[140:143], v[96:111]
	v_mfma_f32_32x32x16_bf16 v[32:47], v[132:135], v[140:143], v[32:47]
	v_mfma_f32_32x32x16_bf16 v[80:95], v[128:131], v[144:147], v[80:95]
	v_mfma_f32_32x32x16_bf16 v[16:31], v[132:135], v[144:147], v[16:31]
	v_mfma_f32_32x32x16_bf16 v[64:79], v[128:131], v[148:151], v[64:79]
	v_mfma_f32_32x32x16_bf16 v[0:15], v[132:135], v[148:151], v[0:15]
	ds_read_b128 v[128:131], v187
	ds_read_b128 v[136:139], v191
	ds_read_b128 v[132:135], v187 offset:4096
	ds_read_b128 v[140:143], v191 offset:4096
	ds_read_b128 v[144:147], v191 offset:8192
	ds_read_b128 v[148:151], v191 offset:12288
	s_waitcnt lgkmcnt(6)
	v_mfma_f32_32x32x16_bf16 v[112:127], v[160:163], v[168:171], v[112:127]
	v_mfma_f32_32x32x16_bf16 v[48:63], v[164:167], v[168:171], v[48:63]
	v_mfma_f32_32x32x16_bf16 v[96:111], v[160:163], v[172:175], v[96:111]
	v_mfma_f32_32x32x16_bf16 v[32:47], v[164:167], v[172:175], v[32:47]
	v_mfma_f32_32x32x16_bf16 v[80:95], v[160:163], v[176:179], v[80:95]
	v_mfma_f32_32x32x16_bf16 v[16:31], v[164:167], v[176:179], v[16:31]
	v_mfma_f32_32x32x16_bf16 v[64:79], v[160:163], v[180:183], v[64:79]
	v_mfma_f32_32x32x16_bf16 v[0:15], v[164:167], v[180:183], v[0:15]
	s_waitcnt vmcnt(0) lgkmcnt(0)
	s_barrier
	ds_read_b128 v[160:163], v240
	ds_read_b128 v[168:171], v244
	ds_read_b128 v[164:167], v240 offset:4096
	ds_read_b128 v[172:175], v244 offset:4096
	ds_read_b128 v[176:179], v244 offset:8192
	ds_read_b128 v[180:183], v244 offset:12288
	s_add_u32 s37, s30, s42
	s_cmpk_ge_u32 s37, 0x780
	s_cbranch_scc1 .Lip11_full_nonext
	s_mul_hi_u32 s38, s37, 0x92492493
	s_lshr_b32 s38, s38, 3
	s_mul_i32 s39, s38, 14
	s_sub_u32 s39, s37, s39
	s_sub_u32 s98, s37, 0x700
	s_cmpk_lt_u32 s37, 0x700
	s_cselect_b32 s39, s39, 14
	s_cselect_b32 s38, s38, s98
	s_lshl_b32 s98, s38, 19
	s_add_u32 s16, s4, s98
	s_addc_u32 s17, s5, 0
	s_lshl_b32 s98, s39, 19
	s_add_u32 s18, s6, s98
	s_addc_u32 s19, s7, 0
	s_add_u32 m0, s27, 0
	v_mfma_f32_32x32x16_bf16 v[112:127], v[128:131], v[136:139], v[112:127]
	global_load_lds_dwordx4 v192, s[16:17]
	s_add_u32 m0, s27, 32768
	v_mfma_f32_32x32x16_bf16 v[48:63], v[132:135], v[136:139], v[48:63]
	global_load_lds_dwordx4 v192, s[18:19]
	s_add_u32 m0, s27, 8192
	v_mfma_f32_32x32x16_bf16 v[96:111], v[128:131], v[140:143], v[96:111]
	global_load_lds_dwordx4 v194, s[16:17]
	s_add_u32 m0, s27, 40960
	v_mfma_f32_32x32x16_bf16 v[32:47], v[132:135], v[140:143], v[32:47]
	global_load_lds_dwordx4 v194, s[18:19]
	s_add_u32 m0, s27, 16384
	v_mfma_f32_32x32x16_bf16 v[80:95], v[128:131], v[144:147], v[80:95]
	global_load_lds_dwordx4 v196, s[16:17]
	s_add_u32 m0, s27, 49152
	v_mfma_f32_32x32x16_bf16 v[16:31], v[132:135], v[144:147], v[16:31]
	global_load_lds_dwordx4 v196, s[18:19]
	s_add_u32 m0, s27, 24576
	v_mfma_f32_32x32x16_bf16 v[64:79], v[128:131], v[148:151], v[64:79]
	global_load_lds_dwordx4 v198, s[16:17]
	s_add_u32 m0, s27, 57344
	v_mfma_f32_32x32x16_bf16 v[0:15], v[132:135], v[148:151], v[0:15]
	global_load_lds_dwordx4 v198, s[18:19]
	s_branch .Lip11_full_join

.Lip11_full_join:
	ds_read_b128 v[128:131], v241
	ds_read_b128 v[136:139], v245
	ds_read_b128 v[132:135], v241 offset:4096
	ds_read_b128 v[140:143], v245 offset:4096
	ds_read_b128 v[144:147], v245 offset:8192
	ds_read_b128 v[148:151], v245 offset:12288
	s_waitcnt lgkmcnt(6)
	v_mfma_f32_32x32x16_bf16 v[112:127], v[160:163], v[168:171], v[112:127]
	v_mfma_f32_32x32x16_bf16 v[48:63], v[164:167], v[168:171], v[48:63]
	v_mfma_f32_32x32x16_bf16 v[96:111], v[160:163], v[172:175], v[96:111]
	v_mfma_f32_32x32x16_bf16 v[32:47], v[164:167], v[172:175], v[32:47]
	v_mfma_f32_32x32x16_bf16 v[80:95], v[160:163], v[176:179], v[80:95]
	v_mfma_f32_32x32x16_bf16 v[16:31], v[164:167], v[176:179], v[16:31]
	v_mfma_f32_32x32x16_bf16 v[64:79], v[160:163], v[180:183], v[64:79]
	v_mfma_f32_32x32x16_bf16 v[0:15], v[164:167], v[180:183], v[0:15]
	ds_read_b128 v[160:163], v242
	ds_read_b128 v[168:171], v246
	ds_read_b128 v[164:167], v242 offset:4096
	ds_read_b128 v[172:175], v246 offset:4096
	ds_read_b128 v[176:179], v246 offset:8192
	ds_read_b128 v[180:183], v246 offset:12288
	s_waitcnt lgkmcnt(6)
	v_mfma_f32_32x32x16_bf16 v[112:127], v[128:131], v[136:139], v[112:127]
	v_mfma_f32_32x32x16_bf16 v[48:63], v[132:135], v[136:139], v[48:63]
	v_mfma_f32_32x32x16_bf16 v[96:111], v[128:131], v[140:143], v[96:111]
	v_mfma_f32_32x32x16_bf16 v[32:47], v[132:135], v[140:143], v[32:47]
	v_mfma_f32_32x32x16_bf16 v[80:95], v[128:131], v[144:147], v[80:95]
	v_mfma_f32_32x32x16_bf16 v[16:31], v[132:135], v[144:147], v[16:31]
	v_mfma_f32_32x32x16_bf16 v[64:79], v[128:131], v[148:151], v[64:79]
	v_mfma_f32_32x32x16_bf16 v[0:15], v[132:135], v[148:151], v[0:15]
	ds_read_b128 v[128:131], v243
	ds_read_b128 v[136:139], v247
	ds_read_b128 v[132:135], v243 offset:4096
	ds_read_b128 v[140:143], v247 offset:4096
	ds_read_b128 v[144:147], v247 offset:8192
	ds_read_b128 v[148:151], v247 offset:12288
	s_waitcnt lgkmcnt(6)
	v_mfma_f32_32x32x16_bf16 v[112:127], v[160:163], v[168:171], v[112:127]
	v_mfma_f32_32x32x16_bf16 v[48:63], v[164:167], v[168:171], v[48:63]
	v_mfma_f32_32x32x16_bf16 v[96:111], v[160:163], v[172:175], v[96:111]
	v_mfma_f32_32x32x16_bf16 v[32:47], v[164:167], v[172:175], v[32:47]
	v_mfma_f32_32x32x16_bf16 v[80:95], v[160:163], v[176:179], v[80:95]
	v_mfma_f32_32x32x16_bf16 v[16:31], v[164:167], v[176:179], v[16:31]
	v_mfma_f32_32x32x16_bf16 v[64:79], v[160:163], v[180:183], v[64:79]
	v_mfma_f32_32x32x16_bf16 v[0:15], v[164:167], v[180:183], v[0:15]
	s_waitcnt vmcnt(0) lgkmcnt(0)
	s_barrier
	v_mfma_f32_32x32x16_bf16 v[112:127], v[128:131], v[136:139], v[112:127]
	v_mfma_f32_32x32x16_bf16 v[48:63], v[132:135], v[136:139], v[48:63]
	v_mfma_f32_32x32x16_bf16 v[96:111], v[128:131], v[140:143], v[96:111]
	v_mfma_f32_32x32x16_bf16 v[32:47], v[132:135], v[140:143], v[32:47]
	v_mfma_f32_32x32x16_bf16 v[80:95], v[128:131], v[144:147], v[80:95]
	v_mfma_f32_32x32x16_bf16 v[16:31], v[132:135], v[144:147], v[16:31]
	v_mfma_f32_32x32x16_bf16 v[64:79], v[128:131], v[148:151], v[64:79]
	v_mfma_f32_32x32x16_bf16 v[0:15], v[132:135], v[148:151], v[0:15]
	s_branch .Lip11_epi
.Lip11_light:
	s_cmp_eq_u32 s31, 0
	s_cbranch_scc0 .Lip11_lload
	ds_read_b128 v[160:163], v184
	ds_read_b128 v[168:171], v188
	ds_read_b128 v[164:167], v184 offset:4096
	ds_read_b128 v[172:175], v188 offset:4096
	ds_read_b128 v[128:131], v185
	ds_read_b128 v[136:139], v189
	ds_read_b128 v[132:135], v185 offset:4096
	ds_read_b128 v[140:143], v189 offset:4096
	s_waitcnt lgkmcnt(4)
	v_mfma_f32_32x32x16_bf16 v[112:127], v[160:163], v[168:171], 0
	v_mfma_f32_32x32x16_bf16 v[48:63], v[164:167], v[168:171], 0
	v_mfma_f32_32x32x16_bf16 v[96:111], v[160:163], v[172:175], 0
	v_mfma_f32_32x32x16_bf16 v[32:47], v[164:167], v[172:175], 0
	ds_read_b128 v[160:163], v186
	ds_read_b128 v[168:171], v190
	ds_read_b128 v[164:167], v186 offset:4096
	ds_read_b128 v[172:175], v190 offset:4096
	s_waitcnt lgkmcnt(4)
	v_mfma_f32_32x32x16_bf16 v[112:127], v[128:131], v[136:139], v[112:127]
	v_mfma_f32_32x32x16_bf16 v[48:63], v[132:135], v[136:139], v[48:63]
	v_mfma_f32_32x32x16_bf16 v[96:111], v[128:131], v[140:143], v[96:111]
	v_mfma_f32_32x32x16_bf16 v[32:47], v[132:135], v[140:143], v[32:47]
	ds_read_b128 v[128:131], v187
	ds_read_b128 v[136:139], v191
	ds_read_b128 v[132:135], v187 offset:4096
	ds_read_b128 v[140:143], v191 offset:4096
	s_waitcnt lgkmcnt(4)
	v_mfma_f32_32x32x16_bf16 v[112:127], v[160:163], v[168:171], v[112:127]
	v_mfma_f32_32x32x16_bf16 v[48:63], v[164:167], v[168:171], v[48:63]
	v_mfma_f32_32x32x16_bf16 v[96:111], v[160:163], v[172:175], v[96:111]
	v_mfma_f32_32x32x16_bf16 v[32:47], v[164:167], v[172:175], v[32:47]
	s_waitcnt vmcnt(0) lgkmcnt(0)
	s_barrier
	ds_read_b128 v[160:163], v240
	ds_read_b128 v[168:171], v244
	ds_read_b128 v[164:167], v240 offset:4096
	ds_read_b128 v[172:175], v244 offset:4096
	s_add_u32 s20, s16, 256
	s_addc_u32 s21, s17, 0
	s_add_u32 s24, s18, 256
	s_addc_u32 s25, s19, 0
	s_add_u32 m0, s27, 0
	v_mfma_f32_32x32x16_bf16 v[112:127], v[128:131], v[136:139], v[112:127]
	global_load_lds_dwordx4 v192, s[20:21]
	s_add_u32 m0, s27, 32768
	v_mfma_f32_32x32x16_bf16 v[48:63], v[132:135], v[136:139], v[48:63]
	global_load_lds_dwordx4 v192, s[24:25]
	s_add_u32 m0, s27, 8192
	v_mfma_f32_32x32x16_bf16 v[96:111], v[128:131], v[140:143], v[96:111]
	global_load_lds_dwordx4 v194, s[20:21]
	s_add_u32 m0, s27, 40960
	v_mfma_f32_32x32x16_bf16 v[32:47], v[132:135], v[140:143], v[32:47]
	global_load_lds_dwordx4 v194, s[24:25]
	s_add_u32 m0, s27, 16384
	s_nop 0
	global_load_lds_dwordx4 v196, s[20:21]
	s_add_u32 m0, s27, 49152
	s_nop 0
	global_load_lds_dwordx4 v196, s[24:25]
	s_add_u32 m0, s27, 24576
	s_nop 0
	global_load_lds_dwordx4 v198, s[20:21]
	s_add_u32 m0, s27, 57344
	s_nop 0
	global_load_lds_dwordx4 v198, s[24:25]
	ds_read_b128 v[128:131], v241
	ds_read_b128 v[136:139], v245
	ds_read_b128 v[132:135], v241 offset:4096
	ds_read_b128 v[140:143], v245 offset:4096
	s_waitcnt lgkmcnt(4)
	v_mfma_f32_32x32x16_bf16 v[112:127], v[160:163], v[168:171], v[112:127]
	v_mfma_f32_32x32x16_bf16 v[48:63], v[164:167], v[168:171], v[48:63]
	v_mfma_f32_32x32x16_bf16 v[96:111], v[160:163], v[172:175], v[96:111]
	v_mfma_f32_32x32x16_bf16 v[32:47], v[164:167], v[172:175], v[32:47]
	ds_read_b128 v[160:163], v242
	ds_read_b128 v[168:171], v246
	ds_read_b128 v[164:167], v242 offset:4096
	ds_read_b128 v[172:175], v246 offset:4096
	s_waitcnt lgkmcnt(4)
	v_mfma_f32_32x32x16_bf16 v[112:127], v[128:131], v[136:139], v[112:127]
	v_mfma_f32_32x32x16_bf16 v[48:63], v[132:135], v[136:139], v[48:63]
	v_mfma_f32_32x32x16_bf16 v[96:111], v[128:131], v[140:143], v[96:111]
	v_mfma_f32_32x32x16_bf16 v[32:47], v[132:135], v[140:143], v[32:47]
	ds_read_b128 v[128:131], v243
	ds_read_b128 v[136:139], v247
	ds_read_b128 v[132:135], v243 offset:4096
	ds_read_b128 v[140:143], v247 offset:4096
	s_waitcnt lgkmcnt(4)
	v_mfma_f32_32x32x16_bf16 v[112:127], v[160:163], v[168:171], v[112:127]
	v_mfma_f32_32x32x16_bf16 v[48:63], v[164:167], v[168:171], v[48:63]
	v_mfma_f32_32x32x16_bf16 v[96:111], v[160:163], v[172:175], v[96:111]
	v_mfma_f32_32x32x16_bf16 v[32:47], v[164:167], v[172:175], v[32:47]
	s_waitcnt vmcnt(0) lgkmcnt(0)
	s_barrier
	ds_read_b128 v[160:163], v184
	ds_read_b128 v[168:171], v188
	ds_read_b128 v[164:167], v184 offset:4096
	ds_read_b128 v[172:175], v188 offset:4096
	s_add_u32 s20, s16, 384
	s_addc_u32 s21, s17, 0
	s_add_u32 s24, s18, 384
	s_addc_u32 s25, s19, 0
	s_add_u32 m0, s27, 65536
	v_mfma_f32_32x32x16_bf16 v[112:127], v[128:131], v[136:139], v[112:127]
	global_load_lds_dwordx4 v192, s[20:21]
	s_add_u32 m0, s27, 98304
	v_mfma_f32_32x32x16_bf16 v[48:63], v[132:135], v[136:139], v[48:63]
	global_load_lds_dwordx4 v192, s[24:25]
	s_add_u32 m0, s27, 73728
	v_mfma_f32_32x32x16_bf16 v[96:111], v[128:131], v[140:143], v[96:111]
	global_load_lds_dwordx4 v194, s[20:21]
	s_add_u32 m0, s27, 106496
	v_mfma_f32_32x32x16_bf16 v[32:47], v[132:135], v[140:143], v[32:47]
	global_load_lds_dwordx4 v194, s[24:25]
	s_add_u32 m0, s27, 81920
	s_nop 0
	global_load_lds_dwordx4 v196, s[20:21]
	s_add_u32 m0, s27, 114688
	s_nop 0
	global_load_lds_dwordx4 v196, s[24:25]
	s_add_u32 m0, s27, 90112
	s_nop 0
	global_load_lds_dwordx4 v198, s[20:21]
	s_add_u32 m0, s27, 122880
	s_nop 0
	global_load_lds_dwordx4 v198, s[24:25]
	ds_read_b128 v[128:131], v185
	ds_read_b128 v[136:139], v189
	ds_read_b128 v[132:135], v185 offset:4096
	ds_read_b128 v[140:143], v189 offset:4096
	s_waitcnt lgkmcnt(4)
	v_mfma_f32_32x32x16_bf16 v[112:127], v[160:163], v[168:171], v[112:127]
	v_mfma_f32_32x32x16_bf16 v[48:63], v[164:167], v[168:171], v[48:63]
	v_mfma_f32_32x32x16_bf16 v[96:111], v[160:163], v[172:175], v[96:111]
	v_mfma_f32_32x32x16_bf16 v[32:47], v[164:167], v[172:175], v[32:47]
	ds_read_b128 v[160:163], v186
	ds_read_b128 v[168:171], v190
	ds_read_b128 v[164:167], v186 offset:4096
	ds_read_b128 v[172:175], v190 offset:4096
	s_waitcnt lgkmcnt(4)
	v_mfma_f32_32x32x16_bf16 v[112:127], v[128:131], v[136:139], v[112:127]
	v_mfma_f32_32x32x16_bf16 v[48:63], v[132:135], v[136:139], v[48:63]
	v_mfma_f32_32x32x16_bf16 v[96:111], v[128:131], v[140:143], v[96:111]
	v_mfma_f32_32x32x16_bf16 v[32:47], v[132:135], v[140:143], v[32:47]
	ds_read_b128 v[128:131], v187
	ds_read_b128 v[136:139], v191
	ds_read_b128 v[132:135], v187 offset:4096
	ds_read_b128 v[140:143], v191 offset:4096
	s_waitcnt lgkmcnt(4)
	v_mfma_f32_32x32x16_bf16 v[112:127], v[160:163], v[168:171], v[112:127]
	v_mfma_f32_32x32x16_bf16 v[48:63], v[164:167], v[168:171], v[48:63]
	v_mfma_f32_32x32x16_bf16 v[96:111], v[160:163], v[172:175], v[96:111]
	v_mfma_f32_32x32x16_bf16 v[32:47], v[164:167], v[172:175], v[32:47]
	s_waitcnt vmcnt(0) lgkmcnt(0)
	s_barrier
	ds_read_b128 v[160:163], v240
	ds_read_b128 v[168:171], v244
	ds_read_b128 v[164:167], v240 offset:4096
	ds_read_b128 v[172:175], v244 offset:4096
	s_add_u32 s20, s16, 512
	s_addc_u32 s21, s17, 0
	s_add_u32 s24, s18, 512
	s_addc_u32 s25, s19, 0
	s_add_u32 m0, s27, 0
	v_mfma_f32_32x32x16_bf16 v[112:127], v[128:131], v[136:139], v[112:127]
	global_load_lds_dwordx4 v192, s[20:21]
	s_add_u32 m0, s27, 32768
	v_mfma_f32_32x32x16_bf16 v[48:63], v[132:135], v[136:139], v[48:63]
	global_load_lds_dwordx4 v192, s[24:25]
	s_add_u32 m0, s27, 8192
	v_mfma_f32_32x32x16_bf16 v[96:111], v[128:131], v[140:143], v[96:111]
	global_load_lds_dwordx4 v194, s[20:21]
	s_add_u32 m0, s27, 40960
	v_mfma_f32_32x32x16_bf16 v[32:47], v[132:135], v[140:143], v[32:47]
	global_load_lds_dwordx4 v194, s[24:25]
	s_add_u32 m0, s27, 16384
	s_nop 0
	global_load_lds_dwordx4 v196, s[20:21]
	s_add_u32 m0, s27, 49152
	s_nop 0
	global_load_lds_dwordx4 v196, s[24:25]
	s_add_u32 m0, s27, 24576
	s_nop 0
	global_load_lds_dwordx4 v198, s[20:21]
	s_add_u32 m0, s27, 57344
	s_nop 0
	global_load_lds_dwordx4 v198, s[24:25]
	ds_read_b128 v[128:131], v241
	ds_read_b128 v[136:139], v245
	ds_read_b128 v[132:135], v241 offset:4096
	ds_read_b128 v[140:143], v245 offset:4096
	s_waitcnt lgkmcnt(4)
	v_mfma_f32_32x32x16_bf16 v[112:127], v[160:163], v[168:171], v[112:127]
	v_mfma_f32_32x32x16_bf16 v[48:63], v[164:167], v[168:171], v[48:63]
	v_mfma_f32_32x32x16_bf16 v[96:111], v[160:163], v[172:175], v[96:111]
	v_mfma_f32_32x32x16_bf16 v[32:47], v[164:167], v[172:175], v[32:47]
	ds_read_b128 v[160:163], v242
	ds_read_b128 v[168:171], v246
	ds_read_b128 v[164:167], v242 offset:4096
	ds_read_b128 v[172:175], v246 offset:4096
	s_waitcnt lgkmcnt(4)
	v_mfma_f32_32x32x16_bf16 v[112:127], v[128:131], v[136:139], v[112:127]
	v_mfma_f32_32x32x16_bf16 v[48:63], v[132:135], v[136:139], v[48:63]
	v_mfma_f32_32x32x16_bf16 v[96:111], v[128:131], v[140:143], v[96:111]
	v_mfma_f32_32x32x16_bf16 v[32:47], v[132:135], v[140:143], v[32:47]
	ds_read_b128 v[128:131], v243
	ds_read_b128 v[136:139], v247
	ds_read_b128 v[132:135], v243 offset:4096
	ds_read_b128 v[140:143], v247 offset:4096
	s_waitcnt lgkmcnt(4)
	v_mfma_f32_32x32x16_bf16 v[112:127], v[160:163], v[168:171], v[112:127]
	v_mfma_f32_32x32x16_bf16 v[48:63], v[164:167], v[168:171], v[48:63]
	v_mfma_f32_32x32x16_bf16 v[96:111], v[160:163], v[172:175], v[96:111]
	v_mfma_f32_32x32x16_bf16 v[32:47], v[164:167], v[172:175], v[32:47]
	s_waitcnt vmcnt(0) lgkmcnt(0)
	s_barrier
	ds_read_b128 v[160:163], v184
	ds_read_b128 v[168:171], v188
	ds_read_b128 v[164:167], v184 offset:4096
	ds_read_b128 v[172:175], v188 offset:4096
	s_add_u32 s20, s16, 640
	s_addc_u32 s21, s17, 0
	s_add_u32 s24, s18, 640
	s_addc_u32 s25, s19, 0
	s_add_u32 m0, s27, 65536
	v_mfma_f32_32x32x16_bf16 v[112:127], v[128:131], v[136:139], v[112:127]
	global_load_lds_dwordx4 v192, s[20:21]
	s_add_u32 m0, s27, 98304
	v_mfma_f32_32x32x16_bf16 v[48:63], v[132:135], v[136:139], v[48:63]
	global_load_lds_dwordx4 v192, s[24:25]
	s_add_u32 m0, s27, 73728
	v_mfma_f32_32x32x16_bf16 v[96:111], v[128:131], v[140:143], v[96:111]
	global_load_lds_dwordx4 v194, s[20:21]
	s_add_u32 m0, s27, 106496
	v_mfma_f32_32x32x16_bf16 v[32:47], v[132:135], v[140:143], v[32:47]
	global_load_lds_dwordx4 v194, s[24:25]
	s_add_u32 m0, s27, 81920
	s_nop 0
	global_load_lds_dwordx4 v196, s[20:21]
	s_add_u32 m0, s27, 114688
	s_nop 0
	global_load_lds_dwordx4 v196, s[24:25]
	s_add_u32 m0, s27, 90112
	s_nop 0
	global_load_lds_dwordx4 v198, s[20:21]
	s_add_u32 m0, s27, 122880
	s_nop 0
	global_load_lds_dwordx4 v198, s[24:25]
	ds_read_b128 v[128:131], v185
	ds_read_b128 v[136:139], v189
	ds_read_b128 v[132:135], v185 offset:4096
	ds_read_b128 v[140:143], v189 offset:4096
	s_waitcnt lgkmcnt(4)
	v_mfma_f32_32x32x16_bf16 v[112:127], v[160:163], v[168:171], v[112:127]
	v_mfma_f32_32x32x16_bf16 v[48:63], v[164:167], v[168:171], v[48:63]
	v_mfma_f32_32x32x16_bf16 v[96:111], v[160:163], v[172:175], v[96:111]
	v_mfma_f32_32x32x16_bf16 v[32:47], v[164:167], v[172:175], v[32:47]
	ds_read_b128 v[160:163], v186
	ds_read_b128 v[168:171], v190
	ds_read_b128 v[164:167], v186 offset:4096
	ds_read_b128 v[172:175], v190 offset:4096
	s_waitcnt lgkmcnt(4)
	v_mfma_f32_32x32x16_bf16 v[112:127], v[128:131], v[136:139], v[112:127]
	v_mfma_f32_32x32x16_bf16 v[48:63], v[132:135], v[136:139], v[48:63]
	v_mfma_f32_32x32x16_bf16 v[96:111], v[128:131], v[140:143], v[96:111]
	v_mfma_f32_32x32x16_bf16 v[32:47], v[132:135], v[140:143], v[32:47]
	ds_read_b128 v[128:131], v187
	ds_read_b128 v[136:139], v191
	ds_read_b128 v[132:135], v187 offset:4096
	ds_read_b128 v[140:143], v191 offset:4096
	s_waitcnt lgkmcnt(4)
	v_mfma_f32_32x32x16_bf16 v[112:127], v[160:163], v[168:171], v[112:127]
	v_mfma_f32_32x32x16_bf16 v[48:63], v[164:167], v[168:171], v[48:63]
	v_mfma_f32_32x32x16_bf16 v[96:111], v[160:163], v[172:175], v[96:111]
	v_mfma_f32_32x32x16_bf16 v[32:47], v[164:167], v[172:175], v[32:47]
	s_waitcnt vmcnt(0) lgkmcnt(0)
	s_barrier
	ds_read_b128 v[160:163], v240
	ds_read_b128 v[168:171], v244
	ds_read_b128 v[164:167], v240 offset:4096
	ds_read_b128 v[172:175], v244 offset:4096
	s_add_u32 s20, s16, 768
	s_addc_u32 s21, s17, 0
	s_add_u32 s24, s18, 768
	s_addc_u32 s25, s19, 0
	s_add_u32 m0, s27, 0
	v_mfma_f32_32x32x16_bf16 v[112:127], v[128:131], v[136:139], v[112:127]
	global_load_lds_dwordx4 v192, s[20:21]
	s_add_u32 m0, s27, 32768
	v_mfma_f32_32x32x16_bf16 v[48:63], v[132:135], v[136:139], v[48:63]
	global_load_lds_dwordx4 v192, s[24:25]
	s_add_u32 m0, s27, 8192
	v_mfma_f32_32x32x16_bf16 v[96:111], v[128:131], v[140:143], v[96:111]
	global_load_lds_dwordx4 v194, s[20:21]
	s_add_u32 m0, s27, 40960
	v_mfma_f32_32x32x16_bf16 v[32:47], v[132:135], v[140:143], v[32:47]
	global_load_lds_dwordx4 v194, s[24:25]
	s_add_u32 m0, s27, 16384
	s_nop 0
	global_load_lds_dwordx4 v196, s[20:21]
	s_add_u32 m0, s27, 49152
	s_nop 0
	global_load_lds_dwordx4 v196, s[24:25]
	s_add_u32 m0, s27, 24576
	s_nop 0
	global_load_lds_dwordx4 v198, s[20:21]
	s_add_u32 m0, s27, 57344
	s_nop 0
	global_load_lds_dwordx4 v198, s[24:25]
	ds_read_b128 v[128:131], v241
	ds_read_b128 v[136:139], v245
	ds_read_b128 v[132:135], v241 offset:4096
	ds_read_b128 v[140:143], v245 offset:4096
	s_waitcnt lgkmcnt(4)
	v_mfma_f32_32x32x16_bf16 v[112:127], v[160:163], v[168:171], v[112:127]
	v_mfma_f32_32x32x16_bf16 v[48:63], v[164:167], v[168:171], v[48:63]
	v_mfma_f32_32x32x16_bf16 v[96:111], v[160:163], v[172:175], v[96:111]
	v_mfma_f32_32x32x16_bf16 v[32:47], v[164:167], v[172:175], v[32:47]
	ds_read_b128 v[160:163], v242
	ds_read_b128 v[168:171], v246
	ds_read_b128 v[164:167], v242 offset:4096
	ds_read_b128 v[172:175], v246 offset:4096
	s_waitcnt lgkmcnt(4)
	v_mfma_f32_32x32x16_bf16 v[112:127], v[128:131], v[136:139], v[112:127]
	v_mfma_f32_32x32x16_bf16 v[48:63], v[132:135], v[136:139], v[48:63]
	v_mfma_f32_32x32x16_bf16 v[96:111], v[128:131], v[140:143], v[96:111]
	v_mfma_f32_32x32x16_bf16 v[32:47], v[132:135], v[140:143], v[32:47]
	ds_read_b128 v[128:131], v243
	ds_read_b128 v[136:139], v247
	ds_read_b128 v[132:135], v243 offset:4096
	ds_read_b128 v[140:143], v247 offset:4096
	s_waitcnt lgkmcnt(4)
	v_mfma_f32_32x32x16_bf16 v[112:127], v[160:163], v[168:171], v[112:127]
	v_mfma_f32_32x32x16_bf16 v[48:63], v[164:167], v[168:171], v[48:63]
	v_mfma_f32_32x32x16_bf16 v[96:111], v[160:163], v[172:175], v[96:111]
	v_mfma_f32_32x32x16_bf16 v[32:47], v[164:167], v[172:175], v[32:47]
	s_waitcnt vmcnt(0) lgkmcnt(0)
	s_barrier
	ds_read_b128 v[160:163], v184
	ds_read_b128 v[168:171], v188
	ds_read_b128 v[164:167], v184 offset:4096
	ds_read_b128 v[172:175], v188 offset:4096
	s_add_u32 s20, s16, 896
	s_addc_u32 s21, s17, 0
	s_add_u32 s24, s18, 896
	s_addc_u32 s25, s19, 0
	s_add_u32 m0, s27, 65536
	v_mfma_f32_32x32x16_bf16 v[112:127], v[128:131], v[136:139], v[112:127]
	global_load_lds_dwordx4 v192, s[20:21]
	s_add_u32 m0, s27, 98304
	v_mfma_f32_32x32x16_bf16 v[48:63], v[132:135], v[136:139], v[48:63]
	global_load_lds_dwordx4 v192, s[24:25]
	s_add_u32 m0, s27, 73728
	v_mfma_f32_32x32x16_bf16 v[96:111], v[128:131], v[140:143], v[96:111]
	global_load_lds_dwordx4 v194, s[20:21]
	s_add_u32 m0, s27, 106496
	v_mfma_f32_32x32x16_bf16 v[32:47], v[132:135], v[140:143], v[32:47]
	global_load_lds_dwordx4 v194, s[24:25]
	s_add_u32 m0, s27, 81920
	s_nop 0
	global_load_lds_dwordx4 v196, s[20:21]
	s_add_u32 m0, s27, 114688
	s_nop 0
	global_load_lds_dwordx4 v196, s[24:25]
	s_add_u32 m0, s27, 90112
	s_nop 0
	global_load_lds_dwordx4 v198, s[20:21]
	s_add_u32 m0, s27, 122880
	s_nop 0
	global_load_lds_dwordx4 v198, s[24:25]
	ds_read_b128 v[128:131], v185
	ds_read_b128 v[136:139], v189
	ds_read_b128 v[132:135], v185 offset:4096
	ds_read_b128 v[140:143], v189 offset:4096
	s_waitcnt lgkmcnt(4)
	v_mfma_f32_32x32x16_bf16 v[112:127], v[160:163], v[168:171], v[112:127]
	v_mfma_f32_32x32x16_bf16 v[48:63], v[164:167], v[168:171], v[48:63]
	v_mfma_f32_32x32x16_bf16 v[96:111], v[160:163], v[172:175], v[96:111]
	v_mfma_f32_32x32x16_bf16 v[32:47], v[164:167], v[172:175], v[32:47]
	ds_read_b128 v[160:163], v186
	ds_read_b128 v[168:171], v190
	ds_read_b128 v[164:167], v186 offset:4096
	ds_read_b128 v[172:175], v190 offset:4096
	s_waitcnt lgkmcnt(4)
	v_mfma_f32_32x32x16_bf16 v[112:127], v[128:131], v[136:139], v[112:127]
	v_mfma_f32_32x32x16_bf16 v[48:63], v[132:135], v[136:139], v[48:63]
	v_mfma_f32_32x32x16_bf16 v[96:111], v[128:131], v[140:143], v[96:111]
	v_mfma_f32_32x32x16_bf16 v[32:47], v[132:135], v[140:143], v[32:47]
	ds_read_b128 v[128:131], v187
	ds_read_b128 v[136:139], v191
	ds_read_b128 v[132:135], v187 offset:4096
	ds_read_b128 v[140:143], v191 offset:4096
	s_waitcnt lgkmcnt(4)
	v_mfma_f32_32x32x16_bf16 v[112:127], v[160:163], v[168:171], v[112:127]
	v_mfma_f32_32x32x16_bf16 v[48:63], v[164:167], v[168:171], v[48:63]
	v_mfma_f32_32x32x16_bf16 v[96:111], v[160:163], v[172:175], v[96:111]
	v_mfma_f32_32x32x16_bf16 v[32:47], v[164:167], v[172:175], v[32:47]
	s_waitcnt vmcnt(0) lgkmcnt(0)
	s_barrier
	ds_read_b128 v[160:163], v240
	ds_read_b128 v[168:171], v244
	ds_read_b128 v[164:167], v240 offset:4096
	ds_read_b128 v[172:175], v244 offset:4096
	s_add_u32 s20, s16, 1024
	s_addc_u32 s21, s17, 0
	s_add_u32 s24, s18, 1024
	s_addc_u32 s25, s19, 0
	s_add_u32 m0, s27, 0
	v_mfma_f32_32x32x16_bf16 v[112:127], v[128:131], v[136:139], v[112:127]
	global_load_lds_dwordx4 v192, s[20:21]
	s_add_u32 m0, s27, 32768
	v_mfma_f32_32x32x16_bf16 v[48:63], v[132:135], v[136:139], v[48:63]
	global_load_lds_dwordx4 v192, s[24:25]
	s_add_u32 m0, s27, 8192
	v_mfma_f32_32x32x16_bf16 v[96:111], v[128:131], v[140:143], v[96:111]
	global_load_lds_dwordx4 v194, s[20:21]
	s_add_u32 m0, s27, 40960
	v_mfma_f32_32x32x16_bf16 v[32:47], v[132:135], v[140:143], v[32:47]
	global_load_lds_dwordx4 v194, s[24:25]
	s_add_u32 m0, s27, 16384
	s_nop 0
	global_load_lds_dwordx4 v196, s[20:21]
	s_add_u32 m0, s27, 49152
	s_nop 0
	global_load_lds_dwordx4 v196, s[24:25]
	s_add_u32 m0, s27, 24576
	s_nop 0
	global_load_lds_dwordx4 v198, s[20:21]
	s_add_u32 m0, s27, 57344
	s_nop 0
	global_load_lds_dwordx4 v198, s[24:25]
	ds_read_b128 v[128:131], v241
	ds_read_b128 v[136:139], v245
	ds_read_b128 v[132:135], v241 offset:4096
	ds_read_b128 v[140:143], v245 offset:4096
	s_waitcnt lgkmcnt(4)
	v_mfma_f32_32x32x16_bf16 v[112:127], v[160:163], v[168:171], v[112:127]
	v_mfma_f32_32x32x16_bf16 v[48:63], v[164:167], v[168:171], v[48:63]
	v_mfma_f32_32x32x16_bf16 v[96:111], v[160:163], v[172:175], v[96:111]
	v_mfma_f32_32x32x16_bf16 v[32:47], v[164:167], v[172:175], v[32:47]
	ds_read_b128 v[160:163], v242
	ds_read_b128 v[168:171], v246
	ds_read_b128 v[164:167], v242 offset:4096
	ds_read_b128 v[172:175], v246 offset:4096
	s_waitcnt lgkmcnt(4)
	v_mfma_f32_32x32x16_bf16 v[112:127], v[128:131], v[136:139], v[112:127]
	v_mfma_f32_32x32x16_bf16 v[48:63], v[132:135], v[136:139], v[48:63]
	v_mfma_f32_32x32x16_bf16 v[96:111], v[128:131], v[140:143], v[96:111]
	v_mfma_f32_32x32x16_bf16 v[32:47], v[132:135], v[140:143], v[32:47]
	ds_read_b128 v[128:131], v243
	ds_read_b128 v[136:139], v247
	ds_read_b128 v[132:135], v243 offset:4096
	ds_read_b128 v[140:143], v247 offset:4096
	s_waitcnt lgkmcnt(4)
	v_mfma_f32_32x32x16_bf16 v[112:127], v[160:163], v[168:171], v[112:127]
	v_mfma_f32_32x32x16_bf16 v[48:63], v[164:167], v[168:171], v[48:63]
	v_mfma_f32_32x32x16_bf16 v[96:111], v[160:163], v[172:175], v[96:111]
	v_mfma_f32_32x32x16_bf16 v[32:47], v[164:167], v[172:175], v[32:47]
	s_waitcnt vmcnt(0) lgkmcnt(0)
	s_barrier
	ds_read_b128 v[160:163], v184
	ds_read_b128 v[168:171], v188
	ds_read_b128 v[164:167], v184 offset:4096
	ds_read_b128 v[172:175], v188 offset:4096
	s_add_u32 s20, s16, 1152
	s_addc_u32 s21, s17, 0
	s_add_u32 s24, s18, 1152
	s_addc_u32 s25, s19, 0
	s_add_u32 m0, s27, 65536
	v_mfma_f32_32x32x16_bf16 v[112:127], v[128:131], v[136:139], v[112:127]
	global_load_lds_dwordx4 v192, s[20:21]
	s_add_u32 m0, s27, 98304
	v_mfma_f32_32x32x16_bf16 v[48:63], v[132:135], v[136:139], v[48:63]
	global_load_lds_dwordx4 v192, s[24:25]
	s_add_u32 m0, s27, 73728
	v_mfma_f32_32x32x16_bf16 v[96:111], v[128:131], v[140:143], v[96:111]
	global_load_lds_dwordx4 v194, s[20:21]
	s_add_u32 m0, s27, 106496
	v_mfma_f32_32x32x16_bf16 v[32:47], v[132:135], v[140:143], v[32:47]
	global_load_lds_dwordx4 v194, s[24:25]
	s_add_u32 m0, s27, 81920
	s_nop 0
	global_load_lds_dwordx4 v196, s[20:21]
	s_add_u32 m0, s27, 114688
	s_nop 0
	global_load_lds_dwordx4 v196, s[24:25]
	s_add_u32 m0, s27, 90112
	s_nop 0
	global_load_lds_dwordx4 v198, s[20:21]
	s_add_u32 m0, s27, 122880
	s_nop 0
	global_load_lds_dwordx4 v198, s[24:25]
	ds_read_b128 v[128:131], v185
	ds_read_b128 v[136:139], v189
	ds_read_b128 v[132:135], v185 offset:4096
	ds_read_b128 v[140:143], v189 offset:4096
	s_waitcnt lgkmcnt(4)
	v_mfma_f32_32x32x16_bf16 v[112:127], v[160:163], v[168:171], v[112:127]
	v_mfma_f32_32x32x16_bf16 v[48:63], v[164:167], v[168:171], v[48:63]
	v_mfma_f32_32x32x16_bf16 v[96:111], v[160:163], v[172:175], v[96:111]
	v_mfma_f32_32x32x16_bf16 v[32:47], v[164:167], v[172:175], v[32:47]
	ds_read_b128 v[160:163], v186
	ds_read_b128 v[168:171], v190
	ds_read_b128 v[164:167], v186 offset:4096
	ds_read_b128 v[172:175], v190 offset:4096
	s_waitcnt lgkmcnt(4)
	v_mfma_f32_32x32x16_bf16 v[112:127], v[128:131], v[136:139], v[112:127]
	v_mfma_f32_32x32x16_bf16 v[48:63], v[132:135], v[136:139], v[48:63]
	v_mfma_f32_32x32x16_bf16 v[96:111], v[128:131], v[140:143], v[96:111]
	v_mfma_f32_32x32x16_bf16 v[32:47], v[132:135], v[140:143], v[32:47]
	ds_read_b128 v[128:131], v187
	ds_read_b128 v[136:139], v191
	ds_read_b128 v[132:135], v187 offset:4096
	ds_read_b128 v[140:143], v191 offset:4096
	s_waitcnt lgkmcnt(4)
	v_mfma_f32_32x32x16_bf16 v[112:127], v[160:163], v[168:171], v[112:127]
	v_mfma_f32_32x32x16_bf16 v[48:63], v[164:167], v[168:171], v[48:63]
	v_mfma_f32_32x32x16_bf16 v[96:111], v[160:163], v[172:175], v[96:111]
	v_mfma_f32_32x32x16_bf16 v[32:47], v[164:167], v[172:175], v[32:47]
	s_waitcnt vmcnt(0) lgkmcnt(0)
	s_barrier
	ds_read_b128 v[160:163], v240
	ds_read_b128 v[168:171], v244
	ds_read_b128 v[164:167], v240 offset:4096
	ds_read_b128 v[172:175], v244 offset:4096
	s_add_u32 s20, s16, 1280
	s_addc_u32 s21, s17, 0
	s_add_u32 s24, s18, 1280
	s_addc_u32 s25, s19, 0
	s_add_u32 m0, s27, 0
	v_mfma_f32_32x32x16_bf16 v[112:127], v[128:131], v[136:139], v[112:127]
	global_load_lds_dwordx4 v192, s[20:21]
	s_add_u32 m0, s27, 32768
	v_mfma_f32_32x32x16_bf16 v[48:63], v[132:135], v[136:139], v[48:63]
	global_load_lds_dwordx4 v192, s[24:25]
	s_add_u32 m0, s27, 8192
	v_mfma_f32_32x32x16_bf16 v[96:111], v[128:131], v[140:143], v[96:111]
	global_load_lds_dwordx4 v194, s[20:21]
	s_add_u32 m0, s27, 40960
	v_mfma_f32_32x32x16_bf16 v[32:47], v[132:135], v[140:143], v[32:47]
	global_load_lds_dwordx4 v194, s[24:25]
	s_add_u32 m0, s27, 16384
	s_nop 0
	global_load_lds_dwordx4 v196, s[20:21]
	s_add_u32 m0, s27, 49152
	s_nop 0
	global_load_lds_dwordx4 v196, s[24:25]
	s_add_u32 m0, s27, 24576
	s_nop 0
	global_load_lds_dwordx4 v198, s[20:21]
	s_add_u32 m0, s27, 57344
	s_nop 0
	global_load_lds_dwordx4 v198, s[24:25]
	ds_read_b128 v[128:131], v241
	ds_read_b128 v[136:139], v245
	ds_read_b128 v[132:135], v241 offset:4096
	ds_read_b128 v[140:143], v245 offset:4096
	s_waitcnt lgkmcnt(4)
	v_mfma_f32_32x32x16_bf16 v[112:127], v[160:163], v[168:171], v[112:127]
	v_mfma_f32_32x32x16_bf16 v[48:63], v[164:167], v[168:171], v[48:63]
	v_mfma_f32_32x32x16_bf16 v[96:111], v[160:163], v[172:175], v[96:111]
	v_mfma_f32_32x32x16_bf16 v[32:47], v[164:167], v[172:175], v[32:47]
	ds_read_b128 v[160:163], v242
	ds_read_b128 v[168:171], v246
	ds_read_b128 v[164:167], v242 offset:4096
	ds_read_b128 v[172:175], v246 offset:4096
	s_waitcnt lgkmcnt(4)
	v_mfma_f32_32x32x16_bf16 v[112:127], v[128:131], v[136:139], v[112:127]
	v_mfma_f32_32x32x16_bf16 v[48:63], v[132:135], v[136:139], v[48:63]
	v_mfma_f32_32x32x16_bf16 v[96:111], v[128:131], v[140:143], v[96:111]
	v_mfma_f32_32x32x16_bf16 v[32:47], v[132:135], v[140:143], v[32:47]
	ds_read_b128 v[128:131], v243
	ds_read_b128 v[136:139], v247
	ds_read_b128 v[132:135], v243 offset:4096
	ds_read_b128 v[140:143], v247 offset:4096
	s_waitcnt lgkmcnt(4)
	v_mfma_f32_32x32x16_bf16 v[112:127], v[160:163], v[168:171], v[112:127]
	v_mfma_f32_32x32x16_bf16 v[48:63], v[164:167], v[168:171], v[48:63]
	v_mfma_f32_32x32x16_bf16 v[96:111], v[160:163], v[172:175], v[96:111]
	v_mfma_f32_32x32x16_bf16 v[32:47], v[164:167], v[172:175], v[32:47]
	s_waitcnt vmcnt(0) lgkmcnt(0)
	s_barrier
	ds_read_b128 v[160:163], v184
	ds_read_b128 v[168:171], v188
	ds_read_b128 v[164:167], v184 offset:4096
	ds_read_b128 v[172:175], v188 offset:4096
	s_add_u32 s20, s16, 1408
	s_addc_u32 s21, s17, 0
	s_add_u32 s24, s18, 1408
	s_addc_u32 s25, s19, 0
	s_add_u32 m0, s27, 65536
	v_mfma_f32_32x32x16_bf16 v[112:127], v[128:131], v[136:139], v[112:127]
	global_load_lds_dwordx4 v192, s[20:21]
	s_add_u32 m0, s27, 98304
	v_mfma_f32_32x32x16_bf16 v[48:63], v[132:135], v[136:139], v[48:63]
	global_load_lds_dwordx4 v192, s[24:25]
	s_add_u32 m0, s27, 73728
	v_mfma_f32_32x32x16_bf16 v[96:111], v[128:131], v[140:143], v[96:111]
	global_load_lds_dwordx4 v194, s[20:21]
	s_add_u32 m0, s27, 106496
	v_mfma_f32_32x32x16_bf16 v[32:47], v[132:135], v[140:143], v[32:47]
	global_load_lds_dwordx4 v194, s[24:25]
	s_add_u32 m0, s27, 81920
	s_nop 0
	global_load_lds_dwordx4 v196, s[20:21]
	s_add_u32 m0, s27, 114688
	s_nop 0
	global_load_lds_dwordx4 v196, s[24:25]
	s_add_u32 m0, s27, 90112
	s_nop 0
	global_load_lds_dwordx4 v198, s[20:21]
	s_add_u32 m0, s27, 122880
	s_nop 0
	global_load_lds_dwordx4 v198, s[24:25]
	ds_read_b128 v[128:131], v185
	ds_read_b128 v[136:139], v189
	ds_read_b128 v[132:135], v185 offset:4096
	ds_read_b128 v[140:143], v189 offset:4096
	s_waitcnt lgkmcnt(4)
	v_mfma_f32_32x32x16_bf16 v[112:127], v[160:163], v[168:171], v[112:127]
	v_mfma_f32_32x32x16_bf16 v[48:63], v[164:167], v[168:171], v[48:63]
	v_mfma_f32_32x32x16_bf16 v[96:111], v[160:163], v[172:175], v[96:111]
	v_mfma_f32_32x32x16_bf16 v[32:47], v[164:167], v[172:175], v[32:47]
	ds_read_b128 v[160:163], v186
	ds_read_b128 v[168:171], v190
	ds_read_b128 v[164:167], v186 offset:4096
	ds_read_b128 v[172:175], v190 offset:4096
	s_waitcnt lgkmcnt(4)
	v_mfma_f32_32x32x16_bf16 v[112:127], v[128:131], v[136:139], v[112:127]
	v_mfma_f32_32x32x16_bf16 v[48:63], v[132:135], v[136:139], v[48:63]
	v_mfma_f32_32x32x16_bf16 v[96:111], v[128:131], v[140:143], v[96:111]
	v_mfma_f32_32x32x16_bf16 v[32:47], v[132:135], v[140:143], v[32:47]
	ds_read_b128 v[128:131], v187
	ds_read_b128 v[136:139], v191
	ds_read_b128 v[132:135], v187 offset:4096
	ds_read_b128 v[140:143], v191 offset:4096
	s_waitcnt lgkmcnt(4)
	v_mfma_f32_32x32x16_bf16 v[112:127], v[160:163], v[168:171], v[112:127]
	v_mfma_f32_32x32x16_bf16 v[48:63], v[164:167], v[168:171], v[48:63]
	v_mfma_f32_32x32x16_bf16 v[96:111], v[160:163], v[172:175], v[96:111]
	v_mfma_f32_32x32x16_bf16 v[32:47], v[164:167], v[172:175], v[32:47]
	s_waitcnt vmcnt(0) lgkmcnt(0)
	s_barrier
	ds_read_b128 v[160:163], v240
	ds_read_b128 v[168:171], v244
	ds_read_b128 v[164:167], v240 offset:4096
	ds_read_b128 v[172:175], v244 offset:4096
	s_add_u32 s20, s16, 1536
	s_addc_u32 s21, s17, 0
	s_add_u32 s24, s18, 1536
	s_addc_u32 s25, s19, 0
	s_add_u32 m0, s27, 0
	v_mfma_f32_32x32x16_bf16 v[112:127], v[128:131], v[136:139], v[112:127]
	global_load_lds_dwordx4 v192, s[20:21]
	s_add_u32 m0, s27, 32768
	v_mfma_f32_32x32x16_bf16 v[48:63], v[132:135], v[136:139], v[48:63]
	global_load_lds_dwordx4 v192, s[24:25]
	s_add_u32 m0, s27, 8192
	v_mfma_f32_32x32x16_bf16 v[96:111], v[128:131], v[140:143], v[96:111]
	global_load_lds_dwordx4 v194, s[20:21]
	s_add_u32 m0, s27, 40960
	v_mfma_f32_32x32x16_bf16 v[32:47], v[132:135], v[140:143], v[32:47]
	global_load_lds_dwordx4 v194, s[24:25]
	s_add_u32 m0, s27, 16384
	s_nop 0
	global_load_lds_dwordx4 v196, s[20:21]
	s_add_u32 m0, s27, 49152
	s_nop 0
	global_load_lds_dwordx4 v196, s[24:25]
	s_add_u32 m0, s27, 24576
	s_nop 0
	global_load_lds_dwordx4 v198, s[20:21]
	s_add_u32 m0, s27, 57344
	s_nop 0
	global_load_lds_dwordx4 v198, s[24:25]
	ds_read_b128 v[128:131], v241
	ds_read_b128 v[136:139], v245
	ds_read_b128 v[132:135], v241 offset:4096
	ds_read_b128 v[140:143], v245 offset:4096
	s_waitcnt lgkmcnt(4)
	v_mfma_f32_32x32x16_bf16 v[112:127], v[160:163], v[168:171], v[112:127]
	v_mfma_f32_32x32x16_bf16 v[48:63], v[164:167], v[168:171], v[48:63]
	v_mfma_f32_32x32x16_bf16 v[96:111], v[160:163], v[172:175], v[96:111]
	v_mfma_f32_32x32x16_bf16 v[32:47], v[164:167], v[172:175], v[32:47]
	ds_read_b128 v[160:163], v242
	ds_read_b128 v[168:171], v246
	ds_read_b128 v[164:167], v242 offset:4096
	ds_read_b128 v[172:175], v246 offset:4096
	s_waitcnt lgkmcnt(4)
	v_mfma_f32_32x32x16_bf16 v[112:127], v[128:131], v[136:139], v[112:127]
	v_mfma_f32_32x32x16_bf16 v[48:63], v[132:135], v[136:139], v[48:63]
	v_mfma_f32_32x32x16_bf16 v[96:111], v[128:131], v[140:143], v[96:111]
	v_mfma_f32_32x32x16_bf16 v[32:47], v[132:135], v[140:143], v[32:47]
	ds_read_b128 v[128:131], v243
	ds_read_b128 v[136:139], v247
	ds_read_b128 v[132:135], v243 offset:4096
	ds_read_b128 v[140:143], v247 offset:4096
	s_waitcnt lgkmcnt(4)
	v_mfma_f32_32x32x16_bf16 v[112:127], v[160:163], v[168:171], v[112:127]
	v_mfma_f32_32x32x16_bf16 v[48:63], v[164:167], v[168:171], v[48:63]
	v_mfma_f32_32x32x16_bf16 v[96:111], v[160:163], v[172:175], v[96:111]
	v_mfma_f32_32x32x16_bf16 v[32:47], v[164:167], v[172:175], v[32:47]
	s_waitcnt vmcnt(0) lgkmcnt(0)
	s_barrier
	ds_read_b128 v[160:163], v184
	ds_read_b128 v[168:171], v188
	ds_read_b128 v[164:167], v184 offset:4096
	ds_read_b128 v[172:175], v188 offset:4096
	s_add_u32 s20, s16, 1664
	s_addc_u32 s21, s17, 0
	s_add_u32 s24, s18, 1664
	s_addc_u32 s25, s19, 0
	s_add_u32 m0, s27, 65536
	v_mfma_f32_32x32x16_bf16 v[112:127], v[128:131], v[136:139], v[112:127]
	global_load_lds_dwordx4 v192, s[20:21]
	s_add_u32 m0, s27, 98304
	v_mfma_f32_32x32x16_bf16 v[48:63], v[132:135], v[136:139], v[48:63]
	global_load_lds_dwordx4 v192, s[24:25]
	s_add_u32 m0, s27, 73728
	v_mfma_f32_32x32x16_bf16 v[96:111], v[128:131], v[140:143], v[96:111]
	global_load_lds_dwordx4 v194, s[20:21]
	s_add_u32 m0, s27, 106496
	v_mfma_f32_32x32x16_bf16 v[32:47], v[132:135], v[140:143], v[32:47]
	global_load_lds_dwordx4 v194, s[24:25]
	s_add_u32 m0, s27, 81920
	s_nop 0
	global_load_lds_dwordx4 v196, s[20:21]
	s_add_u32 m0, s27, 114688
	s_nop 0
	global_load_lds_dwordx4 v196, s[24:25]
	s_add_u32 m0, s27, 90112
	s_nop 0
	global_load_lds_dwordx4 v198, s[20:21]
	s_add_u32 m0, s27, 122880
	s_nop 0
	global_load_lds_dwordx4 v198, s[24:25]
	ds_read_b128 v[128:131], v185
	ds_read_b128 v[136:139], v189
	ds_read_b128 v[132:135], v185 offset:4096
	ds_read_b128 v[140:143], v189 offset:4096
	s_waitcnt lgkmcnt(4)
	v_mfma_f32_32x32x16_bf16 v[112:127], v[160:163], v[168:171], v[112:127]
	v_mfma_f32_32x32x16_bf16 v[48:63], v[164:167], v[168:171], v[48:63]
	v_mfma_f32_32x32x16_bf16 v[96:111], v[160:163], v[172:175], v[96:111]
	v_mfma_f32_32x32x16_bf16 v[32:47], v[164:167], v[172:175], v[32:47]
	ds_read_b128 v[160:163], v186
	ds_read_b128 v[168:171], v190
	ds_read_b128 v[164:167], v186 offset:4096
	ds_read_b128 v[172:175], v190 offset:4096
	s_waitcnt lgkmcnt(4)
	v_mfma_f32_32x32x16_bf16 v[112:127], v[128:131], v[136:139], v[112:127]
	v_mfma_f32_32x32x16_bf16 v[48:63], v[132:135], v[136:139], v[48:63]
	v_mfma_f32_32x32x16_bf16 v[96:111], v[128:131], v[140:143], v[96:111]
	v_mfma_f32_32x32x16_bf16 v[32:47], v[132:135], v[140:143], v[32:47]
	ds_read_b128 v[128:131], v187
	ds_read_b128 v[136:139], v191
	ds_read_b128 v[132:135], v187 offset:4096
	ds_read_b128 v[140:143], v191 offset:4096
	s_waitcnt lgkmcnt(4)
	v_mfma_f32_32x32x16_bf16 v[112:127], v[160:163], v[168:171], v[112:127]
	v_mfma_f32_32x32x16_bf16 v[48:63], v[164:167], v[168:171], v[48:63]
	v_mfma_f32_32x32x16_bf16 v[96:111], v[160:163], v[172:175], v[96:111]
	v_mfma_f32_32x32x16_bf16 v[32:47], v[164:167], v[172:175], v[32:47]
	s_waitcnt vmcnt(0) lgkmcnt(0)
	s_barrier
	ds_read_b128 v[160:163], v240
	ds_read_b128 v[168:171], v244
	ds_read_b128 v[164:167], v240 offset:4096
	ds_read_b128 v[172:175], v244 offset:4096
	s_add_u32 s20, s16, 1792
	s_addc_u32 s21, s17, 0
	s_add_u32 s24, s18, 1792
	s_addc_u32 s25, s19, 0
	s_add_u32 m0, s27, 0
	v_mfma_f32_32x32x16_bf16 v[112:127], v[128:131], v[136:139], v[112:127]
	global_load_lds_dwordx4 v192, s[20:21]
	s_add_u32 m0, s27, 32768
	v_mfma_f32_32x32x16_bf16 v[48:63], v[132:135], v[136:139], v[48:63]
	global_load_lds_dwordx4 v192, s[24:25]
	s_add_u32 m0, s27, 8192
	v_mfma_f32_32x32x16_bf16 v[96:111], v[128:131], v[140:143], v[96:111]
	global_load_lds_dwordx4 v194, s[20:21]
	s_add_u32 m0, s27, 40960
	v_mfma_f32_32x32x16_bf16 v[32:47], v[132:135], v[140:143], v[32:47]
	global_load_lds_dwordx4 v194, s[24:25]
	s_add_u32 m0, s27, 16384
	s_nop 0
	global_load_lds_dwordx4 v196, s[20:21]
	s_add_u32 m0, s27, 49152
	s_nop 0
	global_load_lds_dwordx4 v196, s[24:25]
	s_add_u32 m0, s27, 24576
	s_nop 0
	global_load_lds_dwordx4 v198, s[20:21]
	s_add_u32 m0, s27, 57344
	s_nop 0
	global_load_lds_dwordx4 v198, s[24:25]
	ds_read_b128 v[128:131], v241
	ds_read_b128 v[136:139], v245
	ds_read_b128 v[132:135], v241 offset:4096
	ds_read_b128 v[140:143], v245 offset:4096
	s_waitcnt lgkmcnt(4)
	v_mfma_f32_32x32x16_bf16 v[112:127], v[160:163], v[168:171], v[112:127]
	v_mfma_f32_32x32x16_bf16 v[48:63], v[164:167], v[168:171], v[48:63]
	v_mfma_f32_32x32x16_bf16 v[96:111], v[160:163], v[172:175], v[96:111]
	v_mfma_f32_32x32x16_bf16 v[32:47], v[164:167], v[172:175], v[32:47]
	ds_read_b128 v[160:163], v242
	ds_read_b128 v[168:171], v246
	ds_read_b128 v[164:167], v242 offset:4096
	ds_read_b128 v[172:175], v246 offset:4096
	s_waitcnt lgkmcnt(4)
	v_mfma_f32_32x32x16_bf16 v[112:127], v[128:131], v[136:139], v[112:127]
	v_mfma_f32_32x32x16_bf16 v[48:63], v[132:135], v[136:139], v[48:63]
	v_mfma_f32_32x32x16_bf16 v[96:111], v[128:131], v[140:143], v[96:111]
	v_mfma_f32_32x32x16_bf16 v[32:47], v[132:135], v[140:143], v[32:47]
	ds_read_b128 v[128:131], v243
	ds_read_b128 v[136:139], v247
	ds_read_b128 v[132:135], v243 offset:4096
	ds_read_b128 v[140:143], v247 offset:4096
	s_waitcnt lgkmcnt(4)
	v_mfma_f32_32x32x16_bf16 v[112:127], v[160:163], v[168:171], v[112:127]
	v_mfma_f32_32x32x16_bf16 v[48:63], v[164:167], v[168:171], v[48:63]
	v_mfma_f32_32x32x16_bf16 v[96:111], v[160:163], v[172:175], v[96:111]
	v_mfma_f32_32x32x16_bf16 v[32:47], v[164:167], v[172:175], v[32:47]
	s_waitcnt vmcnt(0) lgkmcnt(0)
	s_barrier
	ds_read_b128 v[160:163], v184
	ds_read_b128 v[168:171], v188
	ds_read_b128 v[164:167], v184 offset:4096
	ds_read_b128 v[172:175], v188 offset:4096
	s_add_u32 s20, s16, 1920
	s_addc_u32 s21, s17, 0
	s_add_u32 s24, s18, 1920
	s_addc_u32 s25, s19, 0
	s_add_u32 m0, s27, 65536
	v_mfma_f32_32x32x16_bf16 v[112:127], v[128:131], v[136:139], v[112:127]
	global_load_lds_dwordx4 v192, s[20:21]
	s_add_u32 m0, s27, 98304
	v_mfma_f32_32x32x16_bf16 v[48:63], v[132:135], v[136:139], v[48:63]
	global_load_lds_dwordx4 v192, s[24:25]
	s_add_u32 m0, s27, 73728
	v_mfma_f32_32x32x16_bf16 v[96:111], v[128:131], v[140:143], v[96:111]
	global_load_lds_dwordx4 v194, s[20:21]
	s_add_u32 m0, s27, 106496
	v_mfma_f32_32x32x16_bf16 v[32:47], v[132:135], v[140:143], v[32:47]
	global_load_lds_dwordx4 v194, s[24:25]
	s_add_u32 m0, s27, 81920
	s_nop 0
	global_load_lds_dwordx4 v196, s[20:21]
	s_add_u32 m0, s27, 114688
	s_nop 0
	global_load_lds_dwordx4 v196, s[24:25]
	s_add_u32 m0, s27, 90112
	s_nop 0
	global_load_lds_dwordx4 v198, s[20:21]
	s_add_u32 m0, s27, 122880
	s_nop 0
	global_load_lds_dwordx4 v198, s[24:25]
	ds_read_b128 v[128:131], v185
	ds_read_b128 v[136:139], v189
	ds_read_b128 v[132:135], v185 offset:4096
	ds_read_b128 v[140:143], v189 offset:4096
	s_waitcnt lgkmcnt(4)
	v_mfma_f32_32x32x16_bf16 v[112:127], v[160:163], v[168:171], v[112:127]
	v_mfma_f32_32x32x16_bf16 v[48:63], v[164:167], v[168:171], v[48:63]
	v_mfma_f32_32x32x16_bf16 v[96:111], v[160:163], v[172:175], v[96:111]
	v_mfma_f32_32x32x16_bf16 v[32:47], v[164:167], v[172:175], v[32:47]
	ds_read_b128 v[160:163], v186
	ds_read_b128 v[168:171], v190
	ds_read_b128 v[164:167], v186 offset:4096
	ds_read_b128 v[172:175], v190 offset:4096
	s_waitcnt lgkmcnt(4)
	v_mfma_f32_32x32x16_bf16 v[112:127], v[128:131], v[136:139], v[112:127]
	v_mfma_f32_32x32x16_bf16 v[48:63], v[132:135], v[136:139], v[48:63]
	v_mfma_f32_32x32x16_bf16 v[96:111], v[128:131], v[140:143], v[96:111]
	v_mfma_f32_32x32x16_bf16 v[32:47], v[132:135], v[140:143], v[32:47]
	ds_read_b128 v[128:131], v187
	ds_read_b128 v[136:139], v191
	ds_read_b128 v[132:135], v187 offset:4096
	ds_read_b128 v[140:143], v191 offset:4096
	s_waitcnt lgkmcnt(4)
	v_mfma_f32_32x32x16_bf16 v[112:127], v[160:163], v[168:171], v[112:127]
	v_mfma_f32_32x32x16_bf16 v[48:63], v[164:167], v[168:171], v[48:63]
	v_mfma_f32_32x32x16_bf16 v[96:111], v[160:163], v[172:175], v[96:111]
	v_mfma_f32_32x32x16_bf16 v[32:47], v[164:167], v[172:175], v[32:47]
	s_waitcnt vmcnt(0) lgkmcnt(0)
	s_barrier
	ds_read_b128 v[160:163], v240
	ds_read_b128 v[168:171], v244
	ds_read_b128 v[164:167], v240 offset:4096
	ds_read_b128 v[172:175], v244 offset:4096
	s_add_u32 s37, s30, s42
	s_cmpk_ge_u32 s37, 0x780
	s_cbranch_scc1 .Lip11_lc_nonext
	s_mul_hi_u32 s38, s37, 0x92492493
	s_lshr_b32 s38, s38, 3
	s_mul_i32 s39, s38, 14
	s_sub_u32 s39, s37, s39
	s_sub_u32 s98, s37, 0x700
	s_cmpk_lt_u32 s37, 0x700
	s_cselect_b32 s39, s39, 14
	s_cselect_b32 s38, s38, s98
	s_lshl_b32 s98, s38, 19
	s_add_u32 s16, s4, s98
	s_addc_u32 s17, s5, 0
	s_lshl_b32 s98, s39, 19
	s_add_u32 s18, s6, s98
	s_addc_u32 s19, s7, 0
	s_add_u32 m0, s27, 0
	v_mfma_f32_32x32x16_bf16 v[112:127], v[128:131], v[136:139], v[112:127]
	global_load_lds_dwordx4 v192, s[16:17]
	s_add_u32 m0, s27, 32768
	v_mfma_f32_32x32x16_bf16 v[48:63], v[132:135], v[136:139], v[48:63]
	global_load_lds_dwordx4 v192, s[18:19]
	s_add_u32 m0, s27, 8192
	v_mfma_f32_32x32x16_bf16 v[96:111], v[128:131], v[140:143], v[96:111]
	global_load_lds_dwordx4 v194, s[16:17]
	s_add_u32 m0, s27, 40960
	v_mfma_f32_32x32x16_bf16 v[32:47], v[132:135], v[140:143], v[32:47]
	global_load_lds_dwordx4 v194, s[18:19]
	s_add_u32 m0, s27, 16384
	s_nop 0
	global_load_lds_dwordx4 v196, s[16:17]
	s_add_u32 m0, s27, 49152
	s_nop 0
	global_load_lds_dwordx4 v196, s[18:19]
	s_add_u32 m0, s27, 24576
	s_nop 0
	global_load_lds_dwordx4 v198, s[16:17]
	s_add_u32 m0, s27, 57344
	s_nop 0
	global_load_lds_dwordx4 v198, s[18:19]
	s_branch .Lip11_lc_join
.Lip11_lc_nonext:
	v_mfma_f32_32x32x16_bf16 v[112:127], v[128:131], v[136:139], v[112:127]
	v_mfma_f32_32x32x16_bf16 v[48:63], v[132:135], v[136:139], v[48:63]
	v_mfma_f32_32x32x16_bf16 v[96:111], v[128:131], v[140:143], v[96:111]
	v_mfma_f32_32x32x16_bf16 v[32:47], v[132:135], v[140:143], v[32:47]
.Lip11_lc_join:
	ds_read_b128 v[128:131], v241
	ds_read_b128 v[136:139], v245
	ds_read_b128 v[132:135], v241 offset:4096
	ds_read_b128 v[140:143], v245 offset:4096
	s_waitcnt lgkmcnt(4)
	v_mfma_f32_32x32x16_bf16 v[112:127], v[160:163], v[168:171], v[112:127]
	v_mfma_f32_32x32x16_bf16 v[48:63], v[164:167], v[168:171], v[48:63]
	v_mfma_f32_32x32x16_bf16 v[96:111], v[160:163], v[172:175], v[96:111]
	v_mfma_f32_32x32x16_bf16 v[32:47], v[164:167], v[172:175], v[32:47]
	ds_read_b128 v[160:163], v242
	ds_read_b128 v[168:171], v246
	ds_read_b128 v[164:167], v242 offset:4096
	ds_read_b128 v[172:175], v246 offset:4096
	s_waitcnt lgkmcnt(4)
	v_mfma_f32_32x32x16_bf16 v[112:127], v[128:131], v[136:139], v[112:127]
	v_mfma_f32_32x32x16_bf16 v[48:63], v[132:135], v[136:139], v[48:63]
	v_mfma_f32_32x32x16_bf16 v[96:111], v[128:131], v[140:143], v[96:111]
	v_mfma_f32_32x32x16_bf16 v[32:47], v[132:135], v[140:143], v[32:47]
	ds_read_b128 v[128:131], v243
	ds_read_b128 v[136:139], v247
	ds_read_b128 v[132:135], v243 offset:4096
	ds_read_b128 v[140:143], v247 offset:4096
	s_waitcnt lgkmcnt(4)
	v_mfma_f32_32x32x16_bf16 v[112:127], v[160:163], v[168:171], v[112:127]
	v_mfma_f32_32x32x16_bf16 v[48:63], v[164:167], v[168:171], v[48:63]
	v_mfma_f32_32x32x16_bf16 v[96:111], v[160:163], v[172:175], v[96:111]
	v_mfma_f32_32x32x16_bf16 v[32:47], v[164:167], v[172:175], v[32:47]
	s_waitcnt vmcnt(0) lgkmcnt(0)
	s_barrier
	v_mfma_f32_32x32x16_bf16 v[112:127], v[128:131], v[136:139], v[112:127]
	v_mfma_f32_32x32x16_bf16 v[48:63], v[132:135], v[136:139], v[48:63]
	v_mfma_f32_32x32x16_bf16 v[96:111], v[128:131], v[140:143], v[96:111]
	v_mfma_f32_32x32x16_bf16 v[32:47], v[132:135], v[140:143], v[32:47]
	s_branch .Lip11_epi

.Lmq19_vb:
	v_mbcnt_hi_u32_b32 v206, -1, v210
	s_lshr_b32 s29, s70, 6
	s_lshl_b32 s88, s70, 4
	s_and_b32 s90, s70, 0x40
	v_and_b32_e32 v245, 48, v206
	v_or_b32_e32 v245, s90, v245
	v_and_b32_e32 v207, 31, v206
	v_lshrrev_b32_e32 v208, 5, v206
	v_bfe_u32 v209, v206, 1, 3
	v_lshlrev_b32_e32 v211, 7, v207
	s_lshr_b32 s91, s70, 7
	s_lshl_b32 s31, s91, 6
	s_lshl_b32 s91, s91, 13
	s_lshl_b32 s34, s90, 1
	s_lshl_b32 s90, s90, 8
	s_add_u32 s90, s90, 0x8000
	v_xor_b32_e32 v212, v208, v209
	v_lshl_add_u32 v212, v212, 4, v211
	v_add_u32_e32 v184, s91, v212
	v_add_u32_e32 v188, s90, v212
	v_add_u32_e32 v246, 0x10000, v184
	v_add_u32_e32 v250, 0x10000, v188
	v_or_b32_e32 v212, 2, v208
	v_xor_b32_e32 v212, v212, v209
	v_lshl_add_u32 v212, v212, 4, v211
	v_add_u32_e32 v185, s91, v212
	v_add_u32_e32 v189, s90, v212
	v_add_u32_e32 v247, 0x10000, v185
	v_add_u32_e32 v251, 0x10000, v189
	v_or_b32_e32 v212, 4, v208
	v_xor_b32_e32 v212, v212, v209
	v_lshl_add_u32 v212, v212, 4, v211
	v_add_u32_e32 v186, s91, v212
	v_add_u32_e32 v190, s90, v212
	v_add_u32_e32 v248, 0x10000, v186
	v_add_u32_e32 v252, 0x10000, v190
	v_or_b32_e32 v212, 6, v208
	v_xor_b32_e32 v212, v212, v209
	v_lshl_add_u32 v212, v212, 4, v211
	v_add_u32_e32 v187, s91, v212
	v_add_u32_e32 v191, s90, v212
	v_add_u32_e32 v249, 0x10000, v187
	v_add_u32_e32 v253, 0x10000, v191
	v_lshlrev_b32_e32 v200, 3, v207
	v_lshlrev_b32_e32 v203, 2, v208
	s_mul_i32 s91, s29, 0x1200
	s_add_u32 s91, s91, 0x12000
	v_mul_u32_u24_e32 v212, 0x240, v208
	v_lshl_add_u32 v212, v207, 1, v212
	v_add_u32_e32 v201, s91, v212
	v_lshrrev_b32_e32 v204, 3, v206
	v_and_b32_e32 v212, 7, v206
	v_lshlrev_b32_e32 v205, 4, v212
	v_mul_u32_u24_e32 v212, 0x90, v204
	v_add3_u32 v202, v212, v205, s91
	s_load_dwordx2 s[4:5], s[0:1], 0x168
	s_load_dwordx2 s[6:7], s[0:1], 0xd8
	s_load_dwordx2 s[8:9], s[0:1], 0x210
	s_load_dwordx2 s[10:11], s[0:1], 0x148
	s_load_dwordx2 s[12:13], s[0:1], 0x178
	s_lshl_b32 s96, s29, 3
	v_add_u32_e32 v206, s96, v204
	v_xor_b32_e32 v207, v245, v205
	v_lshl_add_u32 v192, v206, 9, v207
	v_mov_b32_e32 v193, 0
	v_add_u32_e32 v208, 64, v206
	v_lshl_add_u32 v194, v208, 9, v207
	v_mov_b32_e32 v195, 0
	v_add_u32_e32 v208, 128, v206
	v_lshl_add_u32 v196, v208, 9, v207
	v_mov_b32_e32 v197, 0
	v_add_u32_e32 v208, 192, v206
	v_lshl_add_u32 v198, v208, 9, v207
	v_mov_b32_e32 v199, 0
	s_mov_b32 s30, s28
	s_cmp_ge_u32 s30, 768
	s_cbranch_scc1 .Lmq19q_done
	s_waitcnt lgkmcnt(0)
	s_mul_hi_u32 s35, s30, 0xaaaaaaab
	s_lshr_b32 s35, s35, 2
	s_mul_i32 s36, s35, 6
	s_sub_u32 s36, s30, s36
	s_lshl_b32 s98, s35, 17
	s_add_u32 s16, s4, s98
	s_addc_u32 s17, s5, 0
	s_lshl_b32 s98, s36, 17
	s_add_u32 s18, s6, s98
	s_addc_u32 s19, s7, 0
	s_add_u32 m0, s88, 0
	s_nop 0
	global_load_lds_dwordx4 v192, s[16:17]
	s_add_u32 m0, s88, 32768
	s_nop 0
	global_load_lds_dwordx4 v192, s[18:19]
	s_add_u32 m0, s88, 8192
	s_nop 0
	global_load_lds_dwordx4 v194, s[16:17]
	s_add_u32 m0, s88, 40960
	s_nop 0
	global_load_lds_dwordx4 v194, s[18:19]
	s_add_u32 m0, s88, 16384
	s_nop 0
	global_load_lds_dwordx4 v196, s[16:17]
	s_add_u32 m0, s88, 49152
	s_nop 0
	global_load_lds_dwordx4 v196, s[18:19]
	s_add_u32 m0, s88, 24576
	s_nop 0
	global_load_lds_dwordx4 v198, s[16:17]
	s_add_u32 m0, s88, 57344
	s_nop 0
	global_load_lds_dwordx4 v198, s[18:19]
